# hyena FFT: hand-written radix-4 passes for strides 16/4/1 keep each wave-private 64-element block in an XOR-swizzled, bank-conflict-free LDS layout between the passes (pair forward, pair inverse and f
# speedup vs baseline: 1.1213x; 1.0099x over previous
; DI float cos2pi(float x) { return __builtin_amdgcn_cosf(x); }
; DI float sin2pi(float x) { return __builtin_amdgcn_sinf(x); }
; template <bool INV>
; DI void fft_lds(float2* buf_, int L, int logL, int gtid, int NTG) {
;     ...
;     for (; s >= 2; s >>= 2) {
;       const int S = s >> 1;
;       const float i4 = 0.25f / (float)S;
; #pragma unroll 8
;       for (int t = gtid; t < (L >> 2); t += NTG) {
;         const int k = t & (S - 1), base = ((t - k) << 2) | k;
;         const v2f a0 = buf[base], a1 = buf[base + S], a2 = buf[base + 2 * S], a3 = buf[base + 3 * S];
;         const float fr = (float)k * i4;
;         const v2f w1 = v2f{cos2pi(fr), sin2pi(fr)};
;         const v2f w2 = vcmul(w1, w1);
;         const v2f x0 = a0 + a2;
;         const v2f x2 = vcmulc(a0 - a2, w1);
;         const v2f x1 = a1 + a3;
;         const v2f d13 = vcmulc(a1 - a3, w1);
;         const v2f x3 = v2f{d13.y, -d13.x};
;         buf[base] = x0 + x1;
;         buf[base + S] = vcmulc(x0 - x1, w2);
;         buf[base + 2 * S] = x2 + x3;
;         buf[base + 3 * S] = vcmulc(x2 - x3, w2);
;       }
.LBB0_610:
	s_and_saveexec_b64 s[24:25], s[12:13]
	s_cbranch_execz .LBB0_609
	s_lshr_b32 s9, s6, 1
	s_cmp_gt_u32 s9, 16
	s_cbranch_scc1 .Lffs_g_skip
	s_cmp_eq_u32 s88, 0x200
	s_cbranch_scc1 .Lffs_g1
	s_cmp_eq_u32 s9, 16
	s_cbranch_scc1 .Lffs_g816
	s_cmp_eq_u32 s9, 4
	s_cbranch_scc1 .Lffs_g84
	s_movk_i32 s0, 0x8
	s_movk_i32 s1, 0x10
	s_movk_i32 s4, 0x18
	v_mov_b32_e32 v24, 0x50
	v_mov_b32_e32 v234, v34
	v_lshlrev_b32_e32 v236, 2, v234
	v_lshl_add_u32 v16, v236, 3, v24
	v_bfe_u32 v237, v236, 5, 2
	v_bfe_u32 v238, v236, 6, 1
	v_lshl_or_b32 v237, v237, 2, v237
	v_lshl_or_b32 v237, v238, 4, v237
	v_xor_b32_e32 v237, v237, v236
	v_lshlrev_b32_e32 v237, 3, v237
	v_add_u32_e32 v12, v24, v237
	v_xad_u32 v13, v237, s0, v24
	v_xad_u32 v14, v237, s1, v24
	v_xad_u32 v15, v237, s4, v24
	ds_read_b64 v[4:5], v12
	ds_read_b64 v[6:7], v13
	ds_read_b64 v[8:9], v14
	ds_read_b64 v[10:11], v15
	s_waitcnt lgkmcnt(0)
	v_add_f32_e32 v25, v4, v8
	v_sub_f32_e32 v0, v4, v8
	v_add_f32_e32 v3, v6, v10
	v_sub_f32_e32 v231, v6, v10
	v_add_f32_e32 v26, v5, v9
	v_sub_f32_e32 v2, v5, v9
	v_add_f32_e32 v230, v7, v11
	v_sub_f32_e32 v232, v7, v11
	v_add_f32_e32 v4, v25, v3
	v_add_f32_e32 v5, v26, v230
	v_sub_f32_e32 v6, v25, v3
	v_sub_f32_e32 v7, v26, v230
	v_add_f32_e32 v8, v0, v232
	v_sub_f32_e32 v9, v2, v231
	v_sub_f32_e32 v10, v0, v232
	v_add_f32_e32 v11, v2, v231
	ds_write_b128 v16, v[4:7]
	ds_write_b128 v16, v[8:11] offset:16
	v_add_u32_e32 v234, 0x200, v34
	v_lshlrev_b32_e32 v236, 2, v234
	v_lshl_add_u32 v16, v236, 3, v24
	v_bfe_u32 v237, v236, 5, 2
	v_bfe_u32 v238, v236, 6, 1
	v_lshl_or_b32 v237, v237, 2, v237
	v_lshl_or_b32 v237, v238, 4, v237
	v_xor_b32_e32 v237, v237, v236
	v_lshlrev_b32_e32 v237, 3, v237
	v_add_u32_e32 v12, v24, v237
	v_xad_u32 v13, v237, s0, v24
	v_xad_u32 v14, v237, s1, v24
	v_xad_u32 v15, v237, s4, v24
	ds_read_b64 v[4:5], v12
	ds_read_b64 v[6:7], v13
	ds_read_b64 v[8:9], v14
	ds_read_b64 v[10:11], v15
	s_waitcnt lgkmcnt(0)
	v_add_f32_e32 v25, v4, v8
	v_sub_f32_e32 v0, v4, v8
	v_add_f32_e32 v3, v6, v10
	v_sub_f32_e32 v231, v6, v10
	v_add_f32_e32 v26, v5, v9
	v_sub_f32_e32 v2, v5, v9
	v_add_f32_e32 v230, v7, v11
	v_sub_f32_e32 v232, v7, v11
	v_add_f32_e32 v4, v25, v3
	v_add_f32_e32 v5, v26, v230
	v_sub_f32_e32 v6, v25, v3
	v_sub_f32_e32 v7, v26, v230
	v_add_f32_e32 v8, v0, v232
	v_sub_f32_e32 v9, v2, v231
	v_sub_f32_e32 v10, v0, v232
	v_add_f32_e32 v11, v2, v231
	ds_write_b128 v16, v[4:7]
	ds_write_b128 v16, v[8:11] offset:16
	v_add_u32_e32 v234, 0x400, v34
	v_lshlrev_b32_e32 v236, 2, v234
	v_lshl_add_u32 v16, v236, 3, v24
	v_bfe_u32 v237, v236, 5, 2
	v_bfe_u32 v238, v236, 6, 1
	v_lshl_or_b32 v237, v237, 2, v237
	v_lshl_or_b32 v237, v238, 4, v237
	v_xor_b32_e32 v237, v237, v236
	v_lshlrev_b32_e32 v237, 3, v237
	v_add_u32_e32 v12, v24, v237
	v_xad_u32 v13, v237, s0, v24
	v_xad_u32 v14, v237, s1, v24
	v_xad_u32 v15, v237, s4, v24
	ds_read_b64 v[4:5], v12
	ds_read_b64 v[6:7], v13
	ds_read_b64 v[8:9], v14
	ds_read_b64 v[10:11], v15
	s_waitcnt lgkmcnt(0)
	v_add_f32_e32 v25, v4, v8
	v_sub_f32_e32 v0, v4, v8
	v_add_f32_e32 v3, v6, v10
	v_sub_f32_e32 v231, v6, v10
	v_add_f32_e32 v26, v5, v9
	v_sub_f32_e32 v2, v5, v9
	v_add_f32_e32 v230, v7, v11
	v_sub_f32_e32 v232, v7, v11
	v_add_f32_e32 v4, v25, v3
	v_add_f32_e32 v5, v26, v230
	v_sub_f32_e32 v6, v25, v3
	v_sub_f32_e32 v7, v26, v230
	v_add_f32_e32 v8, v0, v232
	v_sub_f32_e32 v9, v2, v231
	v_sub_f32_e32 v10, v0, v232
	v_add_f32_e32 v11, v2, v231
	ds_write_b128 v16, v[4:7]
	ds_write_b128 v16, v[8:11] offset:16
	v_add_u32_e32 v234, 0x600, v34
	v_lshlrev_b32_e32 v236, 2, v234
	v_lshl_add_u32 v16, v236, 3, v24
	v_bfe_u32 v237, v236, 5, 2
	v_bfe_u32 v238, v236, 6, 1
	v_lshl_or_b32 v237, v237, 2, v237
	v_lshl_or_b32 v237, v238, 4, v237
	v_xor_b32_e32 v237, v237, v236
	v_lshlrev_b32_e32 v237, 3, v237
	v_add_u32_e32 v12, v24, v237
	v_xad_u32 v13, v237, s0, v24
	v_xad_u32 v14, v237, s1, v24
	v_xad_u32 v15, v237, s4, v24
	ds_read_b64 v[4:5], v12
	ds_read_b64 v[6:7], v13
	ds_read_b64 v[8:9], v14
	ds_read_b64 v[10:11], v15
	s_waitcnt lgkmcnt(0)
	v_add_f32_e32 v25, v4, v8
	v_sub_f32_e32 v0, v4, v8
	v_add_f32_e32 v3, v6, v10
	v_sub_f32_e32 v231, v6, v10
	v_add_f32_e32 v26, v5, v9
	v_sub_f32_e32 v2, v5, v9
	v_add_f32_e32 v230, v7, v11
	v_sub_f32_e32 v232, v7, v11
	v_add_f32_e32 v4, v25, v3
	v_add_f32_e32 v5, v26, v230
	v_sub_f32_e32 v6, v25, v3
	v_sub_f32_e32 v7, v26, v230
	v_add_f32_e32 v8, v0, v232
	v_sub_f32_e32 v9, v2, v231
	v_sub_f32_e32 v10, v0, v232
	v_add_f32_e32 v11, v2, v231
	ds_write_b128 v16, v[4:7]
	ds_write_b128 v16, v[8:11] offset:16
	v_add_u32_e32 v234, 0x800, v34
	v_lshlrev_b32_e32 v236, 2, v234
	v_lshl_add_u32 v16, v236, 3, v24
	v_bfe_u32 v237, v236, 5, 2
	v_bfe_u32 v238, v236, 6, 1
	v_lshl_or_b32 v237, v237, 2, v237
	v_lshl_or_b32 v237, v238, 4, v237
	v_xor_b32_e32 v237, v237, v236
	v_lshlrev_b32_e32 v237, 3, v237
	v_add_u32_e32 v12, v24, v237
	v_xad_u32 v13, v237, s0, v24
	v_xad_u32 v14, v237, s1, v24
	v_xad_u32 v15, v237, s4, v24
	ds_read_b64 v[4:5], v12
	ds_read_b64 v[6:7], v13
	ds_read_b64 v[8:9], v14
	ds_read_b64 v[10:11], v15
	s_waitcnt lgkmcnt(0)
	v_add_f32_e32 v25, v4, v8
	v_sub_f32_e32 v0, v4, v8
	v_add_f32_e32 v3, v6, v10
	v_sub_f32_e32 v231, v6, v10
	v_add_f32_e32 v26, v5, v9
	v_sub_f32_e32 v2, v5, v9
	v_add_f32_e32 v230, v7, v11
	v_sub_f32_e32 v232, v7, v11
	v_add_f32_e32 v4, v25, v3
	v_add_f32_e32 v5, v26, v230
	v_sub_f32_e32 v6, v25, v3
	v_sub_f32_e32 v7, v26, v230
	v_add_f32_e32 v8, v0, v232
	v_sub_f32_e32 v9, v2, v231
	v_sub_f32_e32 v10, v0, v232
	v_add_f32_e32 v11, v2, v231
	ds_write_b128 v16, v[4:7]
	ds_write_b128 v16, v[8:11] offset:16
	v_add_u32_e32 v234, 0xa00, v34
	v_lshlrev_b32_e32 v236, 2, v234
	v_lshl_add_u32 v16, v236, 3, v24
	v_bfe_u32 v237, v236, 5, 2
	v_bfe_u32 v238, v236, 6, 1
	v_lshl_or_b32 v237, v237, 2, v237
	v_lshl_or_b32 v237, v238, 4, v237
	v_xor_b32_e32 v237, v237, v236
	v_lshlrev_b32_e32 v237, 3, v237
	v_add_u32_e32 v12, v24, v237
	v_xad_u32 v13, v237, s0, v24
	v_xad_u32 v14, v237, s1, v24
	v_xad_u32 v15, v237, s4, v24
	ds_read_b64 v[4:5], v12
	ds_read_b64 v[6:7], v13
	ds_read_b64 v[8:9], v14
	ds_read_b64 v[10:11], v15
	s_waitcnt lgkmcnt(0)
; DI float cos2pi(float x) { return __builtin_amdgcn_cosf(x); }
; DI float sin2pi(float x) { return __builtin_amdgcn_sinf(x); }
; template <bool INV>
; DI void fft_lds(float2* buf_, int L, int logL, int gtid, int NTG) {
;     ...
;     for (; s >= 2; s >>= 2) {
;       const int S = s >> 1;
;       const float i4 = 0.25f / (float)S;
; #pragma unroll 8
;       for (int t = gtid; t < (L >> 2); t += NTG) {
;         const int k = t & (S - 1), base = ((t - k) << 2) | k;
;         const v2f a0 = buf[base], a1 = buf[base + S], a2 = buf[base + 2 * S], a3 = buf[base + 3 * S];
;         const float fr = (float)k * i4;
;         const v2f w1 = v2f{cos2pi(fr), sin2pi(fr)};
;         const v2f w2 = vcmul(w1, w1);
;         const v2f x0 = a0 + a2;
;         const v2f x2 = vcmulc(a0 - a2, w1);
;         const v2f x1 = a1 + a3;
;         const v2f d13 = vcmulc(a1 - a3, w1);
;         const v2f x3 = v2f{d13.y, -d13.x};
;         buf[base] = x0 + x1;
;         buf[base + S] = vcmulc(x0 - x1, w2);
;         buf[base + 2 * S] = x2 + x3;
;         buf[base + 3 * S] = vcmulc(x2 - x3, w2);
;       }
	v_add_f32_e32 v25, v4, v8
	v_sub_f32_e32 v0, v4, v8
	v_add_f32_e32 v3, v6, v10
	v_sub_f32_e32 v231, v6, v10
	v_add_f32_e32 v26, v5, v9
	v_sub_f32_e32 v2, v5, v9
	v_add_f32_e32 v230, v7, v11
	v_sub_f32_e32 v232, v7, v11
	v_add_f32_e32 v4, v25, v3
	v_add_f32_e32 v5, v26, v230
	v_sub_f32_e32 v6, v25, v3
	v_sub_f32_e32 v7, v26, v230
	v_add_f32_e32 v8, v0, v232
	v_sub_f32_e32 v9, v2, v231
	v_sub_f32_e32 v10, v0, v232
	v_add_f32_e32 v11, v2, v231
	ds_write_b128 v16, v[4:7]
	ds_write_b128 v16, v[8:11] offset:16
	v_add_u32_e32 v234, 0xc00, v34
	v_lshlrev_b32_e32 v236, 2, v234
	v_lshl_add_u32 v16, v236, 3, v24
	v_bfe_u32 v237, v236, 5, 2
	v_bfe_u32 v238, v236, 6, 1
	v_lshl_or_b32 v237, v237, 2, v237
	v_lshl_or_b32 v237, v238, 4, v237
	v_xor_b32_e32 v237, v237, v236
	v_lshlrev_b32_e32 v237, 3, v237
	v_add_u32_e32 v12, v24, v237
	v_xad_u32 v13, v237, s0, v24
	v_xad_u32 v14, v237, s1, v24
	v_xad_u32 v15, v237, s4, v24
	ds_read_b64 v[4:5], v12
	ds_read_b64 v[6:7], v13
	ds_read_b64 v[8:9], v14
	ds_read_b64 v[10:11], v15
	s_waitcnt lgkmcnt(0)
	v_add_f32_e32 v25, v4, v8
	v_sub_f32_e32 v0, v4, v8
	v_add_f32_e32 v3, v6, v10
	v_sub_f32_e32 v231, v6, v10
	v_add_f32_e32 v26, v5, v9
	v_sub_f32_e32 v2, v5, v9
	v_add_f32_e32 v230, v7, v11
	v_sub_f32_e32 v232, v7, v11
	v_add_f32_e32 v4, v25, v3
	v_add_f32_e32 v5, v26, v230
	v_sub_f32_e32 v6, v25, v3
	v_sub_f32_e32 v7, v26, v230
	v_add_f32_e32 v8, v0, v232
	v_sub_f32_e32 v9, v2, v231
	v_sub_f32_e32 v10, v0, v232
	v_add_f32_e32 v11, v2, v231
	ds_write_b128 v16, v[4:7]
	ds_write_b128 v16, v[8:11] offset:16
	v_add_u32_e32 v234, 0xe00, v34
	v_lshlrev_b32_e32 v236, 2, v234
	v_lshl_add_u32 v16, v236, 3, v24
	v_bfe_u32 v237, v236, 5, 2
	v_bfe_u32 v238, v236, 6, 1
	v_lshl_or_b32 v237, v237, 2, v237
	v_lshl_or_b32 v237, v238, 4, v237
	v_xor_b32_e32 v237, v237, v236
	v_lshlrev_b32_e32 v237, 3, v237
	v_add_u32_e32 v12, v24, v237
	v_xad_u32 v13, v237, s0, v24
	v_xad_u32 v14, v237, s1, v24
	v_xad_u32 v15, v237, s4, v24
	ds_read_b64 v[4:5], v12
	ds_read_b64 v[6:7], v13
	ds_read_b64 v[8:9], v14
	ds_read_b64 v[10:11], v15
	s_waitcnt lgkmcnt(0)
	v_add_f32_e32 v25, v4, v8
	v_sub_f32_e32 v0, v4, v8
	v_add_f32_e32 v3, v6, v10
	v_sub_f32_e32 v231, v6, v10
	v_add_f32_e32 v26, v5, v9
	v_sub_f32_e32 v2, v5, v9
	v_add_f32_e32 v230, v7, v11
	v_sub_f32_e32 v232, v7, v11
	v_add_f32_e32 v4, v25, v3
	v_add_f32_e32 v5, v26, v230
	v_sub_f32_e32 v6, v25, v3
	v_sub_f32_e32 v7, v26, v230
	v_add_f32_e32 v8, v0, v232
	v_sub_f32_e32 v9, v2, v231
	v_sub_f32_e32 v10, v0, v232
	v_add_f32_e32 v11, v2, v231
	ds_write_b128 v16, v[4:7]
	ds_write_b128 v16, v[8:11] offset:16
	s_branch .LBB0_609
.Lffs_g84:
	s_movk_i32 s0, 0x20
	s_movk_i32 s1, 0x40
	s_movk_i32 s4, 0x60
	v_mov_b32_e32 v24, 0x50
	v_mov_b32_e32 v234, v34
	v_and_b32_e32 v235, 3, v234
	v_sub_u32_e32 v236, v234, v235
	v_lshl_or_b32 v236, v236, 2, v235
	v_cvt_f32_u32_e32 v235, v235
	v_mul_f32_e32 v235, 0x3d800000, v235
	v_cos_f32_e32 v20, v235
	v_sin_f32_e32 v21, v235
	v_bfe_u32 v237, v236, 5, 2
	v_bfe_u32 v238, v236, 6, 1
	v_lshl_or_b32 v237, v237, 2, v237
	v_lshl_or_b32 v237, v238, 4, v237
	v_xor_b32_e32 v237, v237, v236
	v_lshlrev_b32_e32 v237, 3, v237
	v_add_u32_e32 v12, v24, v237
	v_xad_u32 v13, v237, s0, v24
	v_xad_u32 v14, v237, s1, v24
	v_xad_u32 v15, v237, s4, v24
	v_mul_f32_e32 v22, v21, v21
	v_mul_f32_e32 v23, v21, v20
	v_fma_f32 v22, v20, v20, -v22
	v_fma_f32 v23, v20, v21, v23
	ds_read_b64 v[4:5], v12
	ds_read_b64 v[6:7], v13
	ds_read_b64 v[8:9], v14
	ds_read_b64 v[10:11], v15
	s_waitcnt lgkmcnt(0)
	v_add_f32_e32 v25, v4, v8
	v_sub_f32_e32 v0, v4, v8
	v_add_f32_e32 v3, v6, v10
	v_sub_f32_e32 v231, v6, v10
	v_add_f32_e32 v26, v5, v9
	v_sub_f32_e32 v2, v5, v9
	v_add_f32_e32 v230, v7, v11
	v_sub_f32_e32 v232, v7, v11
	v_mul_f32_e32 v235, v0, v20
	v_mul_f32_e32 v236, v0, v21
	v_fma_f32 v233, v2, v21, v235
	v_fma_f32 v234, v2, v20, -v236
	v_mul_f32_e32 v235, v231, v20
	v_mul_f32_e32 v236, v231, v21
	v_fma_f32 v237, v232, v21, v235
	v_fma_f32 v238, v232, v20, -v236
	v_add_f32_e32 v4, v25, v3
	v_add_f32_e32 v5, v26, v230
	v_sub_f32_e32 v25, v25, v3
	v_sub_f32_e32 v26, v26, v230
	v_mul_f32_e32 v235, v25, v22
	v_mul_f32_e32 v236, v25, v23
	v_fma_f32 v6, v26, v23, v235
	v_fma_f32 v7, v26, v22, -v236
	v_add_f32_e32 v8, v233, v238
	v_sub_f32_e32 v9, v234, v237
	v_sub_f32_e32 v3, v233, v238
	v_add_f32_e32 v230, v234, v237
	v_mul_f32_e32 v235, v3, v22
	v_mul_f32_e32 v236, v3, v23
	v_fma_f32 v10, v230, v23, v235
	v_fma_f32 v11, v230, v22, -v236
	ds_write_b64 v12, v[4:5]
	ds_write_b64 v13, v[6:7]
	ds_write_b64 v14, v[8:9]
	ds_write_b64 v15, v[10:11]
	v_add_u32_e32 v234, 0x200, v34
	v_and_b32_e32 v235, 3, v234
	v_sub_u32_e32 v236, v234, v235
	v_lshl_or_b32 v236, v236, 2, v235
	v_cvt_f32_u32_e32 v235, v235
	v_mul_f32_e32 v235, 0x3d800000, v235
	v_cos_f32_e32 v20, v235
	v_sin_f32_e32 v21, v235
	v_bfe_u32 v237, v236, 5, 2
	v_bfe_u32 v238, v236, 6, 1
	v_lshl_or_b32 v237, v237, 2, v237
	v_lshl_or_b32 v237, v238, 4, v237
	v_xor_b32_e32 v237, v237, v236
	v_lshlrev_b32_e32 v237, 3, v237
	v_add_u32_e32 v12, v24, v237
	v_xad_u32 v13, v237, s0, v24
	v_xad_u32 v14, v237, s1, v24
	v_xad_u32 v15, v237, s4, v24
	v_mul_f32_e32 v22, v21, v21
	v_mul_f32_e32 v23, v21, v20
	v_fma_f32 v22, v20, v20, -v22
	v_fma_f32 v23, v20, v21, v23
	ds_read_b64 v[4:5], v12
	ds_read_b64 v[6:7], v13
	ds_read_b64 v[8:9], v14
	ds_read_b64 v[10:11], v15
	s_waitcnt lgkmcnt(0)
; DI float cos2pi(float x) { return __builtin_amdgcn_cosf(x); }
; DI float sin2pi(float x) { return __builtin_amdgcn_sinf(x); }
; template <bool INV>
; DI void fft_lds(float2* buf_, int L, int logL, int gtid, int NTG) {
;     ...
;       for (int t = gtid; t < (L >> 2); t += NTG) {
;         const int k = t & (S - 1), base = ((t - k) << 2) | k;
;         const v2f a0 = buf[base], a1 = buf[base + S], a2 = buf[base + 2 * S], a3 = buf[base + 3 * S];
;         const float fr = (float)k * i4;
;         const v2f w1 = v2f{cos2pi(fr), sin2pi(fr)};
;         const v2f w2 = vcmul(w1, w1);
;         const v2f x0 = a0 + a2;
;         const v2f x2 = vcmulc(a0 - a2, w1);
;         const v2f x1 = a1 + a3;
;         const v2f d13 = vcmulc(a1 - a3, w1);
;         const v2f x3 = v2f{d13.y, -d13.x};
;         buf[base] = x0 + x1;
;         buf[base + S] = vcmulc(x0 - x1, w2);
;         buf[base + 2 * S] = x2 + x3;
;         buf[base + 3 * S] = vcmulc(x2 - x3, w2);
;       }
	v_add_f32_e32 v25, v4, v8
	v_sub_f32_e32 v0, v4, v8
	v_add_f32_e32 v3, v6, v10
	v_sub_f32_e32 v231, v6, v10
	v_add_f32_e32 v26, v5, v9
	v_sub_f32_e32 v2, v5, v9
	v_add_f32_e32 v230, v7, v11
	v_sub_f32_e32 v232, v7, v11
	v_mul_f32_e32 v235, v0, v20
	v_mul_f32_e32 v236, v0, v21
	v_fma_f32 v233, v2, v21, v235
	v_fma_f32 v234, v2, v20, -v236
	v_mul_f32_e32 v235, v231, v20
	v_mul_f32_e32 v236, v231, v21
	v_fma_f32 v237, v232, v21, v235
	v_fma_f32 v238, v232, v20, -v236
	v_add_f32_e32 v4, v25, v3
	v_add_f32_e32 v5, v26, v230
	v_sub_f32_e32 v25, v25, v3
	v_sub_f32_e32 v26, v26, v230
	v_mul_f32_e32 v235, v25, v22
	v_mul_f32_e32 v236, v25, v23
	v_fma_f32 v6, v26, v23, v235
	v_fma_f32 v7, v26, v22, -v236
	v_add_f32_e32 v8, v233, v238
	v_sub_f32_e32 v9, v234, v237
	v_sub_f32_e32 v3, v233, v238
	v_add_f32_e32 v230, v234, v237
	v_mul_f32_e32 v235, v3, v22
	v_mul_f32_e32 v236, v3, v23
	v_fma_f32 v10, v230, v23, v235
	v_fma_f32 v11, v230, v22, -v236
	ds_write_b64 v12, v[4:5]
	ds_write_b64 v13, v[6:7]
	ds_write_b64 v14, v[8:9]
	ds_write_b64 v15, v[10:11]
	v_add_u32_e32 v234, 0x400, v34
	v_and_b32_e32 v235, 3, v234
	v_sub_u32_e32 v236, v234, v235
	v_lshl_or_b32 v236, v236, 2, v235
	v_cvt_f32_u32_e32 v235, v235
	v_mul_f32_e32 v235, 0x3d800000, v235
	v_cos_f32_e32 v20, v235
	v_sin_f32_e32 v21, v235
	v_bfe_u32 v237, v236, 5, 2
	v_bfe_u32 v238, v236, 6, 1
	v_lshl_or_b32 v237, v237, 2, v237
	v_lshl_or_b32 v237, v238, 4, v237
	v_xor_b32_e32 v237, v237, v236
	v_lshlrev_b32_e32 v237, 3, v237
	v_add_u32_e32 v12, v24, v237
	v_xad_u32 v13, v237, s0, v24
	v_xad_u32 v14, v237, s1, v24
	v_xad_u32 v15, v237, s4, v24
	v_mul_f32_e32 v22, v21, v21
	v_mul_f32_e32 v23, v21, v20
	v_fma_f32 v22, v20, v20, -v22
	v_fma_f32 v23, v20, v21, v23
	ds_read_b64 v[4:5], v12
	ds_read_b64 v[6:7], v13
	ds_read_b64 v[8:9], v14
	ds_read_b64 v[10:11], v15
	s_waitcnt lgkmcnt(0)
	v_add_f32_e32 v25, v4, v8
	v_sub_f32_e32 v0, v4, v8
	v_add_f32_e32 v3, v6, v10
	v_sub_f32_e32 v231, v6, v10
	v_add_f32_e32 v26, v5, v9
	v_sub_f32_e32 v2, v5, v9
	v_add_f32_e32 v230, v7, v11
	v_sub_f32_e32 v232, v7, v11
	v_mul_f32_e32 v235, v0, v20
	v_mul_f32_e32 v236, v0, v21
	v_fma_f32 v233, v2, v21, v235
	v_fma_f32 v234, v2, v20, -v236
	v_mul_f32_e32 v235, v231, v20
	v_mul_f32_e32 v236, v231, v21
	v_fma_f32 v237, v232, v21, v235
	v_fma_f32 v238, v232, v20, -v236
	v_add_f32_e32 v4, v25, v3
	v_add_f32_e32 v5, v26, v230
	v_sub_f32_e32 v25, v25, v3
	v_sub_f32_e32 v26, v26, v230
	v_mul_f32_e32 v235, v25, v22
	v_mul_f32_e32 v236, v25, v23
	v_fma_f32 v6, v26, v23, v235
	v_fma_f32 v7, v26, v22, -v236
	v_add_f32_e32 v8, v233, v238
	v_sub_f32_e32 v9, v234, v237
	v_sub_f32_e32 v3, v233, v238
	v_add_f32_e32 v230, v234, v237
	v_mul_f32_e32 v235, v3, v22
	v_mul_f32_e32 v236, v3, v23
	v_fma_f32 v10, v230, v23, v235
	v_fma_f32 v11, v230, v22, -v236
	ds_write_b64 v12, v[4:5]
	ds_write_b64 v13, v[6:7]
	ds_write_b64 v14, v[8:9]
	ds_write_b64 v15, v[10:11]
	v_add_u32_e32 v234, 0x600, v34
	v_and_b32_e32 v235, 3, v234
	v_sub_u32_e32 v236, v234, v235
	v_lshl_or_b32 v236, v236, 2, v235
	v_cvt_f32_u32_e32 v235, v235
	v_mul_f32_e32 v235, 0x3d800000, v235
	v_cos_f32_e32 v20, v235
	v_sin_f32_e32 v21, v235
	v_bfe_u32 v237, v236, 5, 2
	v_bfe_u32 v238, v236, 6, 1
	v_lshl_or_b32 v237, v237, 2, v237
	v_lshl_or_b32 v237, v238, 4, v237
	v_xor_b32_e32 v237, v237, v236
	v_lshlrev_b32_e32 v237, 3, v237
	v_add_u32_e32 v12, v24, v237
	v_xad_u32 v13, v237, s0, v24
	v_xad_u32 v14, v237, s1, v24
	v_xad_u32 v15, v237, s4, v24
	v_mul_f32_e32 v22, v21, v21
	v_mul_f32_e32 v23, v21, v20
	v_fma_f32 v22, v20, v20, -v22
	v_fma_f32 v23, v20, v21, v23
	ds_read_b64 v[4:5], v12
	ds_read_b64 v[6:7], v13
	ds_read_b64 v[8:9], v14
	ds_read_b64 v[10:11], v15
	s_waitcnt lgkmcnt(0)
	v_add_f32_e32 v25, v4, v8
	v_sub_f32_e32 v0, v4, v8
	v_add_f32_e32 v3, v6, v10
	v_sub_f32_e32 v231, v6, v10
	v_add_f32_e32 v26, v5, v9
	v_sub_f32_e32 v2, v5, v9
	v_add_f32_e32 v230, v7, v11
	v_sub_f32_e32 v232, v7, v11
	v_mul_f32_e32 v235, v0, v20
	v_mul_f32_e32 v236, v0, v21
	v_fma_f32 v233, v2, v21, v235
	v_fma_f32 v234, v2, v20, -v236
	v_mul_f32_e32 v235, v231, v20
	v_mul_f32_e32 v236, v231, v21
	v_fma_f32 v237, v232, v21, v235
	v_fma_f32 v238, v232, v20, -v236
	v_add_f32_e32 v4, v25, v3
	v_add_f32_e32 v5, v26, v230
	v_sub_f32_e32 v25, v25, v3
	v_sub_f32_e32 v26, v26, v230
	v_mul_f32_e32 v235, v25, v22
	v_mul_f32_e32 v236, v25, v23
	v_fma_f32 v6, v26, v23, v235
	v_fma_f32 v7, v26, v22, -v236
	v_add_f32_e32 v8, v233, v238
	v_sub_f32_e32 v9, v234, v237
	v_sub_f32_e32 v3, v233, v238
	v_add_f32_e32 v230, v234, v237
	v_mul_f32_e32 v235, v3, v22
	v_mul_f32_e32 v236, v3, v23
	v_fma_f32 v10, v230, v23, v235
	v_fma_f32 v11, v230, v22, -v236
	ds_write_b64 v12, v[4:5]
	ds_write_b64 v13, v[6:7]
	ds_write_b64 v14, v[8:9]
	ds_write_b64 v15, v[10:11]
	v_add_u32_e32 v234, 0x800, v34
	v_and_b32_e32 v235, 3, v234
	v_sub_u32_e32 v236, v234, v235
	v_lshl_or_b32 v236, v236, 2, v235
	v_cvt_f32_u32_e32 v235, v235
	v_mul_f32_e32 v235, 0x3d800000, v235
	v_cos_f32_e32 v20, v235
	v_sin_f32_e32 v21, v235
	v_bfe_u32 v237, v236, 5, 2
	v_bfe_u32 v238, v236, 6, 1
	v_lshl_or_b32 v237, v237, 2, v237
	v_lshl_or_b32 v237, v238, 4, v237
	v_xor_b32_e32 v237, v237, v236
	v_lshlrev_b32_e32 v237, 3, v237
	v_add_u32_e32 v12, v24, v237
	v_xad_u32 v13, v237, s0, v24
	v_xad_u32 v14, v237, s1, v24
	v_xad_u32 v15, v237, s4, v24
	v_mul_f32_e32 v22, v21, v21
	v_mul_f32_e32 v23, v21, v20
	v_fma_f32 v22, v20, v20, -v22
	v_fma_f32 v23, v20, v21, v23
	ds_read_b64 v[4:5], v12
	ds_read_b64 v[6:7], v13
	ds_read_b64 v[8:9], v14
	ds_read_b64 v[10:11], v15
	s_waitcnt lgkmcnt(0)
; DI float cos2pi(float x) { return __builtin_amdgcn_cosf(x); }
; DI float sin2pi(float x) { return __builtin_amdgcn_sinf(x); }
; template <bool INV>
; DI void fft_lds(float2* buf_, int L, int logL, int gtid, int NTG) {
;     ...
;       for (int t = gtid; t < (L >> 2); t += NTG) {
;         const int k = t & (S - 1), base = ((t - k) << 2) | k;
;         const v2f a0 = buf[base], a1 = buf[base + S], a2 = buf[base + 2 * S], a3 = buf[base + 3 * S];
;         const float fr = (float)k * i4;
;         const v2f w1 = v2f{cos2pi(fr), sin2pi(fr)};
;         const v2f w2 = vcmul(w1, w1);
;         const v2f x0 = a0 + a2;
;         const v2f x2 = vcmulc(a0 - a2, w1);
;         const v2f x1 = a1 + a3;
;         const v2f d13 = vcmulc(a1 - a3, w1);
;         const v2f x3 = v2f{d13.y, -d13.x};
;         buf[base] = x0 + x1;
;         buf[base + S] = vcmulc(x0 - x1, w2);
;         buf[base + 2 * S] = x2 + x3;
;         buf[base + 3 * S] = vcmulc(x2 - x3, w2);
;       }
	v_add_f32_e32 v25, v4, v8
	v_sub_f32_e32 v0, v4, v8
	v_add_f32_e32 v3, v6, v10
	v_sub_f32_e32 v231, v6, v10
	v_add_f32_e32 v26, v5, v9
	v_sub_f32_e32 v2, v5, v9
	v_add_f32_e32 v230, v7, v11
	v_sub_f32_e32 v232, v7, v11
	v_mul_f32_e32 v235, v0, v20
	v_mul_f32_e32 v236, v0, v21
	v_fma_f32 v233, v2, v21, v235
	v_fma_f32 v234, v2, v20, -v236
	v_mul_f32_e32 v235, v231, v20
	v_mul_f32_e32 v236, v231, v21
	v_fma_f32 v237, v232, v21, v235
	v_fma_f32 v238, v232, v20, -v236
	v_add_f32_e32 v4, v25, v3
	v_add_f32_e32 v5, v26, v230
	v_sub_f32_e32 v25, v25, v3
	v_sub_f32_e32 v26, v26, v230
	v_mul_f32_e32 v235, v25, v22
	v_mul_f32_e32 v236, v25, v23
	v_fma_f32 v6, v26, v23, v235
	v_fma_f32 v7, v26, v22, -v236
	v_add_f32_e32 v8, v233, v238
	v_sub_f32_e32 v9, v234, v237
	v_sub_f32_e32 v3, v233, v238
	v_add_f32_e32 v230, v234, v237
	v_mul_f32_e32 v235, v3, v22
	v_mul_f32_e32 v236, v3, v23
	v_fma_f32 v10, v230, v23, v235
	v_fma_f32 v11, v230, v22, -v236
	ds_write_b64 v12, v[4:5]
	ds_write_b64 v13, v[6:7]
	ds_write_b64 v14, v[8:9]
	ds_write_b64 v15, v[10:11]
	v_add_u32_e32 v234, 0xa00, v34
	v_and_b32_e32 v235, 3, v234
	v_sub_u32_e32 v236, v234, v235
	v_lshl_or_b32 v236, v236, 2, v235
	v_cvt_f32_u32_e32 v235, v235
	v_mul_f32_e32 v235, 0x3d800000, v235
	v_cos_f32_e32 v20, v235
	v_sin_f32_e32 v21, v235
	v_bfe_u32 v237, v236, 5, 2
	v_bfe_u32 v238, v236, 6, 1
	v_lshl_or_b32 v237, v237, 2, v237
	v_lshl_or_b32 v237, v238, 4, v237
	v_xor_b32_e32 v237, v237, v236
	v_lshlrev_b32_e32 v237, 3, v237
	v_add_u32_e32 v12, v24, v237
	v_xad_u32 v13, v237, s0, v24
	v_xad_u32 v14, v237, s1, v24
	v_xad_u32 v15, v237, s4, v24
	v_mul_f32_e32 v22, v21, v21
	v_mul_f32_e32 v23, v21, v20
	v_fma_f32 v22, v20, v20, -v22
	v_fma_f32 v23, v20, v21, v23
	ds_read_b64 v[4:5], v12
	ds_read_b64 v[6:7], v13
	ds_read_b64 v[8:9], v14
	ds_read_b64 v[10:11], v15
	s_waitcnt lgkmcnt(0)
	v_add_f32_e32 v25, v4, v8
	v_sub_f32_e32 v0, v4, v8
	v_add_f32_e32 v3, v6, v10
	v_sub_f32_e32 v231, v6, v10
	v_add_f32_e32 v26, v5, v9
	v_sub_f32_e32 v2, v5, v9
	v_add_f32_e32 v230, v7, v11
	v_sub_f32_e32 v232, v7, v11
	v_mul_f32_e32 v235, v0, v20
	v_mul_f32_e32 v236, v0, v21
	v_fma_f32 v233, v2, v21, v235
	v_fma_f32 v234, v2, v20, -v236
	v_mul_f32_e32 v235, v231, v20
	v_mul_f32_e32 v236, v231, v21
	v_fma_f32 v237, v232, v21, v235
	v_fma_f32 v238, v232, v20, -v236
	v_add_f32_e32 v4, v25, v3
	v_add_f32_e32 v5, v26, v230
	v_sub_f32_e32 v25, v25, v3
	v_sub_f32_e32 v26, v26, v230
	v_mul_f32_e32 v235, v25, v22
	v_mul_f32_e32 v236, v25, v23
	v_fma_f32 v6, v26, v23, v235
	v_fma_f32 v7, v26, v22, -v236
	v_add_f32_e32 v8, v233, v238
	v_sub_f32_e32 v9, v234, v237
	v_sub_f32_e32 v3, v233, v238
	v_add_f32_e32 v230, v234, v237
	v_mul_f32_e32 v235, v3, v22
	v_mul_f32_e32 v236, v3, v23
	v_fma_f32 v10, v230, v23, v235
	v_fma_f32 v11, v230, v22, -v236
	ds_write_b64 v12, v[4:5]
	ds_write_b64 v13, v[6:7]
	ds_write_b64 v14, v[8:9]
	ds_write_b64 v15, v[10:11]
	v_add_u32_e32 v234, 0xc00, v34
	v_and_b32_e32 v235, 3, v234
	v_sub_u32_e32 v236, v234, v235
	v_lshl_or_b32 v236, v236, 2, v235
	v_cvt_f32_u32_e32 v235, v235
	v_mul_f32_e32 v235, 0x3d800000, v235
	v_cos_f32_e32 v20, v235
	v_sin_f32_e32 v21, v235
	v_bfe_u32 v237, v236, 5, 2
	v_bfe_u32 v238, v236, 6, 1
	v_lshl_or_b32 v237, v237, 2, v237
	v_lshl_or_b32 v237, v238, 4, v237
	v_xor_b32_e32 v237, v237, v236
	v_lshlrev_b32_e32 v237, 3, v237
	v_add_u32_e32 v12, v24, v237
	v_xad_u32 v13, v237, s0, v24
	v_xad_u32 v14, v237, s1, v24
	v_xad_u32 v15, v237, s4, v24
	v_mul_f32_e32 v22, v21, v21
	v_mul_f32_e32 v23, v21, v20
	v_fma_f32 v22, v20, v20, -v22
	v_fma_f32 v23, v20, v21, v23
	ds_read_b64 v[4:5], v12
	ds_read_b64 v[6:7], v13
	ds_read_b64 v[8:9], v14
	ds_read_b64 v[10:11], v15
	s_waitcnt lgkmcnt(0)
	v_add_f32_e32 v25, v4, v8
	v_sub_f32_e32 v0, v4, v8
	v_add_f32_e32 v3, v6, v10
	v_sub_f32_e32 v231, v6, v10
	v_add_f32_e32 v26, v5, v9
	v_sub_f32_e32 v2, v5, v9
	v_add_f32_e32 v230, v7, v11
	v_sub_f32_e32 v232, v7, v11
	v_mul_f32_e32 v235, v0, v20
	v_mul_f32_e32 v236, v0, v21
	v_fma_f32 v233, v2, v21, v235
	v_fma_f32 v234, v2, v20, -v236
	v_mul_f32_e32 v235, v231, v20
	v_mul_f32_e32 v236, v231, v21
	v_fma_f32 v237, v232, v21, v235
	v_fma_f32 v238, v232, v20, -v236
	v_add_f32_e32 v4, v25, v3
	v_add_f32_e32 v5, v26, v230
	v_sub_f32_e32 v25, v25, v3
	v_sub_f32_e32 v26, v26, v230
	v_mul_f32_e32 v235, v25, v22
	v_mul_f32_e32 v236, v25, v23
	v_fma_f32 v6, v26, v23, v235
	v_fma_f32 v7, v26, v22, -v236
	v_add_f32_e32 v8, v233, v238
	v_sub_f32_e32 v9, v234, v237
	v_sub_f32_e32 v3, v233, v238
	v_add_f32_e32 v230, v234, v237
	v_mul_f32_e32 v235, v3, v22
	v_mul_f32_e32 v236, v3, v23
	v_fma_f32 v10, v230, v23, v235
	v_fma_f32 v11, v230, v22, -v236
	ds_write_b64 v12, v[4:5]
	ds_write_b64 v13, v[6:7]
	ds_write_b64 v14, v[8:9]
	ds_write_b64 v15, v[10:11]
	v_add_u32_e32 v234, 0xe00, v34
	v_and_b32_e32 v235, 3, v234
	v_sub_u32_e32 v236, v234, v235
	v_lshl_or_b32 v236, v236, 2, v235
	v_cvt_f32_u32_e32 v235, v235
	v_mul_f32_e32 v235, 0x3d800000, v235
	v_cos_f32_e32 v20, v235
	v_sin_f32_e32 v21, v235
	v_bfe_u32 v237, v236, 5, 2
	v_bfe_u32 v238, v236, 6, 1
	v_lshl_or_b32 v237, v237, 2, v237
	v_lshl_or_b32 v237, v238, 4, v237
	v_xor_b32_e32 v237, v237, v236
	v_lshlrev_b32_e32 v237, 3, v237
	v_add_u32_e32 v12, v24, v237
	v_xad_u32 v13, v237, s0, v24
	v_xad_u32 v14, v237, s1, v24
	v_xad_u32 v15, v237, s4, v24
	v_mul_f32_e32 v22, v21, v21
	v_mul_f32_e32 v23, v21, v20
	v_fma_f32 v22, v20, v20, -v22
	v_fma_f32 v23, v20, v21, v23
	ds_read_b64 v[4:5], v12
	ds_read_b64 v[6:7], v13
	ds_read_b64 v[8:9], v14
	ds_read_b64 v[10:11], v15
	s_waitcnt lgkmcnt(0)
	v_add_f32_e32 v25, v4, v8
	v_sub_f32_e32 v0, v4, v8
	v_add_f32_e32 v3, v6, v10
	v_sub_f32_e32 v231, v6, v10
	v_add_f32_e32 v26, v5, v9
	v_sub_f32_e32 v2, v5, v9
	v_add_f32_e32 v230, v7, v11
	v_sub_f32_e32 v232, v7, v11
	v_mul_f32_e32 v235, v0, v20
	v_mul_f32_e32 v236, v0, v21
	v_fma_f32 v233, v2, v21, v235
	v_fma_f32 v234, v2, v20, -v236
	v_mul_f32_e32 v235, v231, v20
	v_mul_f32_e32 v236, v231, v21
	v_fma_f32 v237, v232, v21, v235
	v_fma_f32 v238, v232, v20, -v236
	v_add_f32_e32 v4, v25, v3
	v_add_f32_e32 v5, v26, v230
	v_sub_f32_e32 v25, v25, v3
	v_sub_f32_e32 v26, v26, v230
	v_mul_f32_e32 v235, v25, v22
	v_mul_f32_e32 v236, v25, v23
	v_fma_f32 v6, v26, v23, v235
	v_fma_f32 v7, v26, v22, -v236
	v_add_f32_e32 v8, v233, v238
	v_sub_f32_e32 v9, v234, v237
	v_sub_f32_e32 v3, v233, v238
	v_add_f32_e32 v230, v234, v237
	v_mul_f32_e32 v235, v3, v22
	v_mul_f32_e32 v236, v3, v23
	v_fma_f32 v10, v230, v23, v235
	v_fma_f32 v11, v230, v22, -v236
	ds_write_b64 v12, v[4:5]
	ds_write_b64 v13, v[6:7]
	ds_write_b64 v14, v[8:9]
	ds_write_b64 v15, v[10:11]
	s_branch .LBB0_609
; DI float cos2pi(float x) { return __builtin_amdgcn_cosf(x); }
; DI float sin2pi(float x) { return __builtin_amdgcn_sinf(x); }
; template <bool INV>
; DI void fft_lds(float2* buf_, int L, int logL, int gtid, int NTG) {
;     ...
;       for (int t = gtid; t < (L >> 2); t += NTG) {
;         const int k = t & (S - 1), base = ((t - k) << 2) | k;
;         const v2f a0 = buf[base], a1 = buf[base + S], a2 = buf[base + 2 * S], a3 = buf[base + 3 * S];
;         const float fr = (float)k * i4;
;         const v2f w1 = v2f{cos2pi(fr), sin2pi(fr)};
;         const v2f w2 = vcmul(w1, w1);
;         const v2f x0 = a0 + a2;
;         const v2f x2 = vcmulc(a0 - a2, w1);
;         const v2f x1 = a1 + a3;
;         const v2f d13 = vcmulc(a1 - a3, w1);
;         const v2f x3 = v2f{d13.y, -d13.x};
;         buf[base] = x0 + x1;
;         buf[base + S] = vcmulc(x0 - x1, w2);
;         buf[base + 2 * S] = x2 + x3;
;         buf[base + 3 * S] = vcmulc(x2 - x3, w2);
;       }
.Lffs_g816:
	s_movk_i32 s0, 0x80
	s_movk_i32 s1, 0x128
	s_movk_i32 s4, 0x1a8
	v_mov_b32_e32 v24, 0x50
	v_mov_b32_e32 v234, v34
	v_and_b32_e32 v235, 15, v234
	v_sub_u32_e32 v236, v234, v235
	v_lshl_or_b32 v236, v236, 2, v235
	v_cvt_f32_u32_e32 v235, v235
	v_mul_f32_e32 v235, 0x3c800000, v235
	v_cos_f32_e32 v20, v235
	v_sin_f32_e32 v21, v235
	v_lshl_add_u32 v12, v236, 3, v24
	v_add_u32_e32 v13, 0x80, v12
	v_add_u32_e32 v14, 0x100, v12
	v_add_u32_e32 v15, 0x180, v12
	v_bfe_u32 v237, v236, 5, 2
	v_bfe_u32 v238, v236, 6, 1
	v_lshl_or_b32 v237, v237, 2, v237
	v_lshl_or_b32 v237, v238, 4, v237
	v_xor_b32_e32 v237, v237, v236
	v_lshlrev_b32_e32 v237, 3, v237
	v_add_u32_e32 v16, v24, v237
	v_xad_u32 v17, v237, s0, v24
	v_xad_u32 v18, v237, s1, v24
	v_xad_u32 v19, v237, s4, v24
	v_mul_f32_e32 v22, v21, v21
	v_mul_f32_e32 v23, v21, v20
	v_fma_f32 v22, v20, v20, -v22
	v_fma_f32 v23, v20, v21, v23
	ds_read_b64 v[4:5], v12
	ds_read_b64 v[6:7], v13
	ds_read_b64 v[8:9], v14
	ds_read_b64 v[10:11], v15
	s_waitcnt lgkmcnt(0)
	v_add_f32_e32 v25, v4, v8
	v_sub_f32_e32 v0, v4, v8
	v_add_f32_e32 v3, v6, v10
	v_sub_f32_e32 v231, v6, v10
	v_add_f32_e32 v26, v5, v9
	v_sub_f32_e32 v2, v5, v9
	v_add_f32_e32 v230, v7, v11
	v_sub_f32_e32 v232, v7, v11
	v_mul_f32_e32 v235, v0, v20
	v_mul_f32_e32 v236, v0, v21
	v_fma_f32 v233, v2, v21, v235
	v_fma_f32 v234, v2, v20, -v236
	v_mul_f32_e32 v235, v231, v20
	v_mul_f32_e32 v236, v231, v21
	v_fma_f32 v237, v232, v21, v235
	v_fma_f32 v238, v232, v20, -v236
	v_add_f32_e32 v4, v25, v3
	v_add_f32_e32 v5, v26, v230
	v_sub_f32_e32 v25, v25, v3
	v_sub_f32_e32 v26, v26, v230
	v_mul_f32_e32 v235, v25, v22
	v_mul_f32_e32 v236, v25, v23
	v_fma_f32 v6, v26, v23, v235
	v_fma_f32 v7, v26, v22, -v236
	v_add_f32_e32 v8, v233, v238
	v_sub_f32_e32 v9, v234, v237
	v_sub_f32_e32 v3, v233, v238
	v_add_f32_e32 v230, v234, v237
	v_mul_f32_e32 v235, v3, v22
	v_mul_f32_e32 v236, v3, v23
	v_fma_f32 v10, v230, v23, v235
	v_fma_f32 v11, v230, v22, -v236
	ds_write_b64 v16, v[4:5]
	ds_write_b64 v17, v[6:7]
	ds_write_b64 v18, v[8:9]
	ds_write_b64 v19, v[10:11]
	v_add_u32_e32 v234, 0x200, v34
	v_and_b32_e32 v235, 15, v234
	v_sub_u32_e32 v236, v234, v235
	v_lshl_or_b32 v236, v236, 2, v235
	v_cvt_f32_u32_e32 v235, v235
	v_mul_f32_e32 v235, 0x3c800000, v235
	v_cos_f32_e32 v20, v235
	v_sin_f32_e32 v21, v235
	v_lshl_add_u32 v12, v236, 3, v24
	v_add_u32_e32 v13, 0x80, v12
	v_add_u32_e32 v14, 0x100, v12
	v_add_u32_e32 v15, 0x180, v12
	v_bfe_u32 v237, v236, 5, 2
	v_bfe_u32 v238, v236, 6, 1
	v_lshl_or_b32 v237, v237, 2, v237
	v_lshl_or_b32 v237, v238, 4, v237
	v_xor_b32_e32 v237, v237, v236
	v_lshlrev_b32_e32 v237, 3, v237
	v_add_u32_e32 v16, v24, v237
	v_xad_u32 v17, v237, s0, v24
	v_xad_u32 v18, v237, s1, v24
	v_xad_u32 v19, v237, s4, v24
	v_mul_f32_e32 v22, v21, v21
	v_mul_f32_e32 v23, v21, v20
	v_fma_f32 v22, v20, v20, -v22
	v_fma_f32 v23, v20, v21, v23
	ds_read_b64 v[4:5], v12
	ds_read_b64 v[6:7], v13
	ds_read_b64 v[8:9], v14
	ds_read_b64 v[10:11], v15
	s_waitcnt lgkmcnt(0)
	v_add_f32_e32 v25, v4, v8
	v_sub_f32_e32 v0, v4, v8
	v_add_f32_e32 v3, v6, v10
	v_sub_f32_e32 v231, v6, v10
	v_add_f32_e32 v26, v5, v9
	v_sub_f32_e32 v2, v5, v9
	v_add_f32_e32 v230, v7, v11
	v_sub_f32_e32 v232, v7, v11
	v_mul_f32_e32 v235, v0, v20
	v_mul_f32_e32 v236, v0, v21
	v_fma_f32 v233, v2, v21, v235
	v_fma_f32 v234, v2, v20, -v236
	v_mul_f32_e32 v235, v231, v20
	v_mul_f32_e32 v236, v231, v21
	v_fma_f32 v237, v232, v21, v235
	v_fma_f32 v238, v232, v20, -v236
	v_add_f32_e32 v4, v25, v3
	v_add_f32_e32 v5, v26, v230
	v_sub_f32_e32 v25, v25, v3
	v_sub_f32_e32 v26, v26, v230
	v_mul_f32_e32 v235, v25, v22
	v_mul_f32_e32 v236, v25, v23
	v_fma_f32 v6, v26, v23, v235
	v_fma_f32 v7, v26, v22, -v236
	v_add_f32_e32 v8, v233, v238
	v_sub_f32_e32 v9, v234, v237
	v_sub_f32_e32 v3, v233, v238
	v_add_f32_e32 v230, v234, v237
	v_mul_f32_e32 v235, v3, v22
	v_mul_f32_e32 v236, v3, v23
	v_fma_f32 v10, v230, v23, v235
	v_fma_f32 v11, v230, v22, -v236
	ds_write_b64 v16, v[4:5]
	ds_write_b64 v17, v[6:7]
	ds_write_b64 v18, v[8:9]
	ds_write_b64 v19, v[10:11]
	v_add_u32_e32 v234, 0x400, v34
	v_and_b32_e32 v235, 15, v234
	v_sub_u32_e32 v236, v234, v235
	v_lshl_or_b32 v236, v236, 2, v235
	v_cvt_f32_u32_e32 v235, v235
	v_mul_f32_e32 v235, 0x3c800000, v235
	v_cos_f32_e32 v20, v235
	v_sin_f32_e32 v21, v235
	v_lshl_add_u32 v12, v236, 3, v24
	v_add_u32_e32 v13, 0x80, v12
	v_add_u32_e32 v14, 0x100, v12
	v_add_u32_e32 v15, 0x180, v12
	v_bfe_u32 v237, v236, 5, 2
	v_bfe_u32 v238, v236, 6, 1
	v_lshl_or_b32 v237, v237, 2, v237
	v_lshl_or_b32 v237, v238, 4, v237
	v_xor_b32_e32 v237, v237, v236
	v_lshlrev_b32_e32 v237, 3, v237
	v_add_u32_e32 v16, v24, v237
	v_xad_u32 v17, v237, s0, v24
	v_xad_u32 v18, v237, s1, v24
	v_xad_u32 v19, v237, s4, v24
	v_mul_f32_e32 v22, v21, v21
	v_mul_f32_e32 v23, v21, v20
	v_fma_f32 v22, v20, v20, -v22
	v_fma_f32 v23, v20, v21, v23
	ds_read_b64 v[4:5], v12
	ds_read_b64 v[6:7], v13
	ds_read_b64 v[8:9], v14
	ds_read_b64 v[10:11], v15
	s_waitcnt lgkmcnt(0)
; DI float cos2pi(float x) { return __builtin_amdgcn_cosf(x); }
; DI float sin2pi(float x) { return __builtin_amdgcn_sinf(x); }
; template <bool INV>
; DI void fft_lds(float2* buf_, int L, int logL, int gtid, int NTG) {
;     ...
;       for (int t = gtid; t < (L >> 2); t += NTG) {
;         const int k = t & (S - 1), base = ((t - k) << 2) | k;
;         const v2f a0 = buf[base], a1 = buf[base + S], a2 = buf[base + 2 * S], a3 = buf[base + 3 * S];
;         const float fr = (float)k * i4;
;         const v2f w1 = v2f{cos2pi(fr), sin2pi(fr)};
;         const v2f w2 = vcmul(w1, w1);
;         const v2f x0 = a0 + a2;
;         const v2f x2 = vcmulc(a0 - a2, w1);
;         const v2f x1 = a1 + a3;
;         const v2f d13 = vcmulc(a1 - a3, w1);
;         const v2f x3 = v2f{d13.y, -d13.x};
;         buf[base] = x0 + x1;
;         buf[base + S] = vcmulc(x0 - x1, w2);
;         buf[base + 2 * S] = x2 + x3;
;         buf[base + 3 * S] = vcmulc(x2 - x3, w2);
;       }
	v_add_f32_e32 v25, v4, v8
	v_sub_f32_e32 v0, v4, v8
	v_add_f32_e32 v3, v6, v10
	v_sub_f32_e32 v231, v6, v10
	v_add_f32_e32 v26, v5, v9
	v_sub_f32_e32 v2, v5, v9
	v_add_f32_e32 v230, v7, v11
	v_sub_f32_e32 v232, v7, v11
	v_mul_f32_e32 v235, v0, v20
	v_mul_f32_e32 v236, v0, v21
	v_fma_f32 v233, v2, v21, v235
	v_fma_f32 v234, v2, v20, -v236
	v_mul_f32_e32 v235, v231, v20
	v_mul_f32_e32 v236, v231, v21
	v_fma_f32 v237, v232, v21, v235
	v_fma_f32 v238, v232, v20, -v236
	v_add_f32_e32 v4, v25, v3
	v_add_f32_e32 v5, v26, v230
	v_sub_f32_e32 v25, v25, v3
	v_sub_f32_e32 v26, v26, v230
	v_mul_f32_e32 v235, v25, v22
	v_mul_f32_e32 v236, v25, v23
	v_fma_f32 v6, v26, v23, v235
	v_fma_f32 v7, v26, v22, -v236
	v_add_f32_e32 v8, v233, v238
	v_sub_f32_e32 v9, v234, v237
	v_sub_f32_e32 v3, v233, v238
	v_add_f32_e32 v230, v234, v237
	v_mul_f32_e32 v235, v3, v22
	v_mul_f32_e32 v236, v3, v23
	v_fma_f32 v10, v230, v23, v235
	v_fma_f32 v11, v230, v22, -v236
	ds_write_b64 v16, v[4:5]
	ds_write_b64 v17, v[6:7]
	ds_write_b64 v18, v[8:9]
	ds_write_b64 v19, v[10:11]
	v_add_u32_e32 v234, 0x600, v34
	v_and_b32_e32 v235, 15, v234
	v_sub_u32_e32 v236, v234, v235
	v_lshl_or_b32 v236, v236, 2, v235
	v_cvt_f32_u32_e32 v235, v235
	v_mul_f32_e32 v235, 0x3c800000, v235
	v_cos_f32_e32 v20, v235
	v_sin_f32_e32 v21, v235
	v_lshl_add_u32 v12, v236, 3, v24
	v_add_u32_e32 v13, 0x80, v12
	v_add_u32_e32 v14, 0x100, v12
	v_add_u32_e32 v15, 0x180, v12
	v_bfe_u32 v237, v236, 5, 2
	v_bfe_u32 v238, v236, 6, 1
	v_lshl_or_b32 v237, v237, 2, v237
	v_lshl_or_b32 v237, v238, 4, v237
	v_xor_b32_e32 v237, v237, v236
	v_lshlrev_b32_e32 v237, 3, v237
	v_add_u32_e32 v16, v24, v237
	v_xad_u32 v17, v237, s0, v24
	v_xad_u32 v18, v237, s1, v24
	v_xad_u32 v19, v237, s4, v24
	v_mul_f32_e32 v22, v21, v21
	v_mul_f32_e32 v23, v21, v20
	v_fma_f32 v22, v20, v20, -v22
	v_fma_f32 v23, v20, v21, v23
	ds_read_b64 v[4:5], v12
	ds_read_b64 v[6:7], v13
	ds_read_b64 v[8:9], v14
	ds_read_b64 v[10:11], v15
	s_waitcnt lgkmcnt(0)
	v_add_f32_e32 v25, v4, v8
	v_sub_f32_e32 v0, v4, v8
	v_add_f32_e32 v3, v6, v10
	v_sub_f32_e32 v231, v6, v10
	v_add_f32_e32 v26, v5, v9
	v_sub_f32_e32 v2, v5, v9
	v_add_f32_e32 v230, v7, v11
	v_sub_f32_e32 v232, v7, v11
	v_mul_f32_e32 v235, v0, v20
	v_mul_f32_e32 v236, v0, v21
	v_fma_f32 v233, v2, v21, v235
	v_fma_f32 v234, v2, v20, -v236
	v_mul_f32_e32 v235, v231, v20
	v_mul_f32_e32 v236, v231, v21
	v_fma_f32 v237, v232, v21, v235
	v_fma_f32 v238, v232, v20, -v236
	v_add_f32_e32 v4, v25, v3
	v_add_f32_e32 v5, v26, v230
	v_sub_f32_e32 v25, v25, v3
	v_sub_f32_e32 v26, v26, v230
	v_mul_f32_e32 v235, v25, v22
	v_mul_f32_e32 v236, v25, v23
	v_fma_f32 v6, v26, v23, v235
	v_fma_f32 v7, v26, v22, -v236
	v_add_f32_e32 v8, v233, v238
	v_sub_f32_e32 v9, v234, v237
	v_sub_f32_e32 v3, v233, v238
	v_add_f32_e32 v230, v234, v237
	v_mul_f32_e32 v235, v3, v22
	v_mul_f32_e32 v236, v3, v23
	v_fma_f32 v10, v230, v23, v235
	v_fma_f32 v11, v230, v22, -v236
	ds_write_b64 v16, v[4:5]
	ds_write_b64 v17, v[6:7]
	ds_write_b64 v18, v[8:9]
	ds_write_b64 v19, v[10:11]
	v_add_u32_e32 v234, 0x800, v34
	v_and_b32_e32 v235, 15, v234
	v_sub_u32_e32 v236, v234, v235
	v_lshl_or_b32 v236, v236, 2, v235
	v_cvt_f32_u32_e32 v235, v235
	v_mul_f32_e32 v235, 0x3c800000, v235
	v_cos_f32_e32 v20, v235
	v_sin_f32_e32 v21, v235
	v_lshl_add_u32 v12, v236, 3, v24
	v_add_u32_e32 v13, 0x80, v12
	v_add_u32_e32 v14, 0x100, v12
	v_add_u32_e32 v15, 0x180, v12
	v_bfe_u32 v237, v236, 5, 2
	v_bfe_u32 v238, v236, 6, 1
	v_lshl_or_b32 v237, v237, 2, v237
	v_lshl_or_b32 v237, v238, 4, v237
	v_xor_b32_e32 v237, v237, v236
	v_lshlrev_b32_e32 v237, 3, v237
	v_add_u32_e32 v16, v24, v237
	v_xad_u32 v17, v237, s0, v24
	v_xad_u32 v18, v237, s1, v24
	v_xad_u32 v19, v237, s4, v24
	v_mul_f32_e32 v22, v21, v21
	v_mul_f32_e32 v23, v21, v20
	v_fma_f32 v22, v20, v20, -v22
	v_fma_f32 v23, v20, v21, v23
	ds_read_b64 v[4:5], v12
	ds_read_b64 v[6:7], v13
	ds_read_b64 v[8:9], v14
	ds_read_b64 v[10:11], v15
	s_waitcnt lgkmcnt(0)
	v_add_f32_e32 v25, v4, v8
	v_sub_f32_e32 v0, v4, v8
	v_add_f32_e32 v3, v6, v10
	v_sub_f32_e32 v231, v6, v10
	v_add_f32_e32 v26, v5, v9
	v_sub_f32_e32 v2, v5, v9
	v_add_f32_e32 v230, v7, v11
	v_sub_f32_e32 v232, v7, v11
	v_mul_f32_e32 v235, v0, v20
	v_mul_f32_e32 v236, v0, v21
	v_fma_f32 v233, v2, v21, v235
	v_fma_f32 v234, v2, v20, -v236
	v_mul_f32_e32 v235, v231, v20
	v_mul_f32_e32 v236, v231, v21
	v_fma_f32 v237, v232, v21, v235
	v_fma_f32 v238, v232, v20, -v236
	v_add_f32_e32 v4, v25, v3
	v_add_f32_e32 v5, v26, v230
	v_sub_f32_e32 v25, v25, v3
	v_sub_f32_e32 v26, v26, v230
	v_mul_f32_e32 v235, v25, v22
	v_mul_f32_e32 v236, v25, v23
	v_fma_f32 v6, v26, v23, v235
	v_fma_f32 v7, v26, v22, -v236
	v_add_f32_e32 v8, v233, v238
	v_sub_f32_e32 v9, v234, v237
	v_sub_f32_e32 v3, v233, v238
	v_add_f32_e32 v230, v234, v237
	v_mul_f32_e32 v235, v3, v22
	v_mul_f32_e32 v236, v3, v23
	v_fma_f32 v10, v230, v23, v235
	v_fma_f32 v11, v230, v22, -v236
	ds_write_b64 v16, v[4:5]
	ds_write_b64 v17, v[6:7]
	ds_write_b64 v18, v[8:9]
	ds_write_b64 v19, v[10:11]
	v_add_u32_e32 v234, 0xa00, v34
	v_and_b32_e32 v235, 15, v234
	v_sub_u32_e32 v236, v234, v235
	v_lshl_or_b32 v236, v236, 2, v235
	v_cvt_f32_u32_e32 v235, v235
	v_mul_f32_e32 v235, 0x3c800000, v235
	v_cos_f32_e32 v20, v235
	v_sin_f32_e32 v21, v235
	v_lshl_add_u32 v12, v236, 3, v24
	v_add_u32_e32 v13, 0x80, v12
	v_add_u32_e32 v14, 0x100, v12
	v_add_u32_e32 v15, 0x180, v12
	v_bfe_u32 v237, v236, 5, 2
	v_bfe_u32 v238, v236, 6, 1
	v_lshl_or_b32 v237, v237, 2, v237
	v_lshl_or_b32 v237, v238, 4, v237
	v_xor_b32_e32 v237, v237, v236
	v_lshlrev_b32_e32 v237, 3, v237
	v_add_u32_e32 v16, v24, v237
	v_xad_u32 v17, v237, s0, v24
	v_xad_u32 v18, v237, s1, v24
	v_xad_u32 v19, v237, s4, v24
	v_mul_f32_e32 v22, v21, v21
	v_mul_f32_e32 v23, v21, v20
	v_fma_f32 v22, v20, v20, -v22
	v_fma_f32 v23, v20, v21, v23
	ds_read_b64 v[4:5], v12
	ds_read_b64 v[6:7], v13
	ds_read_b64 v[8:9], v14
	ds_read_b64 v[10:11], v15
	s_waitcnt lgkmcnt(0)
; DI float cos2pi(float x) { return __builtin_amdgcn_cosf(x); }
; DI float sin2pi(float x) { return __builtin_amdgcn_sinf(x); }
; template <bool INV>
; DI void fft_lds(float2* buf_, int L, int logL, int gtid, int NTG) {
;     ...
;       for (int t = gtid; t < (L >> 2); t += NTG) {
;         const int k = t & (S - 1), base = ((t - k) << 2) | k;
;         const v2f a0 = buf[base], a1 = buf[base + S], a2 = buf[base + 2 * S], a3 = buf[base + 3 * S];
;         const float fr = (float)k * i4;
;         const v2f w1 = v2f{cos2pi(fr), sin2pi(fr)};
;         const v2f w2 = vcmul(w1, w1);
;         const v2f x0 = a0 + a2;
;         const v2f x2 = vcmulc(a0 - a2, w1);
;         const v2f x1 = a1 + a3;
;         const v2f d13 = vcmulc(a1 - a3, w1);
;         const v2f x3 = v2f{d13.y, -d13.x};
;         buf[base] = x0 + x1;
;         buf[base + S] = vcmulc(x0 - x1, w2);
;         buf[base + 2 * S] = x2 + x3;
;         buf[base + 3 * S] = vcmulc(x2 - x3, w2);
;       }
	v_add_f32_e32 v25, v4, v8
	v_sub_f32_e32 v0, v4, v8
	v_add_f32_e32 v3, v6, v10
	v_sub_f32_e32 v231, v6, v10
	v_add_f32_e32 v26, v5, v9
	v_sub_f32_e32 v2, v5, v9
	v_add_f32_e32 v230, v7, v11
	v_sub_f32_e32 v232, v7, v11
	v_mul_f32_e32 v235, v0, v20
	v_mul_f32_e32 v236, v0, v21
	v_fma_f32 v233, v2, v21, v235
	v_fma_f32 v234, v2, v20, -v236
	v_mul_f32_e32 v235, v231, v20
	v_mul_f32_e32 v236, v231, v21
	v_fma_f32 v237, v232, v21, v235
	v_fma_f32 v238, v232, v20, -v236
	v_add_f32_e32 v4, v25, v3
	v_add_f32_e32 v5, v26, v230
	v_sub_f32_e32 v25, v25, v3
	v_sub_f32_e32 v26, v26, v230
	v_mul_f32_e32 v235, v25, v22
	v_mul_f32_e32 v236, v25, v23
	v_fma_f32 v6, v26, v23, v235
	v_fma_f32 v7, v26, v22, -v236
	v_add_f32_e32 v8, v233, v238
	v_sub_f32_e32 v9, v234, v237
	v_sub_f32_e32 v3, v233, v238
	v_add_f32_e32 v230, v234, v237
	v_mul_f32_e32 v235, v3, v22
	v_mul_f32_e32 v236, v3, v23
	v_fma_f32 v10, v230, v23, v235
	v_fma_f32 v11, v230, v22, -v236
	ds_write_b64 v16, v[4:5]
	ds_write_b64 v17, v[6:7]
	ds_write_b64 v18, v[8:9]
	ds_write_b64 v19, v[10:11]
	v_add_u32_e32 v234, 0xc00, v34
	v_and_b32_e32 v235, 15, v234
	v_sub_u32_e32 v236, v234, v235
	v_lshl_or_b32 v236, v236, 2, v235
	v_cvt_f32_u32_e32 v235, v235
	v_mul_f32_e32 v235, 0x3c800000, v235
	v_cos_f32_e32 v20, v235
	v_sin_f32_e32 v21, v235
	v_lshl_add_u32 v12, v236, 3, v24
	v_add_u32_e32 v13, 0x80, v12
	v_add_u32_e32 v14, 0x100, v12
	v_add_u32_e32 v15, 0x180, v12
	v_bfe_u32 v237, v236, 5, 2
	v_bfe_u32 v238, v236, 6, 1
	v_lshl_or_b32 v237, v237, 2, v237
	v_lshl_or_b32 v237, v238, 4, v237
	v_xor_b32_e32 v237, v237, v236
	v_lshlrev_b32_e32 v237, 3, v237
	v_add_u32_e32 v16, v24, v237
	v_xad_u32 v17, v237, s0, v24
	v_xad_u32 v18, v237, s1, v24
	v_xad_u32 v19, v237, s4, v24
	v_mul_f32_e32 v22, v21, v21
	v_mul_f32_e32 v23, v21, v20
	v_fma_f32 v22, v20, v20, -v22
	v_fma_f32 v23, v20, v21, v23
	ds_read_b64 v[4:5], v12
	ds_read_b64 v[6:7], v13
	ds_read_b64 v[8:9], v14
	ds_read_b64 v[10:11], v15
	s_waitcnt lgkmcnt(0)
	v_add_f32_e32 v25, v4, v8
	v_sub_f32_e32 v0, v4, v8
	v_add_f32_e32 v3, v6, v10
	v_sub_f32_e32 v231, v6, v10
	v_add_f32_e32 v26, v5, v9
	v_sub_f32_e32 v2, v5, v9
	v_add_f32_e32 v230, v7, v11
	v_sub_f32_e32 v232, v7, v11
	v_mul_f32_e32 v235, v0, v20
	v_mul_f32_e32 v236, v0, v21
	v_fma_f32 v233, v2, v21, v235
	v_fma_f32 v234, v2, v20, -v236
	v_mul_f32_e32 v235, v231, v20
	v_mul_f32_e32 v236, v231, v21
	v_fma_f32 v237, v232, v21, v235
	v_fma_f32 v238, v232, v20, -v236
	v_add_f32_e32 v4, v25, v3
	v_add_f32_e32 v5, v26, v230
	v_sub_f32_e32 v25, v25, v3
	v_sub_f32_e32 v26, v26, v230
	v_mul_f32_e32 v235, v25, v22
	v_mul_f32_e32 v236, v25, v23
	v_fma_f32 v6, v26, v23, v235
	v_fma_f32 v7, v26, v22, -v236
	v_add_f32_e32 v8, v233, v238
	v_sub_f32_e32 v9, v234, v237
	v_sub_f32_e32 v3, v233, v238
	v_add_f32_e32 v230, v234, v237
	v_mul_f32_e32 v235, v3, v22
	v_mul_f32_e32 v236, v3, v23
	v_fma_f32 v10, v230, v23, v235
	v_fma_f32 v11, v230, v22, -v236
	ds_write_b64 v16, v[4:5]
	ds_write_b64 v17, v[6:7]
	ds_write_b64 v18, v[8:9]
	ds_write_b64 v19, v[10:11]
	v_add_u32_e32 v234, 0xe00, v34
	v_and_b32_e32 v235, 15, v234
	v_sub_u32_e32 v236, v234, v235
	v_lshl_or_b32 v236, v236, 2, v235
	v_cvt_f32_u32_e32 v235, v235
	v_mul_f32_e32 v235, 0x3c800000, v235
	v_cos_f32_e32 v20, v235
	v_sin_f32_e32 v21, v235
	v_lshl_add_u32 v12, v236, 3, v24
	v_add_u32_e32 v13, 0x80, v12
	v_add_u32_e32 v14, 0x100, v12
	v_add_u32_e32 v15, 0x180, v12
	v_bfe_u32 v237, v236, 5, 2
	v_bfe_u32 v238, v236, 6, 1
	v_lshl_or_b32 v237, v237, 2, v237
	v_lshl_or_b32 v237, v238, 4, v237
	v_xor_b32_e32 v237, v237, v236
	v_lshlrev_b32_e32 v237, 3, v237
	v_add_u32_e32 v16, v24, v237
	v_xad_u32 v17, v237, s0, v24
	v_xad_u32 v18, v237, s1, v24
	v_xad_u32 v19, v237, s4, v24
	v_mul_f32_e32 v22, v21, v21
	v_mul_f32_e32 v23, v21, v20
	v_fma_f32 v22, v20, v20, -v22
	v_fma_f32 v23, v20, v21, v23
	ds_read_b64 v[4:5], v12
	ds_read_b64 v[6:7], v13
	ds_read_b64 v[8:9], v14
	ds_read_b64 v[10:11], v15
	s_waitcnt lgkmcnt(0)
	v_add_f32_e32 v25, v4, v8
	v_sub_f32_e32 v0, v4, v8
	v_add_f32_e32 v3, v6, v10
	v_sub_f32_e32 v231, v6, v10
	v_add_f32_e32 v26, v5, v9
	v_sub_f32_e32 v2, v5, v9
	v_add_f32_e32 v230, v7, v11
	v_sub_f32_e32 v232, v7, v11
	v_mul_f32_e32 v235, v0, v20
	v_mul_f32_e32 v236, v0, v21
	v_fma_f32 v233, v2, v21, v235
	v_fma_f32 v234, v2, v20, -v236
	v_mul_f32_e32 v235, v231, v20
	v_mul_f32_e32 v236, v231, v21
	v_fma_f32 v237, v232, v21, v235
	v_fma_f32 v238, v232, v20, -v236
	v_add_f32_e32 v4, v25, v3
	v_add_f32_e32 v5, v26, v230
	v_sub_f32_e32 v25, v25, v3
	v_sub_f32_e32 v26, v26, v230
	v_mul_f32_e32 v235, v25, v22
	v_mul_f32_e32 v236, v25, v23
	v_fma_f32 v6, v26, v23, v235
	v_fma_f32 v7, v26, v22, -v236
	v_add_f32_e32 v8, v233, v238
	v_sub_f32_e32 v9, v234, v237
	v_sub_f32_e32 v3, v233, v238
	v_add_f32_e32 v230, v234, v237
	v_mul_f32_e32 v235, v3, v22
	v_mul_f32_e32 v236, v3, v23
	v_fma_f32 v10, v230, v23, v235
	v_fma_f32 v11, v230, v22, -v236
	ds_write_b64 v16, v[4:5]
	ds_write_b64 v17, v[6:7]
	ds_write_b64 v18, v[8:9]
	ds_write_b64 v19, v[10:11]
	s_branch .LBB0_609
; DI float cos2pi(float x) { return __builtin_amdgcn_cosf(x); }
; DI float sin2pi(float x) { return __builtin_amdgcn_sinf(x); }
; template <bool INV>
; DI void fft_lds(float2* buf_, int L, int logL, int gtid, int NTG) {
;     ...
;     for (; s >= 2; s >>= 2) {
;       const int S = s >> 1;
;       const float i4 = 0.25f / (float)S;
; #pragma unroll 8
;       for (int t = gtid; t < (L >> 2); t += NTG) {
;         const int k = t & (S - 1), base = ((t - k) << 2) | k;
;         const v2f a0 = buf[base], a1 = buf[base + S], a2 = buf[base + 2 * S], a3 = buf[base + 3 * S];
;         const float fr = (float)k * i4;
;         const v2f w1 = v2f{cos2pi(fr), sin2pi(fr)};
;         const v2f w2 = vcmul(w1, w1);
;         const v2f x0 = a0 + a2;
;         const v2f x2 = vcmulc(a0 - a2, w1);
;         const v2f x1 = a1 + a3;
;         const v2f d13 = vcmulc(a1 - a3, w1);
;         const v2f x3 = v2f{d13.y, -d13.x};
;         buf[base] = x0 + x1;
;         buf[base + S] = vcmulc(x0 - x1, w2);
;         buf[base + 2 * S] = x2 + x3;
;         buf[base + 3 * S] = vcmulc(x2 - x3, w2);
;       }
.Lffs_g1:
	s_cmp_eq_u32 s9, 16
	s_cbranch_scc1 .Lffs_g1x16
	s_cmp_eq_u32 s9, 4
	s_cbranch_scc1 .Lffs_g1x4
	s_movk_i32 s0, 0x8
	s_movk_i32 s1, 0x10
	s_movk_i32 s4, 0x18
	v_mov_b32_e32 v24, 0x50
	v_mov_b32_e32 v234, v34
	v_lshlrev_b32_e32 v236, 2, v234
	v_lshl_add_u32 v16, v236, 3, v24
	v_bfe_u32 v237, v236, 5, 2
	v_bfe_u32 v238, v236, 6, 1
	v_lshl_or_b32 v237, v237, 2, v237
	v_lshl_or_b32 v237, v238, 4, v237
	v_xor_b32_e32 v237, v237, v236
	v_lshlrev_b32_e32 v237, 3, v237
	v_add_u32_e32 v12, v24, v237
	v_xad_u32 v13, v237, s0, v24
	v_xad_u32 v14, v237, s1, v24
	v_xad_u32 v15, v237, s4, v24
	ds_read_b64 v[4:5], v12
	ds_read_b64 v[6:7], v13
	ds_read_b64 v[8:9], v14
	ds_read_b64 v[10:11], v15
	s_waitcnt lgkmcnt(0)
	v_add_f32_e32 v25, v4, v8
	v_sub_f32_e32 v0, v4, v8
	v_add_f32_e32 v3, v6, v10
	v_sub_f32_e32 v231, v6, v10
	v_add_f32_e32 v26, v5, v9
	v_sub_f32_e32 v2, v5, v9
	v_add_f32_e32 v230, v7, v11
	v_sub_f32_e32 v232, v7, v11
	v_add_f32_e32 v4, v25, v3
	v_add_f32_e32 v5, v26, v230
	v_sub_f32_e32 v6, v25, v3
	v_sub_f32_e32 v7, v26, v230
	v_add_f32_e32 v8, v0, v232
	v_sub_f32_e32 v9, v2, v231
	v_sub_f32_e32 v10, v0, v232
	v_add_f32_e32 v11, v2, v231
	ds_write_b128 v16, v[4:7]
	ds_write_b128 v16, v[8:11] offset:16
	s_branch .LBB0_609
.Lffs_g1x4:
	s_movk_i32 s0, 0x20
	s_movk_i32 s1, 0x40
	s_movk_i32 s4, 0x60
	v_mov_b32_e32 v24, 0x50
	v_mov_b32_e32 v234, v34
	v_and_b32_e32 v235, 3, v234
	v_sub_u32_e32 v236, v234, v235
	v_lshl_or_b32 v236, v236, 2, v235
	v_cvt_f32_u32_e32 v235, v235
	v_mul_f32_e32 v235, 0x3d800000, v235
	v_cos_f32_e32 v20, v235
	v_sin_f32_e32 v21, v235
	v_bfe_u32 v237, v236, 5, 2
	v_bfe_u32 v238, v236, 6, 1
	v_lshl_or_b32 v237, v237, 2, v237
	v_lshl_or_b32 v237, v238, 4, v237
	v_xor_b32_e32 v237, v237, v236
	v_lshlrev_b32_e32 v237, 3, v237
	v_add_u32_e32 v12, v24, v237
	v_xad_u32 v13, v237, s0, v24
	v_xad_u32 v14, v237, s1, v24
	v_xad_u32 v15, v237, s4, v24
	v_mul_f32_e32 v22, v21, v21
	v_mul_f32_e32 v23, v21, v20
	v_fma_f32 v22, v20, v20, -v22
	v_fma_f32 v23, v20, v21, v23
	ds_read_b64 v[4:5], v12
	ds_read_b64 v[6:7], v13
	ds_read_b64 v[8:9], v14
	ds_read_b64 v[10:11], v15
	s_waitcnt lgkmcnt(0)
	v_add_f32_e32 v25, v4, v8
	v_sub_f32_e32 v0, v4, v8
	v_add_f32_e32 v3, v6, v10
	v_sub_f32_e32 v231, v6, v10
	v_add_f32_e32 v26, v5, v9
	v_sub_f32_e32 v2, v5, v9
	v_add_f32_e32 v230, v7, v11
	v_sub_f32_e32 v232, v7, v11
	v_mul_f32_e32 v235, v0, v20
	v_mul_f32_e32 v236, v0, v21
	v_fma_f32 v233, v2, v21, v235
	v_fma_f32 v234, v2, v20, -v236
	v_mul_f32_e32 v235, v231, v20
	v_mul_f32_e32 v236, v231, v21
	v_fma_f32 v237, v232, v21, v235
	v_fma_f32 v238, v232, v20, -v236
	v_add_f32_e32 v4, v25, v3
	v_add_f32_e32 v5, v26, v230
	v_sub_f32_e32 v25, v25, v3
	v_sub_f32_e32 v26, v26, v230
	v_mul_f32_e32 v235, v25, v22
	v_mul_f32_e32 v236, v25, v23
	v_fma_f32 v6, v26, v23, v235
	v_fma_f32 v7, v26, v22, -v236
	v_add_f32_e32 v8, v233, v238
	v_sub_f32_e32 v9, v234, v237
	v_sub_f32_e32 v3, v233, v238
	v_add_f32_e32 v230, v234, v237
	v_mul_f32_e32 v235, v3, v22
	v_mul_f32_e32 v236, v3, v23
	v_fma_f32 v10, v230, v23, v235
	v_fma_f32 v11, v230, v22, -v236
	ds_write_b64 v12, v[4:5]
	ds_write_b64 v13, v[6:7]
	ds_write_b64 v14, v[8:9]
	ds_write_b64 v15, v[10:11]
	s_branch .LBB0_609
.Lffs_g1x16:
	s_movk_i32 s0, 0x80
	s_movk_i32 s1, 0x128
	s_movk_i32 s4, 0x1a8
	v_mov_b32_e32 v24, 0x50
	v_mov_b32_e32 v234, v34
	v_and_b32_e32 v235, 15, v234
	v_sub_u32_e32 v236, v234, v235
	v_lshl_or_b32 v236, v236, 2, v235
	v_cvt_f32_u32_e32 v235, v235
	v_mul_f32_e32 v235, 0x3c800000, v235
	v_cos_f32_e32 v20, v235
	v_sin_f32_e32 v21, v235
	v_lshl_add_u32 v12, v236, 3, v24
	v_add_u32_e32 v13, 0x80, v12
	v_add_u32_e32 v14, 0x100, v12
	v_add_u32_e32 v15, 0x180, v12
	v_bfe_u32 v237, v236, 5, 2
	v_bfe_u32 v238, v236, 6, 1
	v_lshl_or_b32 v237, v237, 2, v237
	v_lshl_or_b32 v237, v238, 4, v237
	v_xor_b32_e32 v237, v237, v236
	v_lshlrev_b32_e32 v237, 3, v237
	v_add_u32_e32 v16, v24, v237
	v_xad_u32 v17, v237, s0, v24
	v_xad_u32 v18, v237, s1, v24
	v_xad_u32 v19, v237, s4, v24
	v_mul_f32_e32 v22, v21, v21
	v_mul_f32_e32 v23, v21, v20
	v_fma_f32 v22, v20, v20, -v22
	v_fma_f32 v23, v20, v21, v23
	ds_read_b64 v[4:5], v12
	ds_read_b64 v[6:7], v13
	ds_read_b64 v[8:9], v14
	ds_read_b64 v[10:11], v15
	s_waitcnt lgkmcnt(0)
	v_add_f32_e32 v25, v4, v8
	v_sub_f32_e32 v0, v4, v8
	v_add_f32_e32 v3, v6, v10
	v_sub_f32_e32 v231, v6, v10
	v_add_f32_e32 v26, v5, v9
	v_sub_f32_e32 v2, v5, v9
	v_add_f32_e32 v230, v7, v11
	v_sub_f32_e32 v232, v7, v11
	v_mul_f32_e32 v235, v0, v20
	v_mul_f32_e32 v236, v0, v21
	v_fma_f32 v233, v2, v21, v235
	v_fma_f32 v234, v2, v20, -v236
	v_mul_f32_e32 v235, v231, v20
	v_mul_f32_e32 v236, v231, v21
	v_fma_f32 v237, v232, v21, v235
	v_fma_f32 v238, v232, v20, -v236
	v_add_f32_e32 v4, v25, v3
	v_add_f32_e32 v5, v26, v230
	v_sub_f32_e32 v25, v25, v3
	v_sub_f32_e32 v26, v26, v230
	v_mul_f32_e32 v235, v25, v22
	v_mul_f32_e32 v236, v25, v23
	v_fma_f32 v6, v26, v23, v235
	v_fma_f32 v7, v26, v22, -v236
	v_add_f32_e32 v8, v233, v238
	v_sub_f32_e32 v9, v234, v237
	v_sub_f32_e32 v3, v233, v238
	v_add_f32_e32 v230, v234, v237
	v_mul_f32_e32 v235, v3, v22
	v_mul_f32_e32 v236, v3, v23
	v_fma_f32 v10, v230, v23, v235
	v_fma_f32 v11, v230, v22, -v236
	ds_write_b64 v16, v[4:5]
	ds_write_b64 v17, v[6:7]
	ds_write_b64 v18, v[8:9]
	ds_write_b64 v19, v[10:11]
	s_branch .LBB0_609
.Lffs_g_skip:
	v_cvt_f32_u32_e32 v0, s9
	s_and_b32 s10, s6, 0x7ffffffe
	s_add_i32 s7, s9, -1
	s_mul_i32 s11, s9, 24
	v_div_scale_f32 v2, s[0:1], v0, v0, s60
	v_rcp_f32_e32 v3, v2
	v_div_scale_f32 v4, vcc, s60, v0, s60
	v_fma_f32 v5, -v2, v3, 1.0
	v_fmac_f32_e32 v3, v5, v3
	v_mul_f32_e32 v5, v4, v3
	v_fma_f32 v6, -v2, v5, v4
	v_fmac_f32_e32 v5, v6, v3
	v_fma_f32 v2, -v2, v5, v4
	v_div_fmas_f32 v2, v2, v3, v5
	v_div_fixup_f32 v0, v2, v0, s60
	v_mov_b32_e32 v2, v34
	s_and_saveexec_b64 s[0:1], s[38:39]
	s_cbranch_execz .LBB0_615
	s_lshl_b32 s4, s9, 3
	s_add_i32 s28, s4, 0x50
	s_lshl_b32 s4, s10, 3
	s_add_i32 s29, s4, 0x50
	s_add_i32 s34, s11, 0x50
	s_mov_b64 s[4:5], 0
	v_mov_b32_e32 v3, v97
	v_mov_b32_e32 v4, v76
	v_mov_b32_e32 v2, v34

; DI float cos2pi(float x) { return __builtin_amdgcn_cosf(x); }
; DI float sin2pi(float x) { return __builtin_amdgcn_sinf(x); }
; template <bool INV>
; DI void fft_lds(float2* buf_, int L, int logL, int gtid, int NTG) {
;     ...
;     for (; s >= 2; s >>= 2) {
;       const int S = s >> 1;
;       const float i4 = 0.25f / (float)S;
; #pragma unroll 8
;       for (int t = gtid; t < (L >> 2); t += NTG) {
;         const int k = t & (S - 1), base = ((t - k) << 2) | k;
;         const v2f a0 = buf[base], a1 = buf[base + S], a2 = buf[base + 2 * S], a3 = buf[base + 3 * S];
;         const float fr = (float)k * i4;
;         const v2f w1 = v2f{cos2pi(fr), sin2pi(fr)};
;         const v2f w2 = vcmul(w1, w1);
;         const v2f x0 = a0 + a2;
;         const v2f x2 = vcmulc(a0 - a2, w1);
;         const v2f x1 = a1 + a3;
;         const v2f d13 = vcmulc(a1 - a3, w1);
;         const v2f x3 = v2f{d13.y, -d13.x};
;         buf[base] = x0 + x1;
;         buf[base + S] = vcmulc(x0 - x1, w2);
;         buf[base + 2 * S] = x2 + x3;
;         buf[base + 3 * S] = vcmulc(x2 - x3, w2);
;       }
.LBB0_705:
	s_and_saveexec_b64 s[54:55], s[18:19]
	s_cbranch_execz .LBB0_704
	s_lshr_b32 s82, s6, 1
	s_cmp_gt_u32 s82, 16
	s_cbranch_scc1 .Lffs_f_skip
	s_cmp_eq_u32 s82, 16
	s_cbranch_scc1 .Lffs_f16
	s_cmp_eq_u32 s82, 4
	s_cbranch_scc1 .Lffs_f4
	s_movk_i32 s0, 0x8
	s_movk_i32 s1, 0x10
	s_movk_i32 s4, 0x18
	v_mov_b32_e32 v250, v38
	v_lshlrev_b32_e32 v252, 2, v250
	v_lshl_add_u32 v102, v252, 3, v40
	v_bfe_u32 v253, v252, 5, 2
	v_bfe_u32 v254, v252, 6, 1
	v_lshl_or_b32 v253, v253, 2, v253
	v_lshl_or_b32 v253, v254, 4, v253
	v_xor_b32_e32 v253, v253, v252
	v_lshlrev_b32_e32 v253, 3, v253
	v_add_u32_e32 v72, v40, v253
	v_xad_u32 v73, v253, s0, v40
	v_xad_u32 v74, v253, s1, v40
	v_xad_u32 v75, v253, s4, v40
	ds_read_b64 v[64:65], v72
	ds_read_b64 v[66:67], v73
	ds_read_b64 v[68:69], v74
	ds_read_b64 v[70:71], v75
	v_mad_u32_u24 v250, s61, 1, v38
	v_lshlrev_b32_e32 v252, 2, v250
	v_lshl_add_u32 v242, v252, 3, v40
	v_bfe_u32 v253, v252, 5, 2
	v_bfe_u32 v254, v252, 6, 1
	v_lshl_or_b32 v253, v253, 2, v253
	v_lshl_or_b32 v253, v254, 4, v253
	v_xor_b32_e32 v253, v253, v252
	v_lshlrev_b32_e32 v253, 3, v253
	v_add_u32_e32 v238, v40, v253
	v_xad_u32 v239, v253, s0, v40
	v_xad_u32 v240, v253, s1, v40
	v_xad_u32 v241, v253, s4, v40
	ds_read_b64 v[230:231], v238
	ds_read_b64 v[232:233], v239
	ds_read_b64 v[234:235], v240
	ds_read_b64 v[236:237], v241
	s_waitcnt lgkmcnt(4)
	v_add_f32_e32 v110, v64, v68
	v_sub_f32_e32 v112, v64, v68
	v_add_f32_e32 v30, v66, v70
	v_sub_f32_e32 v32, v66, v70
	v_add_f32_e32 v111, v65, v69
	v_sub_f32_e32 v113, v65, v69
	v_add_f32_e32 v31, v67, v71
	v_sub_f32_e32 v33, v67, v71
	v_add_f32_e32 v64, v110, v30
	v_add_f32_e32 v65, v111, v31
	v_sub_f32_e32 v66, v110, v30
	v_sub_f32_e32 v67, v111, v31
	v_add_f32_e32 v68, v112, v33
	v_sub_f32_e32 v69, v113, v32
	v_sub_f32_e32 v70, v112, v33
	v_add_f32_e32 v71, v113, v32
	ds_write_b128 v102, v[64:67]
	ds_write_b128 v102, v[68:71] offset:16
	v_mad_u32_u24 v250, s61, 2, v38
	v_lshlrev_b32_e32 v252, 2, v250
	v_lshl_add_u32 v102, v252, 3, v40
	v_bfe_u32 v253, v252, 5, 2
	v_bfe_u32 v254, v252, 6, 1
	v_lshl_or_b32 v253, v253, 2, v253
	v_lshl_or_b32 v253, v254, 4, v253
	v_xor_b32_e32 v253, v253, v252
	v_lshlrev_b32_e32 v253, 3, v253
	v_add_u32_e32 v72, v40, v253
	v_xad_u32 v73, v253, s0, v40
	v_xad_u32 v74, v253, s1, v40
	v_xad_u32 v75, v253, s4, v40
	ds_read_b64 v[64:65], v72
	ds_read_b64 v[66:67], v73
	ds_read_b64 v[68:69], v74
	ds_read_b64 v[70:71], v75
	s_waitcnt lgkmcnt(6)
	v_add_f32_e32 v110, v230, v234
	v_sub_f32_e32 v112, v230, v234
	v_add_f32_e32 v30, v232, v236
	v_sub_f32_e32 v32, v232, v236
	v_add_f32_e32 v111, v231, v235
	v_sub_f32_e32 v113, v231, v235
	v_add_f32_e32 v31, v233, v237
	v_sub_f32_e32 v33, v233, v237
	v_add_f32_e32 v230, v110, v30
	v_add_f32_e32 v231, v111, v31
	v_sub_f32_e32 v232, v110, v30
	v_sub_f32_e32 v233, v111, v31
	v_add_f32_e32 v234, v112, v33
	v_sub_f32_e32 v235, v113, v32
	v_sub_f32_e32 v236, v112, v33
	v_add_f32_e32 v237, v113, v32
	ds_write_b128 v242, v[230:233]
	ds_write_b128 v242, v[234:237] offset:16
	v_mad_u32_u24 v250, s61, 3, v38
	v_lshlrev_b32_e32 v252, 2, v250
	v_lshl_add_u32 v242, v252, 3, v40
	v_bfe_u32 v253, v252, 5, 2
	v_bfe_u32 v254, v252, 6, 1
	v_lshl_or_b32 v253, v253, 2, v253
	v_lshl_or_b32 v253, v254, 4, v253
	v_xor_b32_e32 v253, v253, v252
	v_lshlrev_b32_e32 v253, 3, v253
	v_add_u32_e32 v238, v40, v253
	v_xad_u32 v239, v253, s0, v40
	v_xad_u32 v240, v253, s1, v40
	v_xad_u32 v241, v253, s4, v40
	ds_read_b64 v[230:231], v238
	ds_read_b64 v[232:233], v239
	ds_read_b64 v[234:235], v240
	ds_read_b64 v[236:237], v241
	s_waitcnt lgkmcnt(6)
	v_add_f32_e32 v110, v64, v68
	v_sub_f32_e32 v112, v64, v68
	v_add_f32_e32 v30, v66, v70
	v_sub_f32_e32 v32, v66, v70
	v_add_f32_e32 v111, v65, v69
	v_sub_f32_e32 v113, v65, v69
	v_add_f32_e32 v31, v67, v71
	v_sub_f32_e32 v33, v67, v71
	v_add_f32_e32 v64, v110, v30
	v_add_f32_e32 v65, v111, v31
	v_sub_f32_e32 v66, v110, v30
	v_sub_f32_e32 v67, v111, v31
	v_add_f32_e32 v68, v112, v33
	v_sub_f32_e32 v69, v113, v32
	v_sub_f32_e32 v70, v112, v33
	v_add_f32_e32 v71, v113, v32
	ds_write_b128 v102, v[64:67]
	ds_write_b128 v102, v[68:71] offset:16
	v_mad_u32_u24 v250, s61, 4, v38
	v_lshlrev_b32_e32 v252, 2, v250
	v_lshl_add_u32 v102, v252, 3, v40
	v_bfe_u32 v253, v252, 5, 2
	v_bfe_u32 v254, v252, 6, 1
	v_lshl_or_b32 v253, v253, 2, v253
	v_lshl_or_b32 v253, v254, 4, v253
	v_xor_b32_e32 v253, v253, v252
	v_lshlrev_b32_e32 v253, 3, v253
	v_add_u32_e32 v72, v40, v253
	v_xad_u32 v73, v253, s0, v40
	v_xad_u32 v74, v253, s1, v40
	v_xad_u32 v75, v253, s4, v40
	ds_read_b64 v[64:65], v72
	ds_read_b64 v[66:67], v73
	ds_read_b64 v[68:69], v74
	ds_read_b64 v[70:71], v75
	s_waitcnt lgkmcnt(6)
	v_add_f32_e32 v110, v230, v234
	v_sub_f32_e32 v112, v230, v234
	v_add_f32_e32 v30, v232, v236
	v_sub_f32_e32 v32, v232, v236
	v_add_f32_e32 v111, v231, v235
	v_sub_f32_e32 v113, v231, v235
	v_add_f32_e32 v31, v233, v237
	v_sub_f32_e32 v33, v233, v237
	v_add_f32_e32 v230, v110, v30
	v_add_f32_e32 v231, v111, v31
	v_sub_f32_e32 v232, v110, v30
	v_sub_f32_e32 v233, v111, v31
	v_add_f32_e32 v234, v112, v33
	v_sub_f32_e32 v235, v113, v32
	v_sub_f32_e32 v236, v112, v33
	v_add_f32_e32 v237, v113, v32
	ds_write_b128 v242, v[230:233]
	ds_write_b128 v242, v[234:237] offset:16
	v_mad_u32_u24 v250, s61, 5, v38
	v_lshlrev_b32_e32 v252, 2, v250
	v_lshl_add_u32 v242, v252, 3, v40
	v_bfe_u32 v253, v252, 5, 2
	v_bfe_u32 v254, v252, 6, 1
	v_lshl_or_b32 v253, v253, 2, v253
	v_lshl_or_b32 v253, v254, 4, v253
	v_xor_b32_e32 v253, v253, v252
	v_lshlrev_b32_e32 v253, 3, v253
	v_add_u32_e32 v238, v40, v253
	v_xad_u32 v239, v253, s0, v40
	v_xad_u32 v240, v253, s1, v40
	v_xad_u32 v241, v253, s4, v40
	ds_read_b64 v[230:231], v238
	ds_read_b64 v[232:233], v239
	ds_read_b64 v[234:235], v240
	ds_read_b64 v[236:237], v241
	s_waitcnt lgkmcnt(6)
; DI float cos2pi(float x) { return __builtin_amdgcn_cosf(x); }
; DI float sin2pi(float x) { return __builtin_amdgcn_sinf(x); }
; template <bool INV>
; DI void fft_lds(float2* buf_, int L, int logL, int gtid, int NTG) {
;     ...
;     for (; s >= 2; s >>= 2) {
;       const int S = s >> 1;
;       const float i4 = 0.25f / (float)S;
; #pragma unroll 8
;       for (int t = gtid; t < (L >> 2); t += NTG) {
;         const int k = t & (S - 1), base = ((t - k) << 2) | k;
;         const v2f a0 = buf[base], a1 = buf[base + S], a2 = buf[base + 2 * S], a3 = buf[base + 3 * S];
;         const float fr = (float)k * i4;
;         const v2f w1 = v2f{cos2pi(fr), sin2pi(fr)};
;         const v2f w2 = vcmul(w1, w1);
;         const v2f x0 = a0 + a2;
;         const v2f x2 = vcmulc(a0 - a2, w1);
;         const v2f x1 = a1 + a3;
;         const v2f d13 = vcmulc(a1 - a3, w1);
;         const v2f x3 = v2f{d13.y, -d13.x};
;         buf[base] = x0 + x1;
;         buf[base + S] = vcmulc(x0 - x1, w2);
;         buf[base + 2 * S] = x2 + x3;
;         buf[base + 3 * S] = vcmulc(x2 - x3, w2);
;       }
	v_add_f32_e32 v110, v64, v68
	v_sub_f32_e32 v112, v64, v68
	v_add_f32_e32 v30, v66, v70
	v_sub_f32_e32 v32, v66, v70
	v_add_f32_e32 v111, v65, v69
	v_sub_f32_e32 v113, v65, v69
	v_add_f32_e32 v31, v67, v71
	v_sub_f32_e32 v33, v67, v71
	v_add_f32_e32 v64, v110, v30
	v_add_f32_e32 v65, v111, v31
	v_sub_f32_e32 v66, v110, v30
	v_sub_f32_e32 v67, v111, v31
	v_add_f32_e32 v68, v112, v33
	v_sub_f32_e32 v69, v113, v32
	v_sub_f32_e32 v70, v112, v33
	v_add_f32_e32 v71, v113, v32
	ds_write_b128 v102, v[64:67]
	ds_write_b128 v102, v[68:71] offset:16
	v_mad_u32_u24 v250, s61, 6, v38
	v_lshlrev_b32_e32 v252, 2, v250
	v_lshl_add_u32 v102, v252, 3, v40
	v_bfe_u32 v253, v252, 5, 2
	v_bfe_u32 v254, v252, 6, 1
	v_lshl_or_b32 v253, v253, 2, v253
	v_lshl_or_b32 v253, v254, 4, v253
	v_xor_b32_e32 v253, v253, v252
	v_lshlrev_b32_e32 v253, 3, v253
	v_add_u32_e32 v72, v40, v253
	v_xad_u32 v73, v253, s0, v40
	v_xad_u32 v74, v253, s1, v40
	v_xad_u32 v75, v253, s4, v40
	ds_read_b64 v[64:65], v72
	ds_read_b64 v[66:67], v73
	ds_read_b64 v[68:69], v74
	ds_read_b64 v[70:71], v75
	s_waitcnt lgkmcnt(6)
	v_add_f32_e32 v110, v230, v234
	v_sub_f32_e32 v112, v230, v234
	v_add_f32_e32 v30, v232, v236
	v_sub_f32_e32 v32, v232, v236
	v_add_f32_e32 v111, v231, v235
	v_sub_f32_e32 v113, v231, v235
	v_add_f32_e32 v31, v233, v237
	v_sub_f32_e32 v33, v233, v237
	v_add_f32_e32 v230, v110, v30
	v_add_f32_e32 v231, v111, v31
	v_sub_f32_e32 v232, v110, v30
	v_sub_f32_e32 v233, v111, v31
	v_add_f32_e32 v234, v112, v33
	v_sub_f32_e32 v235, v113, v32
	v_sub_f32_e32 v236, v112, v33
	v_add_f32_e32 v237, v113, v32
	ds_write_b128 v242, v[230:233]
	ds_write_b128 v242, v[234:237] offset:16
	v_mad_u32_u24 v250, s61, 7, v38
	v_lshlrev_b32_e32 v252, 2, v250
	v_lshl_add_u32 v242, v252, 3, v40
	v_bfe_u32 v253, v252, 5, 2
	v_bfe_u32 v254, v252, 6, 1
	v_lshl_or_b32 v253, v253, 2, v253
	v_lshl_or_b32 v253, v254, 4, v253
	v_xor_b32_e32 v253, v253, v252
	v_lshlrev_b32_e32 v253, 3, v253
	v_add_u32_e32 v238, v40, v253
	v_xad_u32 v239, v253, s0, v40
	v_xad_u32 v240, v253, s1, v40
	v_xad_u32 v241, v253, s4, v40
	ds_read_b64 v[230:231], v238
	ds_read_b64 v[232:233], v239
	ds_read_b64 v[234:235], v240
	ds_read_b64 v[236:237], v241
	s_waitcnt lgkmcnt(6)
	v_add_f32_e32 v110, v64, v68
	v_sub_f32_e32 v112, v64, v68
	v_add_f32_e32 v30, v66, v70
	v_sub_f32_e32 v32, v66, v70
	v_add_f32_e32 v111, v65, v69
	v_sub_f32_e32 v113, v65, v69
	v_add_f32_e32 v31, v67, v71
	v_sub_f32_e32 v33, v67, v71
	v_add_f32_e32 v64, v110, v30
	v_add_f32_e32 v65, v111, v31
	v_sub_f32_e32 v66, v110, v30
	v_sub_f32_e32 v67, v111, v31
	v_add_f32_e32 v68, v112, v33
	v_sub_f32_e32 v69, v113, v32
	v_sub_f32_e32 v70, v112, v33
	v_add_f32_e32 v71, v113, v32
	ds_write_b128 v102, v[64:67]
	ds_write_b128 v102, v[68:71] offset:16
	s_waitcnt lgkmcnt(2)
	v_add_f32_e32 v110, v230, v234
	v_sub_f32_e32 v112, v230, v234
	v_add_f32_e32 v30, v232, v236
	v_sub_f32_e32 v32, v232, v236
	v_add_f32_e32 v111, v231, v235
	v_sub_f32_e32 v113, v231, v235
	v_add_f32_e32 v31, v233, v237
	v_sub_f32_e32 v33, v233, v237
	v_add_f32_e32 v230, v110, v30
	v_add_f32_e32 v231, v111, v31
	v_sub_f32_e32 v232, v110, v30
	v_sub_f32_e32 v233, v111, v31
	v_add_f32_e32 v234, v112, v33
	v_sub_f32_e32 v235, v113, v32
	v_sub_f32_e32 v236, v112, v33
	v_add_f32_e32 v237, v113, v32
	ds_write_b128 v242, v[230:233]
	ds_write_b128 v242, v[234:237] offset:16
	s_branch .LBB0_704
.Lffs_f4:
	s_movk_i32 s0, 0x20
	s_movk_i32 s1, 0x40
	s_movk_i32 s4, 0x60
	v_mov_b32_e32 v250, v38
	v_and_b32_e32 v251, 3, v250
	v_sub_u32_e32 v252, v250, v251
	v_lshl_or_b32 v252, v252, 2, v251
	v_cvt_f32_u32_e32 v251, v251
	v_mul_f32_e32 v251, 0x3d800000, v251
	v_cos_f32_e32 v106, v251
	v_sin_f32_e32 v107, v251
	v_bfe_u32 v253, v252, 5, 2
	v_bfe_u32 v254, v252, 6, 1
	v_lshl_or_b32 v253, v253, 2, v253
	v_lshl_or_b32 v253, v254, 4, v253
	v_xor_b32_e32 v253, v253, v252
	v_lshlrev_b32_e32 v253, 3, v253
	v_add_u32_e32 v72, v40, v253
	v_xad_u32 v73, v253, s0, v40
	v_xad_u32 v74, v253, s1, v40
	v_xad_u32 v75, v253, s4, v40
	v_mul_f32_e32 v108, v107, v107
	v_mul_f32_e32 v109, v107, v106
	v_fma_f32 v108, v106, v106, -v108
	v_fma_f32 v109, v106, v107, v109
	ds_read_b64 v[64:65], v72
	ds_read_b64 v[66:67], v73
	ds_read_b64 v[68:69], v74
	ds_read_b64 v[70:71], v75
	v_mad_u32_u24 v250, s61, 1, v38
	v_and_b32_e32 v251, 3, v250
	v_sub_u32_e32 v252, v250, v251
	v_lshl_or_b32 v252, v252, 2, v251
	v_cvt_f32_u32_e32 v251, v251
	v_mul_f32_e32 v251, 0x3d800000, v251
	v_cos_f32_e32 v246, v251
	v_sin_f32_e32 v247, v251
	v_bfe_u32 v253, v252, 5, 2
	v_bfe_u32 v254, v252, 6, 1
	v_lshl_or_b32 v253, v253, 2, v253
	v_lshl_or_b32 v253, v254, 4, v253
	v_xor_b32_e32 v253, v253, v252
	v_lshlrev_b32_e32 v253, 3, v253
	v_add_u32_e32 v238, v40, v253
	v_xad_u32 v239, v253, s0, v40
	v_xad_u32 v240, v253, s1, v40
	v_xad_u32 v241, v253, s4, v40
	v_mul_f32_e32 v248, v247, v247
	v_mul_f32_e32 v249, v247, v246
	v_fma_f32 v248, v246, v246, -v248
	v_fma_f32 v249, v246, v247, v249
	ds_read_b64 v[230:231], v238
	ds_read_b64 v[232:233], v239
	ds_read_b64 v[234:235], v240
	ds_read_b64 v[236:237], v241
	s_waitcnt lgkmcnt(4)
; DI float cos2pi(float x) { return __builtin_amdgcn_cosf(x); }
; DI float sin2pi(float x) { return __builtin_amdgcn_sinf(x); }
; template <bool INV>
; DI void fft_lds(float2* buf_, int L, int logL, int gtid, int NTG) {
;     ...
;       for (int t = gtid; t < (L >> 2); t += NTG) {
;         const int k = t & (S - 1), base = ((t - k) << 2) | k;
;         const v2f a0 = buf[base], a1 = buf[base + S], a2 = buf[base + 2 * S], a3 = buf[base + 3 * S];
;         const float fr = (float)k * i4;
;         const v2f w1 = v2f{cos2pi(fr), sin2pi(fr)};
;         const v2f w2 = vcmul(w1, w1);
;         const v2f x0 = a0 + a2;
;         const v2f x2 = vcmulc(a0 - a2, w1);
;         const v2f x1 = a1 + a3;
;         const v2f d13 = vcmulc(a1 - a3, w1);
;         const v2f x3 = v2f{d13.y, -d13.x};
;         buf[base] = x0 + x1;
;         buf[base + S] = vcmulc(x0 - x1, w2);
;         buf[base + 2 * S] = x2 + x3;
;         buf[base + 3 * S] = vcmulc(x2 - x3, w2);
;       }
	v_add_f32_e32 v110, v64, v68
	v_sub_f32_e32 v112, v64, v68
	v_add_f32_e32 v30, v66, v70
	v_sub_f32_e32 v32, v66, v70
	v_add_f32_e32 v111, v65, v69
	v_sub_f32_e32 v113, v65, v69
	v_add_f32_e32 v31, v67, v71
	v_sub_f32_e32 v33, v67, v71
	v_mul_f32_e32 v251, v112, v106
	v_mul_f32_e32 v252, v112, v107
	v_fma_f32 v47, v113, v107, v251
	v_fma_f32 v250, v113, v106, -v252
	v_mul_f32_e32 v251, v32, v106
	v_mul_f32_e32 v252, v32, v107
	v_fma_f32 v253, v33, v107, v251
	v_fma_f32 v254, v33, v106, -v252
	v_add_f32_e32 v64, v110, v30
	v_add_f32_e32 v65, v111, v31
	v_sub_f32_e32 v110, v110, v30
	v_sub_f32_e32 v111, v111, v31
	v_mul_f32_e32 v251, v110, v108
	v_mul_f32_e32 v252, v110, v109
	v_fma_f32 v66, v111, v109, v251
	v_fma_f32 v67, v111, v108, -v252
	v_add_f32_e32 v68, v47, v254
	v_sub_f32_e32 v69, v250, v253
	v_sub_f32_e32 v30, v47, v254
	v_add_f32_e32 v31, v250, v253
	v_mul_f32_e32 v251, v30, v108
	v_mul_f32_e32 v252, v30, v109
	v_fma_f32 v70, v31, v109, v251
	v_fma_f32 v71, v31, v108, -v252
	ds_write_b64 v72, v[64:65]
	ds_write_b64 v73, v[66:67]
	ds_write_b64 v74, v[68:69]
	ds_write_b64 v75, v[70:71]
	v_mad_u32_u24 v250, s61, 2, v38
	v_and_b32_e32 v251, 3, v250
	v_sub_u32_e32 v252, v250, v251
	v_lshl_or_b32 v252, v252, 2, v251
	v_cvt_f32_u32_e32 v251, v251
	v_mul_f32_e32 v251, 0x3d800000, v251
	v_cos_f32_e32 v106, v251
	v_sin_f32_e32 v107, v251
	v_bfe_u32 v253, v252, 5, 2
	v_bfe_u32 v254, v252, 6, 1
	v_lshl_or_b32 v253, v253, 2, v253
	v_lshl_or_b32 v253, v254, 4, v253
	v_xor_b32_e32 v253, v253, v252
	v_lshlrev_b32_e32 v253, 3, v253
	v_add_u32_e32 v72, v40, v253
	v_xad_u32 v73, v253, s0, v40
	v_xad_u32 v74, v253, s1, v40
	v_xad_u32 v75, v253, s4, v40
	v_mul_f32_e32 v108, v107, v107
	v_mul_f32_e32 v109, v107, v106
	v_fma_f32 v108, v106, v106, -v108
	v_fma_f32 v109, v106, v107, v109
	ds_read_b64 v[64:65], v72
	ds_read_b64 v[66:67], v73
	ds_read_b64 v[68:69], v74
	ds_read_b64 v[70:71], v75
	s_waitcnt lgkmcnt(8)
	v_add_f32_e32 v110, v230, v234
	v_sub_f32_e32 v112, v230, v234
	v_add_f32_e32 v30, v232, v236
	v_sub_f32_e32 v32, v232, v236
	v_add_f32_e32 v111, v231, v235
	v_sub_f32_e32 v113, v231, v235
	v_add_f32_e32 v31, v233, v237
	v_sub_f32_e32 v33, v233, v237
	v_mul_f32_e32 v251, v112, v246
	v_mul_f32_e32 v252, v112, v247
	v_fma_f32 v47, v113, v247, v251
	v_fma_f32 v250, v113, v246, -v252
	v_mul_f32_e32 v251, v32, v246
	v_mul_f32_e32 v252, v32, v247
	v_fma_f32 v253, v33, v247, v251
	v_fma_f32 v254, v33, v246, -v252
	v_add_f32_e32 v230, v110, v30
	v_add_f32_e32 v231, v111, v31
	v_sub_f32_e32 v110, v110, v30
	v_sub_f32_e32 v111, v111, v31
	v_mul_f32_e32 v251, v110, v248
	v_mul_f32_e32 v252, v110, v249
	v_fma_f32 v232, v111, v249, v251
	v_fma_f32 v233, v111, v248, -v252
	v_add_f32_e32 v234, v47, v254
	v_sub_f32_e32 v235, v250, v253
	v_sub_f32_e32 v30, v47, v254
	v_add_f32_e32 v31, v250, v253
	v_mul_f32_e32 v251, v30, v248
	v_mul_f32_e32 v252, v30, v249
	v_fma_f32 v236, v31, v249, v251
	v_fma_f32 v237, v31, v248, -v252
	ds_write_b64 v238, v[230:231]
	ds_write_b64 v239, v[232:233]
	ds_write_b64 v240, v[234:235]
	ds_write_b64 v241, v[236:237]
	v_mad_u32_u24 v250, s61, 3, v38
	v_and_b32_e32 v251, 3, v250
	v_sub_u32_e32 v252, v250, v251
	v_lshl_or_b32 v252, v252, 2, v251
	v_cvt_f32_u32_e32 v251, v251
	v_mul_f32_e32 v251, 0x3d800000, v251
	v_cos_f32_e32 v246, v251
	v_sin_f32_e32 v247, v251
	v_bfe_u32 v253, v252, 5, 2
	v_bfe_u32 v254, v252, 6, 1
	v_lshl_or_b32 v253, v253, 2, v253
	v_lshl_or_b32 v253, v254, 4, v253
	v_xor_b32_e32 v253, v253, v252
	v_lshlrev_b32_e32 v253, 3, v253
	v_add_u32_e32 v238, v40, v253
	v_xad_u32 v239, v253, s0, v40
	v_xad_u32 v240, v253, s1, v40
	v_xad_u32 v241, v253, s4, v40
	v_mul_f32_e32 v248, v247, v247
	v_mul_f32_e32 v249, v247, v246
	v_fma_f32 v248, v246, v246, -v248
	v_fma_f32 v249, v246, v247, v249
	ds_read_b64 v[230:231], v238
	ds_read_b64 v[232:233], v239
	ds_read_b64 v[234:235], v240
	ds_read_b64 v[236:237], v241
	s_waitcnt lgkmcnt(8)
	v_add_f32_e32 v110, v64, v68
	v_sub_f32_e32 v112, v64, v68
	v_add_f32_e32 v30, v66, v70
	v_sub_f32_e32 v32, v66, v70
	v_add_f32_e32 v111, v65, v69
	v_sub_f32_e32 v113, v65, v69
	v_add_f32_e32 v31, v67, v71
	v_sub_f32_e32 v33, v67, v71
	v_mul_f32_e32 v251, v112, v106
	v_mul_f32_e32 v252, v112, v107
	v_fma_f32 v47, v113, v107, v251
	v_fma_f32 v250, v113, v106, -v252
	v_mul_f32_e32 v251, v32, v106
	v_mul_f32_e32 v252, v32, v107
	v_fma_f32 v253, v33, v107, v251
	v_fma_f32 v254, v33, v106, -v252
	v_add_f32_e32 v64, v110, v30
	v_add_f32_e32 v65, v111, v31
	v_sub_f32_e32 v110, v110, v30
	v_sub_f32_e32 v111, v111, v31
	v_mul_f32_e32 v251, v110, v108
	v_mul_f32_e32 v252, v110, v109
	v_fma_f32 v66, v111, v109, v251
	v_fma_f32 v67, v111, v108, -v252
	v_add_f32_e32 v68, v47, v254
	v_sub_f32_e32 v69, v250, v253
	v_sub_f32_e32 v30, v47, v254
	v_add_f32_e32 v31, v250, v253
	v_mul_f32_e32 v251, v30, v108
	v_mul_f32_e32 v252, v30, v109
	v_fma_f32 v70, v31, v109, v251
	v_fma_f32 v71, v31, v108, -v252
	ds_write_b64 v72, v[64:65]
	ds_write_b64 v73, v[66:67]
	ds_write_b64 v74, v[68:69]
	ds_write_b64 v75, v[70:71]
	v_mad_u32_u24 v250, s61, 4, v38
	v_and_b32_e32 v251, 3, v250
	v_sub_u32_e32 v252, v250, v251
	v_lshl_or_b32 v252, v252, 2, v251
	v_cvt_f32_u32_e32 v251, v251
	v_mul_f32_e32 v251, 0x3d800000, v251
	v_cos_f32_e32 v106, v251
	v_sin_f32_e32 v107, v251
	v_bfe_u32 v253, v252, 5, 2
	v_bfe_u32 v254, v252, 6, 1
	v_lshl_or_b32 v253, v253, 2, v253
	v_lshl_or_b32 v253, v254, 4, v253
	v_xor_b32_e32 v253, v253, v252
	v_lshlrev_b32_e32 v253, 3, v253
	v_add_u32_e32 v72, v40, v253
	v_xad_u32 v73, v253, s0, v40
	v_xad_u32 v74, v253, s1, v40
	v_xad_u32 v75, v253, s4, v40
	v_mul_f32_e32 v108, v107, v107
	v_mul_f32_e32 v109, v107, v106
	v_fma_f32 v108, v106, v106, -v108
	v_fma_f32 v109, v106, v107, v109
	ds_read_b64 v[64:65], v72
	ds_read_b64 v[66:67], v73
	ds_read_b64 v[68:69], v74
	ds_read_b64 v[70:71], v75
	s_waitcnt lgkmcnt(8)
; DI float cos2pi(float x) { return __builtin_amdgcn_cosf(x); }
; DI float sin2pi(float x) { return __builtin_amdgcn_sinf(x); }
; template <bool INV>
; DI void fft_lds(float2* buf_, int L, int logL, int gtid, int NTG) {
;     ...
;       for (int t = gtid; t < (L >> 2); t += NTG) {
;         const int k = t & (S - 1), base = ((t - k) << 2) | k;
;         const v2f a0 = buf[base], a1 = buf[base + S], a2 = buf[base + 2 * S], a3 = buf[base + 3 * S];
;         const float fr = (float)k * i4;
;         const v2f w1 = v2f{cos2pi(fr), sin2pi(fr)};
;         const v2f w2 = vcmul(w1, w1);
;         const v2f x0 = a0 + a2;
;         const v2f x2 = vcmulc(a0 - a2, w1);
;         const v2f x1 = a1 + a3;
;         const v2f d13 = vcmulc(a1 - a3, w1);
;         const v2f x3 = v2f{d13.y, -d13.x};
;         buf[base] = x0 + x1;
;         buf[base + S] = vcmulc(x0 - x1, w2);
;         buf[base + 2 * S] = x2 + x3;
;         buf[base + 3 * S] = vcmulc(x2 - x3, w2);
;       }
	v_add_f32_e32 v110, v230, v234
	v_sub_f32_e32 v112, v230, v234
	v_add_f32_e32 v30, v232, v236
	v_sub_f32_e32 v32, v232, v236
	v_add_f32_e32 v111, v231, v235
	v_sub_f32_e32 v113, v231, v235
	v_add_f32_e32 v31, v233, v237
	v_sub_f32_e32 v33, v233, v237
	v_mul_f32_e32 v251, v112, v246
	v_mul_f32_e32 v252, v112, v247
	v_fma_f32 v47, v113, v247, v251
	v_fma_f32 v250, v113, v246, -v252
	v_mul_f32_e32 v251, v32, v246
	v_mul_f32_e32 v252, v32, v247
	v_fma_f32 v253, v33, v247, v251
	v_fma_f32 v254, v33, v246, -v252
	v_add_f32_e32 v230, v110, v30
	v_add_f32_e32 v231, v111, v31
	v_sub_f32_e32 v110, v110, v30
	v_sub_f32_e32 v111, v111, v31
	v_mul_f32_e32 v251, v110, v248
	v_mul_f32_e32 v252, v110, v249
	v_fma_f32 v232, v111, v249, v251
	v_fma_f32 v233, v111, v248, -v252
	v_add_f32_e32 v234, v47, v254
	v_sub_f32_e32 v235, v250, v253
	v_sub_f32_e32 v30, v47, v254
	v_add_f32_e32 v31, v250, v253
	v_mul_f32_e32 v251, v30, v248
	v_mul_f32_e32 v252, v30, v249
	v_fma_f32 v236, v31, v249, v251
	v_fma_f32 v237, v31, v248, -v252
	ds_write_b64 v238, v[230:231]
	ds_write_b64 v239, v[232:233]
	ds_write_b64 v240, v[234:235]
	ds_write_b64 v241, v[236:237]
	v_mad_u32_u24 v250, s61, 5, v38
	v_and_b32_e32 v251, 3, v250
	v_sub_u32_e32 v252, v250, v251
	v_lshl_or_b32 v252, v252, 2, v251
	v_cvt_f32_u32_e32 v251, v251
	v_mul_f32_e32 v251, 0x3d800000, v251
	v_cos_f32_e32 v246, v251
	v_sin_f32_e32 v247, v251
	v_bfe_u32 v253, v252, 5, 2
	v_bfe_u32 v254, v252, 6, 1
	v_lshl_or_b32 v253, v253, 2, v253
	v_lshl_or_b32 v253, v254, 4, v253
	v_xor_b32_e32 v253, v253, v252
	v_lshlrev_b32_e32 v253, 3, v253
	v_add_u32_e32 v238, v40, v253
	v_xad_u32 v239, v253, s0, v40
	v_xad_u32 v240, v253, s1, v40
	v_xad_u32 v241, v253, s4, v40
	v_mul_f32_e32 v248, v247, v247
	v_mul_f32_e32 v249, v247, v246
	v_fma_f32 v248, v246, v246, -v248
	v_fma_f32 v249, v246, v247, v249
	ds_read_b64 v[230:231], v238
	ds_read_b64 v[232:233], v239
	ds_read_b64 v[234:235], v240
	ds_read_b64 v[236:237], v241
	s_waitcnt lgkmcnt(8)
	v_add_f32_e32 v110, v64, v68
	v_sub_f32_e32 v112, v64, v68
	v_add_f32_e32 v30, v66, v70
	v_sub_f32_e32 v32, v66, v70
	v_add_f32_e32 v111, v65, v69
	v_sub_f32_e32 v113, v65, v69
	v_add_f32_e32 v31, v67, v71
	v_sub_f32_e32 v33, v67, v71
	v_mul_f32_e32 v251, v112, v106
	v_mul_f32_e32 v252, v112, v107
	v_fma_f32 v47, v113, v107, v251
	v_fma_f32 v250, v113, v106, -v252
	v_mul_f32_e32 v251, v32, v106
	v_mul_f32_e32 v252, v32, v107
	v_fma_f32 v253, v33, v107, v251
	v_fma_f32 v254, v33, v106, -v252
	v_add_f32_e32 v64, v110, v30
	v_add_f32_e32 v65, v111, v31
	v_sub_f32_e32 v110, v110, v30
	v_sub_f32_e32 v111, v111, v31
	v_mul_f32_e32 v251, v110, v108
	v_mul_f32_e32 v252, v110, v109
	v_fma_f32 v66, v111, v109, v251
	v_fma_f32 v67, v111, v108, -v252
	v_add_f32_e32 v68, v47, v254
	v_sub_f32_e32 v69, v250, v253
	v_sub_f32_e32 v30, v47, v254
	v_add_f32_e32 v31, v250, v253
	v_mul_f32_e32 v251, v30, v108
	v_mul_f32_e32 v252, v30, v109
	v_fma_f32 v70, v31, v109, v251
	v_fma_f32 v71, v31, v108, -v252
	ds_write_b64 v72, v[64:65]
	ds_write_b64 v73, v[66:67]
	ds_write_b64 v74, v[68:69]
	ds_write_b64 v75, v[70:71]
	v_mad_u32_u24 v250, s61, 6, v38
	v_and_b32_e32 v251, 3, v250
	v_sub_u32_e32 v252, v250, v251
	v_lshl_or_b32 v252, v252, 2, v251
	v_cvt_f32_u32_e32 v251, v251
	v_mul_f32_e32 v251, 0x3d800000, v251
	v_cos_f32_e32 v106, v251
	v_sin_f32_e32 v107, v251
	v_bfe_u32 v253, v252, 5, 2
	v_bfe_u32 v254, v252, 6, 1
	v_lshl_or_b32 v253, v253, 2, v253
	v_lshl_or_b32 v253, v254, 4, v253
	v_xor_b32_e32 v253, v253, v252
	v_lshlrev_b32_e32 v253, 3, v253
	v_add_u32_e32 v72, v40, v253
	v_xad_u32 v73, v253, s0, v40
	v_xad_u32 v74, v253, s1, v40
	v_xad_u32 v75, v253, s4, v40
	v_mul_f32_e32 v108, v107, v107
	v_mul_f32_e32 v109, v107, v106
	v_fma_f32 v108, v106, v106, -v108
	v_fma_f32 v109, v106, v107, v109
	ds_read_b64 v[64:65], v72
	ds_read_b64 v[66:67], v73
	ds_read_b64 v[68:69], v74
	ds_read_b64 v[70:71], v75
	s_waitcnt lgkmcnt(8)
	v_add_f32_e32 v110, v230, v234
	v_sub_f32_e32 v112, v230, v234
	v_add_f32_e32 v30, v232, v236
	v_sub_f32_e32 v32, v232, v236
	v_add_f32_e32 v111, v231, v235
	v_sub_f32_e32 v113, v231, v235
	v_add_f32_e32 v31, v233, v237
	v_sub_f32_e32 v33, v233, v237
	v_mul_f32_e32 v251, v112, v246
	v_mul_f32_e32 v252, v112, v247
	v_fma_f32 v47, v113, v247, v251
	v_fma_f32 v250, v113, v246, -v252
	v_mul_f32_e32 v251, v32, v246
	v_mul_f32_e32 v252, v32, v247
	v_fma_f32 v253, v33, v247, v251
	v_fma_f32 v254, v33, v246, -v252
	v_add_f32_e32 v230, v110, v30
	v_add_f32_e32 v231, v111, v31
	v_sub_f32_e32 v110, v110, v30
	v_sub_f32_e32 v111, v111, v31
	v_mul_f32_e32 v251, v110, v248
	v_mul_f32_e32 v252, v110, v249
	v_fma_f32 v232, v111, v249, v251
	v_fma_f32 v233, v111, v248, -v252
	v_add_f32_e32 v234, v47, v254
	v_sub_f32_e32 v235, v250, v253
	v_sub_f32_e32 v30, v47, v254
	v_add_f32_e32 v31, v250, v253
	v_mul_f32_e32 v251, v30, v248
	v_mul_f32_e32 v252, v30, v249
	v_fma_f32 v236, v31, v249, v251
	v_fma_f32 v237, v31, v248, -v252
	ds_write_b64 v238, v[230:231]
	ds_write_b64 v239, v[232:233]
	ds_write_b64 v240, v[234:235]
	ds_write_b64 v241, v[236:237]
	v_mad_u32_u24 v250, s61, 7, v38
	v_and_b32_e32 v251, 3, v250
	v_sub_u32_e32 v252, v250, v251
	v_lshl_or_b32 v252, v252, 2, v251
	v_cvt_f32_u32_e32 v251, v251
	v_mul_f32_e32 v251, 0x3d800000, v251
	v_cos_f32_e32 v246, v251
	v_sin_f32_e32 v247, v251
	v_bfe_u32 v253, v252, 5, 2
	v_bfe_u32 v254, v252, 6, 1
	v_lshl_or_b32 v253, v253, 2, v253
	v_lshl_or_b32 v253, v254, 4, v253
	v_xor_b32_e32 v253, v253, v252
	v_lshlrev_b32_e32 v253, 3, v253
	v_add_u32_e32 v238, v40, v253
	v_xad_u32 v239, v253, s0, v40
	v_xad_u32 v240, v253, s1, v40
	v_xad_u32 v241, v253, s4, v40
	v_mul_f32_e32 v248, v247, v247
	v_mul_f32_e32 v249, v247, v246
	v_fma_f32 v248, v246, v246, -v248
	v_fma_f32 v249, v246, v247, v249
	ds_read_b64 v[230:231], v238
	ds_read_b64 v[232:233], v239
	ds_read_b64 v[234:235], v240
	ds_read_b64 v[236:237], v241
	s_waitcnt lgkmcnt(8)
; DI float cos2pi(float x) { return __builtin_amdgcn_cosf(x); }
; DI float sin2pi(float x) { return __builtin_amdgcn_sinf(x); }
; template <bool INV>
; DI void fft_lds(float2* buf_, int L, int logL, int gtid, int NTG) {
;     ...
;       for (int t = gtid; t < (L >> 2); t += NTG) {
;         const int k = t & (S - 1), base = ((t - k) << 2) | k;
;         const v2f a0 = buf[base], a1 = buf[base + S], a2 = buf[base + 2 * S], a3 = buf[base + 3 * S];
;         const float fr = (float)k * i4;
;         const v2f w1 = v2f{cos2pi(fr), sin2pi(fr)};
;         const v2f w2 = vcmul(w1, w1);
;         const v2f x0 = a0 + a2;
;         const v2f x2 = vcmulc(a0 - a2, w1);
;         const v2f x1 = a1 + a3;
;         const v2f d13 = vcmulc(a1 - a3, w1);
;         const v2f x3 = v2f{d13.y, -d13.x};
;         buf[base] = x0 + x1;
;         buf[base + S] = vcmulc(x0 - x1, w2);
;         buf[base + 2 * S] = x2 + x3;
;         buf[base + 3 * S] = vcmulc(x2 - x3, w2);
;       }
	v_add_f32_e32 v110, v64, v68
	v_sub_f32_e32 v112, v64, v68
	v_add_f32_e32 v30, v66, v70
	v_sub_f32_e32 v32, v66, v70
	v_add_f32_e32 v111, v65, v69
	v_sub_f32_e32 v113, v65, v69
	v_add_f32_e32 v31, v67, v71
	v_sub_f32_e32 v33, v67, v71
	v_mul_f32_e32 v251, v112, v106
	v_mul_f32_e32 v252, v112, v107
	v_fma_f32 v47, v113, v107, v251
	v_fma_f32 v250, v113, v106, -v252
	v_mul_f32_e32 v251, v32, v106
	v_mul_f32_e32 v252, v32, v107
	v_fma_f32 v253, v33, v107, v251
	v_fma_f32 v254, v33, v106, -v252
	v_add_f32_e32 v64, v110, v30
	v_add_f32_e32 v65, v111, v31
	v_sub_f32_e32 v110, v110, v30
	v_sub_f32_e32 v111, v111, v31
	v_mul_f32_e32 v251, v110, v108
	v_mul_f32_e32 v252, v110, v109
	v_fma_f32 v66, v111, v109, v251
	v_fma_f32 v67, v111, v108, -v252
	v_add_f32_e32 v68, v47, v254
	v_sub_f32_e32 v69, v250, v253
	v_sub_f32_e32 v30, v47, v254
	v_add_f32_e32 v31, v250, v253
	v_mul_f32_e32 v251, v30, v108
	v_mul_f32_e32 v252, v30, v109
	v_fma_f32 v70, v31, v109, v251
	v_fma_f32 v71, v31, v108, -v252
	ds_write_b64 v72, v[64:65]
	ds_write_b64 v73, v[66:67]
	ds_write_b64 v74, v[68:69]
	ds_write_b64 v75, v[70:71]
	s_waitcnt lgkmcnt(4)
	v_add_f32_e32 v110, v230, v234
	v_sub_f32_e32 v112, v230, v234
	v_add_f32_e32 v30, v232, v236
	v_sub_f32_e32 v32, v232, v236
	v_add_f32_e32 v111, v231, v235
	v_sub_f32_e32 v113, v231, v235
	v_add_f32_e32 v31, v233, v237
	v_sub_f32_e32 v33, v233, v237
	v_mul_f32_e32 v251, v112, v246
	v_mul_f32_e32 v252, v112, v247
	v_fma_f32 v47, v113, v247, v251
	v_fma_f32 v250, v113, v246, -v252
	v_mul_f32_e32 v251, v32, v246
	v_mul_f32_e32 v252, v32, v247
	v_fma_f32 v253, v33, v247, v251
	v_fma_f32 v254, v33, v246, -v252
	v_add_f32_e32 v230, v110, v30
	v_add_f32_e32 v231, v111, v31
	v_sub_f32_e32 v110, v110, v30
	v_sub_f32_e32 v111, v111, v31
	v_mul_f32_e32 v251, v110, v248
	v_mul_f32_e32 v252, v110, v249
	v_fma_f32 v232, v111, v249, v251
	v_fma_f32 v233, v111, v248, -v252
	v_add_f32_e32 v234, v47, v254
	v_sub_f32_e32 v235, v250, v253
	v_sub_f32_e32 v30, v47, v254
	v_add_f32_e32 v31, v250, v253
	v_mul_f32_e32 v251, v30, v248
	v_mul_f32_e32 v252, v30, v249
	v_fma_f32 v236, v31, v249, v251
	v_fma_f32 v237, v31, v248, -v252
	ds_write_b64 v238, v[230:231]
	ds_write_b64 v239, v[232:233]
	ds_write_b64 v240, v[234:235]
	ds_write_b64 v241, v[236:237]
	s_branch .LBB0_704
.Lffs_f16:
	s_movk_i32 s0, 0x80
	s_movk_i32 s1, 0x128
	s_movk_i32 s4, 0x1a8
	v_mov_b32_e32 v250, v38
	v_and_b32_e32 v251, 15, v250
	v_sub_u32_e32 v252, v250, v251
	v_lshl_or_b32 v252, v252, 2, v251
	v_cvt_f32_u32_e32 v251, v251
	v_mul_f32_e32 v251, 0x3c800000, v251
	v_cos_f32_e32 v106, v251
	v_sin_f32_e32 v107, v251
	v_lshl_add_u32 v72, v252, 3, v40
	v_add_u32_e32 v73, 0x80, v72
	v_add_u32_e32 v74, 0x100, v72
	v_add_u32_e32 v75, 0x180, v72
	v_bfe_u32 v253, v252, 5, 2
	v_bfe_u32 v254, v252, 6, 1
	v_lshl_or_b32 v253, v253, 2, v253
	v_lshl_or_b32 v253, v254, 4, v253
	v_xor_b32_e32 v253, v253, v252
	v_lshlrev_b32_e32 v253, 3, v253
	v_add_u32_e32 v102, v40, v253
	v_xad_u32 v103, v253, s0, v40
	v_xad_u32 v104, v253, s1, v40
	v_xad_u32 v105, v253, s4, v40
	v_mul_f32_e32 v108, v107, v107
	v_mul_f32_e32 v109, v107, v106
	v_fma_f32 v108, v106, v106, -v108
	v_fma_f32 v109, v106, v107, v109
	ds_read_b64 v[64:65], v72
	ds_read_b64 v[66:67], v73
	ds_read_b64 v[68:69], v74
	ds_read_b64 v[70:71], v75
	v_mad_u32_u24 v250, s61, 1, v38
	v_and_b32_e32 v251, 15, v250
	v_sub_u32_e32 v252, v250, v251
	v_lshl_or_b32 v252, v252, 2, v251
	v_cvt_f32_u32_e32 v251, v251
	v_mul_f32_e32 v251, 0x3c800000, v251
	v_cos_f32_e32 v246, v251
	v_sin_f32_e32 v247, v251
	v_lshl_add_u32 v238, v252, 3, v40
	v_add_u32_e32 v239, 0x80, v238
	v_add_u32_e32 v240, 0x100, v238
	v_add_u32_e32 v241, 0x180, v238
	v_bfe_u32 v253, v252, 5, 2
	v_bfe_u32 v254, v252, 6, 1
	v_lshl_or_b32 v253, v253, 2, v253
	v_lshl_or_b32 v253, v254, 4, v253
	v_xor_b32_e32 v253, v253, v252
	v_lshlrev_b32_e32 v253, 3, v253
	v_add_u32_e32 v242, v40, v253
	v_xad_u32 v243, v253, s0, v40
	v_xad_u32 v244, v253, s1, v40
	v_xad_u32 v245, v253, s4, v40
	v_mul_f32_e32 v248, v247, v247
	v_mul_f32_e32 v249, v247, v246
	v_fma_f32 v248, v246, v246, -v248
	v_fma_f32 v249, v246, v247, v249
	ds_read_b64 v[230:231], v238
	ds_read_b64 v[232:233], v239
	ds_read_b64 v[234:235], v240
	ds_read_b64 v[236:237], v241
	s_waitcnt lgkmcnt(4)
	v_add_f32_e32 v110, v64, v68
	v_sub_f32_e32 v112, v64, v68
	v_add_f32_e32 v30, v66, v70
	v_sub_f32_e32 v32, v66, v70
	v_add_f32_e32 v111, v65, v69
	v_sub_f32_e32 v113, v65, v69
	v_add_f32_e32 v31, v67, v71
	v_sub_f32_e32 v33, v67, v71
	v_mul_f32_e32 v251, v112, v106
	v_mul_f32_e32 v252, v112, v107
	v_fma_f32 v47, v113, v107, v251
	v_fma_f32 v250, v113, v106, -v252
	v_mul_f32_e32 v251, v32, v106
	v_mul_f32_e32 v252, v32, v107
	v_fma_f32 v253, v33, v107, v251
	v_fma_f32 v254, v33, v106, -v252
	v_add_f32_e32 v64, v110, v30
	v_add_f32_e32 v65, v111, v31
	v_sub_f32_e32 v110, v110, v30
	v_sub_f32_e32 v111, v111, v31
	v_mul_f32_e32 v251, v110, v108
	v_mul_f32_e32 v252, v110, v109
	v_fma_f32 v66, v111, v109, v251
	v_fma_f32 v67, v111, v108, -v252
	v_add_f32_e32 v68, v47, v254
	v_sub_f32_e32 v69, v250, v253
	v_sub_f32_e32 v30, v47, v254
	v_add_f32_e32 v31, v250, v253
	v_mul_f32_e32 v251, v30, v108
	v_mul_f32_e32 v252, v30, v109
	v_fma_f32 v70, v31, v109, v251
	v_fma_f32 v71, v31, v108, -v252
	ds_write_b64 v102, v[64:65]
	ds_write_b64 v103, v[66:67]
	ds_write_b64 v104, v[68:69]
	ds_write_b64 v105, v[70:71]
	v_mad_u32_u24 v250, s61, 2, v38
	v_and_b32_e32 v251, 15, v250
	v_sub_u32_e32 v252, v250, v251
	v_lshl_or_b32 v252, v252, 2, v251
	v_cvt_f32_u32_e32 v251, v251
	v_mul_f32_e32 v251, 0x3c800000, v251
	v_cos_f32_e32 v106, v251
	v_sin_f32_e32 v107, v251
	v_lshl_add_u32 v72, v252, 3, v40
	v_add_u32_e32 v73, 0x80, v72
	v_add_u32_e32 v74, 0x100, v72
	v_add_u32_e32 v75, 0x180, v72
	v_bfe_u32 v253, v252, 5, 2
	v_bfe_u32 v254, v252, 6, 1
	v_lshl_or_b32 v253, v253, 2, v253
	v_lshl_or_b32 v253, v254, 4, v253
	v_xor_b32_e32 v253, v253, v252
	v_lshlrev_b32_e32 v253, 3, v253
	v_add_u32_e32 v102, v40, v253
	v_xad_u32 v103, v253, s0, v40
	v_xad_u32 v104, v253, s1, v40
	v_xad_u32 v105, v253, s4, v40
	v_mul_f32_e32 v108, v107, v107
	v_mul_f32_e32 v109, v107, v106
	v_fma_f32 v108, v106, v106, -v108
	v_fma_f32 v109, v106, v107, v109
	ds_read_b64 v[64:65], v72
	ds_read_b64 v[66:67], v73
	ds_read_b64 v[68:69], v74
	ds_read_b64 v[70:71], v75
	s_waitcnt lgkmcnt(8)
; DI float cos2pi(float x) { return __builtin_amdgcn_cosf(x); }
; DI float sin2pi(float x) { return __builtin_amdgcn_sinf(x); }
; template <bool INV>
; DI void fft_lds(float2* buf_, int L, int logL, int gtid, int NTG) {
;     ...
;       for (int t = gtid; t < (L >> 2); t += NTG) {
;         const int k = t & (S - 1), base = ((t - k) << 2) | k;
;         const v2f a0 = buf[base], a1 = buf[base + S], a2 = buf[base + 2 * S], a3 = buf[base + 3 * S];
;         const float fr = (float)k * i4;
;         const v2f w1 = v2f{cos2pi(fr), sin2pi(fr)};
;         const v2f w2 = vcmul(w1, w1);
;         const v2f x0 = a0 + a2;
;         const v2f x2 = vcmulc(a0 - a2, w1);
;         const v2f x1 = a1 + a3;
;         const v2f d13 = vcmulc(a1 - a3, w1);
;         const v2f x3 = v2f{d13.y, -d13.x};
;         buf[base] = x0 + x1;
;         buf[base + S] = vcmulc(x0 - x1, w2);
;         buf[base + 2 * S] = x2 + x3;
;         buf[base + 3 * S] = vcmulc(x2 - x3, w2);
;       }
	v_add_f32_e32 v110, v230, v234
	v_sub_f32_e32 v112, v230, v234
	v_add_f32_e32 v30, v232, v236
	v_sub_f32_e32 v32, v232, v236
	v_add_f32_e32 v111, v231, v235
	v_sub_f32_e32 v113, v231, v235
	v_add_f32_e32 v31, v233, v237
	v_sub_f32_e32 v33, v233, v237
	v_mul_f32_e32 v251, v112, v246
	v_mul_f32_e32 v252, v112, v247
	v_fma_f32 v47, v113, v247, v251
	v_fma_f32 v250, v113, v246, -v252
	v_mul_f32_e32 v251, v32, v246
	v_mul_f32_e32 v252, v32, v247
	v_fma_f32 v253, v33, v247, v251
	v_fma_f32 v254, v33, v246, -v252
	v_add_f32_e32 v230, v110, v30
	v_add_f32_e32 v231, v111, v31
	v_sub_f32_e32 v110, v110, v30
	v_sub_f32_e32 v111, v111, v31
	v_mul_f32_e32 v251, v110, v248
	v_mul_f32_e32 v252, v110, v249
	v_fma_f32 v232, v111, v249, v251
	v_fma_f32 v233, v111, v248, -v252
	v_add_f32_e32 v234, v47, v254
	v_sub_f32_e32 v235, v250, v253
	v_sub_f32_e32 v30, v47, v254
	v_add_f32_e32 v31, v250, v253
	v_mul_f32_e32 v251, v30, v248
	v_mul_f32_e32 v252, v30, v249
	v_fma_f32 v236, v31, v249, v251
	v_fma_f32 v237, v31, v248, -v252
	ds_write_b64 v242, v[230:231]
	ds_write_b64 v243, v[232:233]
	ds_write_b64 v244, v[234:235]
	ds_write_b64 v245, v[236:237]
	v_mad_u32_u24 v250, s61, 3, v38
	v_and_b32_e32 v251, 15, v250
	v_sub_u32_e32 v252, v250, v251
	v_lshl_or_b32 v252, v252, 2, v251
	v_cvt_f32_u32_e32 v251, v251
	v_mul_f32_e32 v251, 0x3c800000, v251
	v_cos_f32_e32 v246, v251
	v_sin_f32_e32 v247, v251
	v_lshl_add_u32 v238, v252, 3, v40
	v_add_u32_e32 v239, 0x80, v238
	v_add_u32_e32 v240, 0x100, v238
	v_add_u32_e32 v241, 0x180, v238
	v_bfe_u32 v253, v252, 5, 2
	v_bfe_u32 v254, v252, 6, 1
	v_lshl_or_b32 v253, v253, 2, v253
	v_lshl_or_b32 v253, v254, 4, v253
	v_xor_b32_e32 v253, v253, v252
	v_lshlrev_b32_e32 v253, 3, v253
	v_add_u32_e32 v242, v40, v253
	v_xad_u32 v243, v253, s0, v40
	v_xad_u32 v244, v253, s1, v40
	v_xad_u32 v245, v253, s4, v40
	v_mul_f32_e32 v248, v247, v247
	v_mul_f32_e32 v249, v247, v246
	v_fma_f32 v248, v246, v246, -v248
	v_fma_f32 v249, v246, v247, v249
	ds_read_b64 v[230:231], v238
	ds_read_b64 v[232:233], v239
	ds_read_b64 v[234:235], v240
	ds_read_b64 v[236:237], v241
	s_waitcnt lgkmcnt(8)
	v_add_f32_e32 v110, v64, v68
	v_sub_f32_e32 v112, v64, v68
	v_add_f32_e32 v30, v66, v70
	v_sub_f32_e32 v32, v66, v70
	v_add_f32_e32 v111, v65, v69
	v_sub_f32_e32 v113, v65, v69
	v_add_f32_e32 v31, v67, v71
	v_sub_f32_e32 v33, v67, v71
	v_mul_f32_e32 v251, v112, v106
	v_mul_f32_e32 v252, v112, v107
	v_fma_f32 v47, v113, v107, v251
	v_fma_f32 v250, v113, v106, -v252
	v_mul_f32_e32 v251, v32, v106
	v_mul_f32_e32 v252, v32, v107
	v_fma_f32 v253, v33, v107, v251
	v_fma_f32 v254, v33, v106, -v252
	v_add_f32_e32 v64, v110, v30
	v_add_f32_e32 v65, v111, v31
	v_sub_f32_e32 v110, v110, v30
	v_sub_f32_e32 v111, v111, v31
	v_mul_f32_e32 v251, v110, v108
	v_mul_f32_e32 v252, v110, v109
	v_fma_f32 v66, v111, v109, v251
	v_fma_f32 v67, v111, v108, -v252
	v_add_f32_e32 v68, v47, v254
	v_sub_f32_e32 v69, v250, v253
	v_sub_f32_e32 v30, v47, v254
	v_add_f32_e32 v31, v250, v253
	v_mul_f32_e32 v251, v30, v108
	v_mul_f32_e32 v252, v30, v109
	v_fma_f32 v70, v31, v109, v251
	v_fma_f32 v71, v31, v108, -v252
	ds_write_b64 v102, v[64:65]
	ds_write_b64 v103, v[66:67]
	ds_write_b64 v104, v[68:69]
	ds_write_b64 v105, v[70:71]
	v_mad_u32_u24 v250, s61, 4, v38
	v_and_b32_e32 v251, 15, v250
	v_sub_u32_e32 v252, v250, v251
	v_lshl_or_b32 v252, v252, 2, v251
	v_cvt_f32_u32_e32 v251, v251
	v_mul_f32_e32 v251, 0x3c800000, v251
	v_cos_f32_e32 v106, v251
	v_sin_f32_e32 v107, v251
	v_lshl_add_u32 v72, v252, 3, v40
	v_add_u32_e32 v73, 0x80, v72
	v_add_u32_e32 v74, 0x100, v72
	v_add_u32_e32 v75, 0x180, v72
	v_bfe_u32 v253, v252, 5, 2
	v_bfe_u32 v254, v252, 6, 1
	v_lshl_or_b32 v253, v253, 2, v253
	v_lshl_or_b32 v253, v254, 4, v253
	v_xor_b32_e32 v253, v253, v252
	v_lshlrev_b32_e32 v253, 3, v253
	v_add_u32_e32 v102, v40, v253
	v_xad_u32 v103, v253, s0, v40
	v_xad_u32 v104, v253, s1, v40
	v_xad_u32 v105, v253, s4, v40
	v_mul_f32_e32 v108, v107, v107
	v_mul_f32_e32 v109, v107, v106
	v_fma_f32 v108, v106, v106, -v108
	v_fma_f32 v109, v106, v107, v109
	ds_read_b64 v[64:65], v72
	ds_read_b64 v[66:67], v73
	ds_read_b64 v[68:69], v74
	ds_read_b64 v[70:71], v75
	s_waitcnt lgkmcnt(8)
	v_add_f32_e32 v110, v230, v234
	v_sub_f32_e32 v112, v230, v234
	v_add_f32_e32 v30, v232, v236
	v_sub_f32_e32 v32, v232, v236
	v_add_f32_e32 v111, v231, v235
	v_sub_f32_e32 v113, v231, v235
	v_add_f32_e32 v31, v233, v237
	v_sub_f32_e32 v33, v233, v237
	v_mul_f32_e32 v251, v112, v246
	v_mul_f32_e32 v252, v112, v247
	v_fma_f32 v47, v113, v247, v251
	v_fma_f32 v250, v113, v246, -v252
	v_mul_f32_e32 v251, v32, v246
	v_mul_f32_e32 v252, v32, v247
	v_fma_f32 v253, v33, v247, v251
	v_fma_f32 v254, v33, v246, -v252
	v_add_f32_e32 v230, v110, v30
	v_add_f32_e32 v231, v111, v31
	v_sub_f32_e32 v110, v110, v30
	v_sub_f32_e32 v111, v111, v31
	v_mul_f32_e32 v251, v110, v248
	v_mul_f32_e32 v252, v110, v249
	v_fma_f32 v232, v111, v249, v251
	v_fma_f32 v233, v111, v248, -v252
	v_add_f32_e32 v234, v47, v254
	v_sub_f32_e32 v235, v250, v253
	v_sub_f32_e32 v30, v47, v254
	v_add_f32_e32 v31, v250, v253
	v_mul_f32_e32 v251, v30, v248
	v_mul_f32_e32 v252, v30, v249
	v_fma_f32 v236, v31, v249, v251
	v_fma_f32 v237, v31, v248, -v252
	ds_write_b64 v242, v[230:231]
	ds_write_b64 v243, v[232:233]
	ds_write_b64 v244, v[234:235]
	ds_write_b64 v245, v[236:237]
	v_mad_u32_u24 v250, s61, 5, v38
	v_and_b32_e32 v251, 15, v250
	v_sub_u32_e32 v252, v250, v251
	v_lshl_or_b32 v252, v252, 2, v251
	v_cvt_f32_u32_e32 v251, v251
	v_mul_f32_e32 v251, 0x3c800000, v251
	v_cos_f32_e32 v246, v251
	v_sin_f32_e32 v247, v251
	v_lshl_add_u32 v238, v252, 3, v40
	v_add_u32_e32 v239, 0x80, v238
	v_add_u32_e32 v240, 0x100, v238
	v_add_u32_e32 v241, 0x180, v238
	v_bfe_u32 v253, v252, 5, 2
	v_bfe_u32 v254, v252, 6, 1
	v_lshl_or_b32 v253, v253, 2, v253
	v_lshl_or_b32 v253, v254, 4, v253
	v_xor_b32_e32 v253, v253, v252
	v_lshlrev_b32_e32 v253, 3, v253
	v_add_u32_e32 v242, v40, v253
	v_xad_u32 v243, v253, s0, v40
	v_xad_u32 v244, v253, s1, v40
	v_xad_u32 v245, v253, s4, v40
	v_mul_f32_e32 v248, v247, v247
	v_mul_f32_e32 v249, v247, v246
	v_fma_f32 v248, v246, v246, -v248
	v_fma_f32 v249, v246, v247, v249
	ds_read_b64 v[230:231], v238
	ds_read_b64 v[232:233], v239
	ds_read_b64 v[234:235], v240
	ds_read_b64 v[236:237], v241
	s_waitcnt lgkmcnt(8)
; DI float cos2pi(float x) { return __builtin_amdgcn_cosf(x); }
; DI float sin2pi(float x) { return __builtin_amdgcn_sinf(x); }
; template <bool INV>
; DI void fft_lds(float2* buf_, int L, int logL, int gtid, int NTG) {
;     ...
;       for (int t = gtid; t < (L >> 2); t += NTG) {
;         const int k = t & (S - 1), base = ((t - k) << 2) | k;
;         const v2f a0 = buf[base], a1 = buf[base + S], a2 = buf[base + 2 * S], a3 = buf[base + 3 * S];
;         const float fr = (float)k * i4;
;         const v2f w1 = v2f{cos2pi(fr), sin2pi(fr)};
;         const v2f w2 = vcmul(w1, w1);
;         const v2f x0 = a0 + a2;
;         const v2f x2 = vcmulc(a0 - a2, w1);
;         const v2f x1 = a1 + a3;
;         const v2f d13 = vcmulc(a1 - a3, w1);
;         const v2f x3 = v2f{d13.y, -d13.x};
;         buf[base] = x0 + x1;
;         buf[base + S] = vcmulc(x0 - x1, w2);
;         buf[base + 2 * S] = x2 + x3;
;         buf[base + 3 * S] = vcmulc(x2 - x3, w2);
;       }
	v_add_f32_e32 v110, v64, v68
	v_sub_f32_e32 v112, v64, v68
	v_add_f32_e32 v30, v66, v70
	v_sub_f32_e32 v32, v66, v70
	v_add_f32_e32 v111, v65, v69
	v_sub_f32_e32 v113, v65, v69
	v_add_f32_e32 v31, v67, v71
	v_sub_f32_e32 v33, v67, v71
	v_mul_f32_e32 v251, v112, v106
	v_mul_f32_e32 v252, v112, v107
	v_fma_f32 v47, v113, v107, v251
	v_fma_f32 v250, v113, v106, -v252
	v_mul_f32_e32 v251, v32, v106
	v_mul_f32_e32 v252, v32, v107
	v_fma_f32 v253, v33, v107, v251
	v_fma_f32 v254, v33, v106, -v252
	v_add_f32_e32 v64, v110, v30
	v_add_f32_e32 v65, v111, v31
	v_sub_f32_e32 v110, v110, v30
	v_sub_f32_e32 v111, v111, v31
	v_mul_f32_e32 v251, v110, v108
	v_mul_f32_e32 v252, v110, v109
	v_fma_f32 v66, v111, v109, v251
	v_fma_f32 v67, v111, v108, -v252
	v_add_f32_e32 v68, v47, v254
	v_sub_f32_e32 v69, v250, v253
	v_sub_f32_e32 v30, v47, v254
	v_add_f32_e32 v31, v250, v253
	v_mul_f32_e32 v251, v30, v108
	v_mul_f32_e32 v252, v30, v109
	v_fma_f32 v70, v31, v109, v251
	v_fma_f32 v71, v31, v108, -v252
	ds_write_b64 v102, v[64:65]
	ds_write_b64 v103, v[66:67]
	ds_write_b64 v104, v[68:69]
	ds_write_b64 v105, v[70:71]
	v_mad_u32_u24 v250, s61, 6, v38
	v_and_b32_e32 v251, 15, v250
	v_sub_u32_e32 v252, v250, v251
	v_lshl_or_b32 v252, v252, 2, v251
	v_cvt_f32_u32_e32 v251, v251
	v_mul_f32_e32 v251, 0x3c800000, v251
	v_cos_f32_e32 v106, v251
	v_sin_f32_e32 v107, v251
	v_lshl_add_u32 v72, v252, 3, v40
	v_add_u32_e32 v73, 0x80, v72
	v_add_u32_e32 v74, 0x100, v72
	v_add_u32_e32 v75, 0x180, v72
	v_bfe_u32 v253, v252, 5, 2
	v_bfe_u32 v254, v252, 6, 1
	v_lshl_or_b32 v253, v253, 2, v253
	v_lshl_or_b32 v253, v254, 4, v253
	v_xor_b32_e32 v253, v253, v252
	v_lshlrev_b32_e32 v253, 3, v253
	v_add_u32_e32 v102, v40, v253
	v_xad_u32 v103, v253, s0, v40
	v_xad_u32 v104, v253, s1, v40
	v_xad_u32 v105, v253, s4, v40
	v_mul_f32_e32 v108, v107, v107
	v_mul_f32_e32 v109, v107, v106
	v_fma_f32 v108, v106, v106, -v108
	v_fma_f32 v109, v106, v107, v109
	ds_read_b64 v[64:65], v72
	ds_read_b64 v[66:67], v73
	ds_read_b64 v[68:69], v74
	ds_read_b64 v[70:71], v75
	s_waitcnt lgkmcnt(8)
	v_add_f32_e32 v110, v230, v234
	v_sub_f32_e32 v112, v230, v234
	v_add_f32_e32 v30, v232, v236
	v_sub_f32_e32 v32, v232, v236
	v_add_f32_e32 v111, v231, v235
	v_sub_f32_e32 v113, v231, v235
	v_add_f32_e32 v31, v233, v237
	v_sub_f32_e32 v33, v233, v237
	v_mul_f32_e32 v251, v112, v246
	v_mul_f32_e32 v252, v112, v247
	v_fma_f32 v47, v113, v247, v251
	v_fma_f32 v250, v113, v246, -v252
	v_mul_f32_e32 v251, v32, v246
	v_mul_f32_e32 v252, v32, v247
	v_fma_f32 v253, v33, v247, v251
	v_fma_f32 v254, v33, v246, -v252
	v_add_f32_e32 v230, v110, v30
	v_add_f32_e32 v231, v111, v31
	v_sub_f32_e32 v110, v110, v30
	v_sub_f32_e32 v111, v111, v31
	v_mul_f32_e32 v251, v110, v248
	v_mul_f32_e32 v252, v110, v249
	v_fma_f32 v232, v111, v249, v251
	v_fma_f32 v233, v111, v248, -v252
	v_add_f32_e32 v234, v47, v254
	v_sub_f32_e32 v235, v250, v253
	v_sub_f32_e32 v30, v47, v254
	v_add_f32_e32 v31, v250, v253
	v_mul_f32_e32 v251, v30, v248
	v_mul_f32_e32 v252, v30, v249
	v_fma_f32 v236, v31, v249, v251
	v_fma_f32 v237, v31, v248, -v252
	ds_write_b64 v242, v[230:231]
	ds_write_b64 v243, v[232:233]
	ds_write_b64 v244, v[234:235]
	ds_write_b64 v245, v[236:237]
	v_mad_u32_u24 v250, s61, 7, v38
	v_and_b32_e32 v251, 15, v250
	v_sub_u32_e32 v252, v250, v251
	v_lshl_or_b32 v252, v252, 2, v251
	v_cvt_f32_u32_e32 v251, v251
	v_mul_f32_e32 v251, 0x3c800000, v251
	v_cos_f32_e32 v246, v251
	v_sin_f32_e32 v247, v251
	v_lshl_add_u32 v238, v252, 3, v40
	v_add_u32_e32 v239, 0x80, v238
	v_add_u32_e32 v240, 0x100, v238
	v_add_u32_e32 v241, 0x180, v238
	v_bfe_u32 v253, v252, 5, 2
	v_bfe_u32 v254, v252, 6, 1
	v_lshl_or_b32 v253, v253, 2, v253
	v_lshl_or_b32 v253, v254, 4, v253
	v_xor_b32_e32 v253, v253, v252
	v_lshlrev_b32_e32 v253, 3, v253
	v_add_u32_e32 v242, v40, v253
	v_xad_u32 v243, v253, s0, v40
	v_xad_u32 v244, v253, s1, v40
	v_xad_u32 v245, v253, s4, v40
	v_mul_f32_e32 v248, v247, v247
	v_mul_f32_e32 v249, v247, v246
	v_fma_f32 v248, v246, v246, -v248
	v_fma_f32 v249, v246, v247, v249
	ds_read_b64 v[230:231], v238
	ds_read_b64 v[232:233], v239
	ds_read_b64 v[234:235], v240
	ds_read_b64 v[236:237], v241
	s_waitcnt lgkmcnt(8)
	v_add_f32_e32 v110, v64, v68
	v_sub_f32_e32 v112, v64, v68
	v_add_f32_e32 v30, v66, v70
	v_sub_f32_e32 v32, v66, v70
	v_add_f32_e32 v111, v65, v69
	v_sub_f32_e32 v113, v65, v69
	v_add_f32_e32 v31, v67, v71
	v_sub_f32_e32 v33, v67, v71
	v_mul_f32_e32 v251, v112, v106
	v_mul_f32_e32 v252, v112, v107
	v_fma_f32 v47, v113, v107, v251
	v_fma_f32 v250, v113, v106, -v252
	v_mul_f32_e32 v251, v32, v106
	v_mul_f32_e32 v252, v32, v107
	v_fma_f32 v253, v33, v107, v251
	v_fma_f32 v254, v33, v106, -v252
	v_add_f32_e32 v64, v110, v30
	v_add_f32_e32 v65, v111, v31
	v_sub_f32_e32 v110, v110, v30
	v_sub_f32_e32 v111, v111, v31
	v_mul_f32_e32 v251, v110, v108
	v_mul_f32_e32 v252, v110, v109
	v_fma_f32 v66, v111, v109, v251
	v_fma_f32 v67, v111, v108, -v252
	v_add_f32_e32 v68, v47, v254
	v_sub_f32_e32 v69, v250, v253
	v_sub_f32_e32 v30, v47, v254
	v_add_f32_e32 v31, v250, v253
	v_mul_f32_e32 v251, v30, v108
	v_mul_f32_e32 v252, v30, v109
	v_fma_f32 v70, v31, v109, v251
	v_fma_f32 v71, v31, v108, -v252
	ds_write_b64 v102, v[64:65]
	ds_write_b64 v103, v[66:67]
	ds_write_b64 v104, v[68:69]
	ds_write_b64 v105, v[70:71]
	s_waitcnt lgkmcnt(4)
	v_add_f32_e32 v110, v230, v234
	v_sub_f32_e32 v112, v230, v234
	v_add_f32_e32 v30, v232, v236
	v_sub_f32_e32 v32, v232, v236
	v_add_f32_e32 v111, v231, v235
	v_sub_f32_e32 v113, v231, v235
	v_add_f32_e32 v31, v233, v237
	v_sub_f32_e32 v33, v233, v237
	v_mul_f32_e32 v251, v112, v246
	v_mul_f32_e32 v252, v112, v247
	v_fma_f32 v47, v113, v247, v251
	v_fma_f32 v250, v113, v246, -v252
	v_mul_f32_e32 v251, v32, v246
	v_mul_f32_e32 v252, v32, v247
	v_fma_f32 v253, v33, v247, v251
	v_fma_f32 v254, v33, v246, -v252
	v_add_f32_e32 v230, v110, v30
	v_add_f32_e32 v231, v111, v31
	v_sub_f32_e32 v110, v110, v30
	v_sub_f32_e32 v111, v111, v31
	v_mul_f32_e32 v251, v110, v248
	v_mul_f32_e32 v252, v110, v249
	v_fma_f32 v232, v111, v249, v251
	v_fma_f32 v233, v111, v248, -v252
	v_add_f32_e32 v234, v47, v254
	v_sub_f32_e32 v235, v250, v253
	v_sub_f32_e32 v30, v47, v254
	v_add_f32_e32 v31, v250, v253
	v_mul_f32_e32 v251, v30, v248
	v_mul_f32_e32 v252, v30, v249
	v_fma_f32 v236, v31, v249, v251
	v_fma_f32 v237, v31, v248, -v252
	ds_write_b64 v242, v[230:231]
	ds_write_b64 v243, v[232:233]
	ds_write_b64 v244, v[234:235]
	ds_write_b64 v245, v[236:237]
	s_branch .LBB0_704
; template <bool INV>
; DI void fft_lds(float2* buf_, int L, int logL, int gtid, int NTG) {
;     ...
;     for (; s >= 2; s >>= 2) {
;       const int S = s >> 1;
;       const float i4 = 0.25f / (float)S;
; #pragma unroll 8
;       for (int t = gtid; t < (L >> 2); t += NTG) {
.Lffs_f_skip:
	v_cvt_f32_u32_e32 v30, s82
	s_and_b32 s4, s6, 0x7ffffffe
	s_add_i32 s7, s82, -1
	v_div_scale_f32 v31, s[0:1], v30, v30, s60
	v_rcp_f32_e32 v32, v31
	v_div_scale_f32 v33, vcc, s60, v30, s60
	v_fma_f32 v47, -v31, v32, 1.0
	v_fmac_f32_e32 v32, v47, v32
	v_mul_f32_e32 v47, v33, v32
	v_fma_f32 v64, -v31, v47, v33
	v_fmac_f32_e32 v47, v64, v32
	v_fma_f32 v31, -v31, v47, v33
	v_div_fmas_f32 v31, v31, v32, v47
	v_div_fixup_f32 v32, v31, v30, s60
	v_lshl_add_u32 v33, s82, 3, v40
	v_lshl_add_u32 v47, s4, 3, v40
	v_mov_b32_e32 v64, v38
	s_and_saveexec_b64 s[0:1], s[48:49]
	s_cbranch_execz .LBB0_710
	v_mad_u64_u32 v[30:31], s[4:5], s82, 24, v[40:41]
	s_mov_b64 s[4:5], 0
	v_mov_b32_e32 v31, v90
	v_mov_b32_e32 v65, v101
	v_mov_b32_e32 v64, v38

; DI float cos2pi(float x) { return __builtin_amdgcn_cosf(x); }
; DI float sin2pi(float x) { return __builtin_amdgcn_sinf(x); }
; template <bool INV>
; DI void fft_lds(float2* buf_, int L, int logL, int gtid, int NTG) {
;     ...
;     for (int f = 0; f < nf; ++f, S <<= 2) {
;       const float i4 = 0.25f / (float)S;
; #pragma unroll 8
;       for (int t = gtid; t < (L >> 2); t += NTG) {
;         const int k = t & (S - 1), base = ((t - k) << 2) | k;
;         const v2f p0 = buf[base], p1 = buf[base + S], p2 = buf[base + 2 * S], p3 = buf[base + 3 * S];
;         const float fr = (float)k * i4;
;         const v2f w1 = v2f{cos2pi(fr), sin2pi(fr)};
;         const v2f w2 = vcmul(w1, w1);
;         const v2f b1 = vcmul(p1, w2), b3 = vcmul(p3, w2);
;         const v2f q0 = p0 + b1, q1 = p0 - b1, q2 = p2 + b3, q3 = p2 - b3;
;         const v2f c2 = vcmul(q2, w1);
;         const v2f t3 = vcmul(q3, w1); const v2f c3 = v2f{-t3.y, t3.x};
;         buf[base] = q0 + c2;
;         buf[base + 2 * S] = q0 - c2;
;         buf[base + S] = q1 + c3;
;         buf[base + 3 * S] = q1 - c3;
;       }
.LBB0_723:
	s_and_saveexec_b64 s[54:55], s[18:19]
	s_cbranch_execz .LBB0_722
	s_cmp_gt_u32 s7, 16
	s_cbranch_scc1 .Lffs_i_skip
	s_cmp_eq_u32 s7, 16
	s_cbranch_scc1 .Lffs_i16
	s_cmp_eq_u32 s7, 4
	s_cbranch_scc1 .Lffs_i4
	s_movk_i32 s0, 0x8
	s_movk_i32 s1, 0x10
	s_movk_i32 s4, 0x18
	v_mov_b32_e32 v250, v38
	v_lshlrev_b32_e32 v252, 2, v250
	v_lshl_add_u32 v72, v252, 3, v40
	v_bfe_u32 v253, v252, 5, 2
	v_bfe_u32 v254, v252, 6, 1
	v_lshl_or_b32 v253, v253, 2, v253
	v_lshl_or_b32 v253, v254, 4, v253
	v_xor_b32_e32 v253, v253, v252
	v_lshlrev_b32_e32 v253, 3, v253
	v_add_u32_e32 v102, v40, v253
	v_xad_u32 v103, v253, s0, v40
	v_xad_u32 v104, v253, s1, v40
	v_xad_u32 v105, v253, s4, v40
	ds_read_b128 v[64:67], v72
	ds_read_b128 v[68:71], v72 offset:16
	v_mad_u32_u24 v250, s61, 1, v38
	v_lshlrev_b32_e32 v252, 2, v250
	v_lshl_add_u32 v238, v252, 3, v40
	v_bfe_u32 v253, v252, 5, 2
	v_bfe_u32 v254, v252, 6, 1
	v_lshl_or_b32 v253, v253, 2, v253
	v_lshl_or_b32 v253, v254, 4, v253
	v_xor_b32_e32 v253, v253, v252
	v_lshlrev_b32_e32 v253, 3, v253
	v_add_u32_e32 v242, v40, v253
	v_xad_u32 v243, v253, s0, v40
	v_xad_u32 v244, v253, s1, v40
	v_xad_u32 v245, v253, s4, v40
	ds_read_b128 v[230:233], v238
	ds_read_b128 v[234:237], v238 offset:16
	s_waitcnt lgkmcnt(2)
	v_add_f32_e32 v30, v64, v66
	v_sub_f32_e32 v32, v64, v66
	v_add_f32_e32 v47, v68, v70
	v_sub_f32_e32 v253, v68, v70
	v_add_f32_e32 v31, v65, v67
	v_sub_f32_e32 v33, v65, v67
	v_add_f32_e32 v250, v69, v71
	v_sub_f32_e32 v254, v69, v71
	v_add_f32_e32 v64, v30, v47
	v_add_f32_e32 v65, v31, v250
	v_sub_f32_e32 v66, v32, v254
	v_add_f32_e32 v67, v33, v253
	v_sub_f32_e32 v68, v30, v47
	v_sub_f32_e32 v69, v31, v250
	v_add_f32_e32 v70, v32, v254
	v_sub_f32_e32 v71, v33, v253
	ds_write_b64 v102, v[64:65]
	ds_write_b64 v103, v[66:67]
	ds_write_b64 v104, v[68:69]
	ds_write_b64 v105, v[70:71]
	v_mad_u32_u24 v250, s61, 2, v38
	v_lshlrev_b32_e32 v252, 2, v250
	v_lshl_add_u32 v72, v252, 3, v40
	v_bfe_u32 v253, v252, 5, 2
	v_bfe_u32 v254, v252, 6, 1
	v_lshl_or_b32 v253, v253, 2, v253
	v_lshl_or_b32 v253, v254, 4, v253
	v_xor_b32_e32 v253, v253, v252
	v_lshlrev_b32_e32 v253, 3, v253
	v_add_u32_e32 v102, v40, v253
	v_xad_u32 v103, v253, s0, v40
	v_xad_u32 v104, v253, s1, v40
	v_xad_u32 v105, v253, s4, v40
	ds_read_b128 v[64:67], v72
	ds_read_b128 v[68:71], v72 offset:16
	s_waitcnt lgkmcnt(6)
	v_add_f32_e32 v30, v230, v232
	v_sub_f32_e32 v32, v230, v232
	v_add_f32_e32 v47, v234, v236
	v_sub_f32_e32 v253, v234, v236
	v_add_f32_e32 v31, v231, v233
	v_sub_f32_e32 v33, v231, v233
	v_add_f32_e32 v250, v235, v237
	v_sub_f32_e32 v254, v235, v237
	v_add_f32_e32 v230, v30, v47
	v_add_f32_e32 v231, v31, v250
	v_sub_f32_e32 v232, v32, v254
	v_add_f32_e32 v233, v33, v253
	v_sub_f32_e32 v234, v30, v47
	v_sub_f32_e32 v235, v31, v250
	v_add_f32_e32 v236, v32, v254
	v_sub_f32_e32 v237, v33, v253
	ds_write_b64 v242, v[230:231]
	ds_write_b64 v243, v[232:233]
	ds_write_b64 v244, v[234:235]
	ds_write_b64 v245, v[236:237]
	v_mad_u32_u24 v250, s61, 3, v38
	v_lshlrev_b32_e32 v252, 2, v250
	v_lshl_add_u32 v238, v252, 3, v40
	v_bfe_u32 v253, v252, 5, 2
	v_bfe_u32 v254, v252, 6, 1
	v_lshl_or_b32 v253, v253, 2, v253
	v_lshl_or_b32 v253, v254, 4, v253
	v_xor_b32_e32 v253, v253, v252
	v_lshlrev_b32_e32 v253, 3, v253
	v_add_u32_e32 v242, v40, v253
	v_xad_u32 v243, v253, s0, v40
	v_xad_u32 v244, v253, s1, v40
	v_xad_u32 v245, v253, s4, v40
	ds_read_b128 v[230:233], v238
	ds_read_b128 v[234:237], v238 offset:16
	s_waitcnt lgkmcnt(6)
	v_add_f32_e32 v30, v64, v66
	v_sub_f32_e32 v32, v64, v66
	v_add_f32_e32 v47, v68, v70
	v_sub_f32_e32 v253, v68, v70
	v_add_f32_e32 v31, v65, v67
	v_sub_f32_e32 v33, v65, v67
	v_add_f32_e32 v250, v69, v71
	v_sub_f32_e32 v254, v69, v71
	v_add_f32_e32 v64, v30, v47
	v_add_f32_e32 v65, v31, v250
	v_sub_f32_e32 v66, v32, v254
	v_add_f32_e32 v67, v33, v253
	v_sub_f32_e32 v68, v30, v47
	v_sub_f32_e32 v69, v31, v250
	v_add_f32_e32 v70, v32, v254
	v_sub_f32_e32 v71, v33, v253
	ds_write_b64 v102, v[64:65]
	ds_write_b64 v103, v[66:67]
	ds_write_b64 v104, v[68:69]
	ds_write_b64 v105, v[70:71]
	v_mad_u32_u24 v250, s61, 4, v38
	v_lshlrev_b32_e32 v252, 2, v250
	v_lshl_add_u32 v72, v252, 3, v40
	v_bfe_u32 v253, v252, 5, 2
	v_bfe_u32 v254, v252, 6, 1
	v_lshl_or_b32 v253, v253, 2, v253
	v_lshl_or_b32 v253, v254, 4, v253
	v_xor_b32_e32 v253, v253, v252
	v_lshlrev_b32_e32 v253, 3, v253
	v_add_u32_e32 v102, v40, v253
	v_xad_u32 v103, v253, s0, v40
	v_xad_u32 v104, v253, s1, v40
	v_xad_u32 v105, v253, s4, v40
	ds_read_b128 v[64:67], v72
	ds_read_b128 v[68:71], v72 offset:16
	s_waitcnt lgkmcnt(6)
	v_add_f32_e32 v30, v230, v232
	v_sub_f32_e32 v32, v230, v232
	v_add_f32_e32 v47, v234, v236
	v_sub_f32_e32 v253, v234, v236
	v_add_f32_e32 v31, v231, v233
	v_sub_f32_e32 v33, v231, v233
	v_add_f32_e32 v250, v235, v237
	v_sub_f32_e32 v254, v235, v237
	v_add_f32_e32 v230, v30, v47
	v_add_f32_e32 v231, v31, v250
	v_sub_f32_e32 v232, v32, v254
	v_add_f32_e32 v233, v33, v253
	v_sub_f32_e32 v234, v30, v47
	v_sub_f32_e32 v235, v31, v250
	v_add_f32_e32 v236, v32, v254
	v_sub_f32_e32 v237, v33, v253
	ds_write_b64 v242, v[230:231]
	ds_write_b64 v243, v[232:233]
	ds_write_b64 v244, v[234:235]
	ds_write_b64 v245, v[236:237]
	v_mad_u32_u24 v250, s61, 5, v38
	v_lshlrev_b32_e32 v252, 2, v250
	v_lshl_add_u32 v238, v252, 3, v40
	v_bfe_u32 v253, v252, 5, 2
	v_bfe_u32 v254, v252, 6, 1
	v_lshl_or_b32 v253, v253, 2, v253
	v_lshl_or_b32 v253, v254, 4, v253
	v_xor_b32_e32 v253, v253, v252
	v_lshlrev_b32_e32 v253, 3, v253
	v_add_u32_e32 v242, v40, v253
	v_xad_u32 v243, v253, s0, v40
	v_xad_u32 v244, v253, s1, v40
	v_xad_u32 v245, v253, s4, v40
	ds_read_b128 v[230:233], v238
	ds_read_b128 v[234:237], v238 offset:16
	s_waitcnt lgkmcnt(6)
; DI float cos2pi(float x) { return __builtin_amdgcn_cosf(x); }
; DI float sin2pi(float x) { return __builtin_amdgcn_sinf(x); }
; template <bool INV>
; DI void fft_lds(float2* buf_, int L, int logL, int gtid, int NTG) {
;     ...
;     for (int f = 0; f < nf; ++f, S <<= 2) {
;       const float i4 = 0.25f / (float)S;
; #pragma unroll 8
;       for (int t = gtid; t < (L >> 2); t += NTG) {
;         const int k = t & (S - 1), base = ((t - k) << 2) | k;
;         const v2f p0 = buf[base], p1 = buf[base + S], p2 = buf[base + 2 * S], p3 = buf[base + 3 * S];
;         const float fr = (float)k * i4;
;         const v2f w1 = v2f{cos2pi(fr), sin2pi(fr)};
;         const v2f w2 = vcmul(w1, w1);
;         const v2f b1 = vcmul(p1, w2), b3 = vcmul(p3, w2);
;         const v2f q0 = p0 + b1, q1 = p0 - b1, q2 = p2 + b3, q3 = p2 - b3;
;         const v2f c2 = vcmul(q2, w1);
;         const v2f t3 = vcmul(q3, w1); const v2f c3 = v2f{-t3.y, t3.x};
;         buf[base] = q0 + c2;
;         buf[base + 2 * S] = q0 - c2;
;         buf[base + S] = q1 + c3;
;         buf[base + 3 * S] = q1 - c3;
;       }
	v_add_f32_e32 v30, v64, v66
	v_sub_f32_e32 v32, v64, v66
	v_add_f32_e32 v47, v68, v70
	v_sub_f32_e32 v253, v68, v70
	v_add_f32_e32 v31, v65, v67
	v_sub_f32_e32 v33, v65, v67
	v_add_f32_e32 v250, v69, v71
	v_sub_f32_e32 v254, v69, v71
	v_add_f32_e32 v64, v30, v47
	v_add_f32_e32 v65, v31, v250
	v_sub_f32_e32 v66, v32, v254
	v_add_f32_e32 v67, v33, v253
	v_sub_f32_e32 v68, v30, v47
	v_sub_f32_e32 v69, v31, v250
	v_add_f32_e32 v70, v32, v254
	v_sub_f32_e32 v71, v33, v253
	ds_write_b64 v102, v[64:65]
	ds_write_b64 v103, v[66:67]
	ds_write_b64 v104, v[68:69]
	ds_write_b64 v105, v[70:71]
	v_mad_u32_u24 v250, s61, 6, v38
	v_lshlrev_b32_e32 v252, 2, v250
	v_lshl_add_u32 v72, v252, 3, v40
	v_bfe_u32 v253, v252, 5, 2
	v_bfe_u32 v254, v252, 6, 1
	v_lshl_or_b32 v253, v253, 2, v253
	v_lshl_or_b32 v253, v254, 4, v253
	v_xor_b32_e32 v253, v253, v252
	v_lshlrev_b32_e32 v253, 3, v253
	v_add_u32_e32 v102, v40, v253
	v_xad_u32 v103, v253, s0, v40
	v_xad_u32 v104, v253, s1, v40
	v_xad_u32 v105, v253, s4, v40
	ds_read_b128 v[64:67], v72
	ds_read_b128 v[68:71], v72 offset:16
	s_waitcnt lgkmcnt(6)
	v_add_f32_e32 v30, v230, v232
	v_sub_f32_e32 v32, v230, v232
	v_add_f32_e32 v47, v234, v236
	v_sub_f32_e32 v253, v234, v236
	v_add_f32_e32 v31, v231, v233
	v_sub_f32_e32 v33, v231, v233
	v_add_f32_e32 v250, v235, v237
	v_sub_f32_e32 v254, v235, v237
	v_add_f32_e32 v230, v30, v47
	v_add_f32_e32 v231, v31, v250
	v_sub_f32_e32 v232, v32, v254
	v_add_f32_e32 v233, v33, v253
	v_sub_f32_e32 v234, v30, v47
	v_sub_f32_e32 v235, v31, v250
	v_add_f32_e32 v236, v32, v254
	v_sub_f32_e32 v237, v33, v253
	ds_write_b64 v242, v[230:231]
	ds_write_b64 v243, v[232:233]
	ds_write_b64 v244, v[234:235]
	ds_write_b64 v245, v[236:237]
	v_mad_u32_u24 v250, s61, 7, v38
	v_lshlrev_b32_e32 v252, 2, v250
	v_lshl_add_u32 v238, v252, 3, v40
	v_bfe_u32 v253, v252, 5, 2
	v_bfe_u32 v254, v252, 6, 1
	v_lshl_or_b32 v253, v253, 2, v253
	v_lshl_or_b32 v253, v254, 4, v253
	v_xor_b32_e32 v253, v253, v252
	v_lshlrev_b32_e32 v253, 3, v253
	v_add_u32_e32 v242, v40, v253
	v_xad_u32 v243, v253, s0, v40
	v_xad_u32 v244, v253, s1, v40
	v_xad_u32 v245, v253, s4, v40
	ds_read_b128 v[230:233], v238
	ds_read_b128 v[234:237], v238 offset:16
	s_waitcnt lgkmcnt(6)
	v_add_f32_e32 v30, v64, v66
	v_sub_f32_e32 v32, v64, v66
	v_add_f32_e32 v47, v68, v70
	v_sub_f32_e32 v253, v68, v70
	v_add_f32_e32 v31, v65, v67
	v_sub_f32_e32 v33, v65, v67
	v_add_f32_e32 v250, v69, v71
	v_sub_f32_e32 v254, v69, v71
	v_add_f32_e32 v64, v30, v47
	v_add_f32_e32 v65, v31, v250
	v_sub_f32_e32 v66, v32, v254
	v_add_f32_e32 v67, v33, v253
	v_sub_f32_e32 v68, v30, v47
	v_sub_f32_e32 v69, v31, v250
	v_add_f32_e32 v70, v32, v254
	v_sub_f32_e32 v71, v33, v253
	ds_write_b64 v102, v[64:65]
	ds_write_b64 v103, v[66:67]
	ds_write_b64 v104, v[68:69]
	ds_write_b64 v105, v[70:71]
	s_waitcnt lgkmcnt(4)
	v_add_f32_e32 v30, v230, v232
	v_sub_f32_e32 v32, v230, v232
	v_add_f32_e32 v47, v234, v236
	v_sub_f32_e32 v253, v234, v236
	v_add_f32_e32 v31, v231, v233
	v_sub_f32_e32 v33, v231, v233
	v_add_f32_e32 v250, v235, v237
	v_sub_f32_e32 v254, v235, v237
	v_add_f32_e32 v230, v30, v47
	v_add_f32_e32 v231, v31, v250
	v_sub_f32_e32 v232, v32, v254
	v_add_f32_e32 v233, v33, v253
	v_sub_f32_e32 v234, v30, v47
	v_sub_f32_e32 v235, v31, v250
	v_add_f32_e32 v236, v32, v254
	v_sub_f32_e32 v237, v33, v253
	ds_write_b64 v242, v[230:231]
	ds_write_b64 v243, v[232:233]
	ds_write_b64 v244, v[234:235]
	ds_write_b64 v245, v[236:237]
	s_branch .LBB0_722
.Lffs_i4:
	s_movk_i32 s0, 0x20
	s_movk_i32 s1, 0x40
	s_movk_i32 s4, 0x60
	v_mov_b32_e32 v250, v38
	v_and_b32_e32 v251, 3, v250
	v_sub_u32_e32 v252, v250, v251
	v_lshl_or_b32 v252, v252, 2, v251
	v_cvt_f32_u32_e32 v251, v251
	v_mul_f32_e32 v251, 0x3d800000, v251
	v_cos_f32_e32 v106, v251
	v_sin_f32_e32 v107, v251
	v_bfe_u32 v253, v252, 5, 2
	v_bfe_u32 v254, v252, 6, 1
	v_lshl_or_b32 v253, v253, 2, v253
	v_lshl_or_b32 v253, v254, 4, v253
	v_xor_b32_e32 v253, v253, v252
	v_lshlrev_b32_e32 v253, 3, v253
	v_add_u32_e32 v72, v40, v253
	v_xad_u32 v73, v253, s0, v40
	v_xad_u32 v74, v253, s1, v40
	v_xad_u32 v75, v253, s4, v40
	v_mul_f32_e32 v108, v107, v107
	v_mul_f32_e32 v109, v107, v106
	v_fma_f32 v108, v106, v106, -v108
	v_fma_f32 v109, v106, v107, v109
	ds_read_b64 v[64:65], v72
	ds_read_b64 v[66:67], v73
	ds_read_b64 v[68:69], v74
	ds_read_b64 v[70:71], v75
	v_mad_u32_u24 v250, s61, 1, v38
	v_and_b32_e32 v251, 3, v250
	v_sub_u32_e32 v252, v250, v251
	v_lshl_or_b32 v252, v252, 2, v251
	v_cvt_f32_u32_e32 v251, v251
	v_mul_f32_e32 v251, 0x3d800000, v251
	v_cos_f32_e32 v246, v251
	v_sin_f32_e32 v247, v251
	v_bfe_u32 v253, v252, 5, 2
	v_bfe_u32 v254, v252, 6, 1
	v_lshl_or_b32 v253, v253, 2, v253
	v_lshl_or_b32 v253, v254, 4, v253
	v_xor_b32_e32 v253, v253, v252
	v_lshlrev_b32_e32 v253, 3, v253
	v_add_u32_e32 v238, v40, v253
	v_xad_u32 v239, v253, s0, v40
	v_xad_u32 v240, v253, s1, v40
	v_xad_u32 v241, v253, s4, v40
	v_mul_f32_e32 v248, v247, v247
	v_mul_f32_e32 v249, v247, v246
	v_fma_f32 v248, v246, v246, -v248
	v_fma_f32 v249, v246, v247, v249
	ds_read_b64 v[230:231], v238
	ds_read_b64 v[232:233], v239
	ds_read_b64 v[234:235], v240
	ds_read_b64 v[236:237], v241
	s_waitcnt lgkmcnt(4)
; DI float cos2pi(float x) { return __builtin_amdgcn_cosf(x); }
; DI float sin2pi(float x) { return __builtin_amdgcn_sinf(x); }
; template <bool INV>
; DI void fft_lds(float2* buf_, int L, int logL, int gtid, int NTG) {
;     ...
;     for (int f = 0; f < nf; ++f, S <<= 2) {
;       const float i4 = 0.25f / (float)S;
; #pragma unroll 8
;       for (int t = gtid; t < (L >> 2); t += NTG) {
;         const int k = t & (S - 1), base = ((t - k) << 2) | k;
;         const v2f p0 = buf[base], p1 = buf[base + S], p2 = buf[base + 2 * S], p3 = buf[base + 3 * S];
;         const float fr = (float)k * i4;
;         const v2f w1 = v2f{cos2pi(fr), sin2pi(fr)};
;         const v2f w2 = vcmul(w1, w1);
;         const v2f b1 = vcmul(p1, w2), b3 = vcmul(p3, w2);
;         const v2f q0 = p0 + b1, q1 = p0 - b1, q2 = p2 + b3, q3 = p2 - b3;
;         const v2f c2 = vcmul(q2, w1);
;         const v2f t3 = vcmul(q3, w1); const v2f c3 = v2f{-t3.y, t3.x};
;         buf[base] = q0 + c2;
;         buf[base + 2 * S] = q0 - c2;
;         buf[base + S] = q1 + c3;
;         buf[base + 3 * S] = q1 - c3;
;       }
	v_mul_f32_e32 v251, v67, v109
	v_mul_f32_e32 v252, v67, v108
	v_fma_f32 v110, v66, v108, -v251
	v_fma_f32 v111, v66, v109, v252
	v_mul_f32_e32 v251, v71, v109
	v_mul_f32_e32 v252, v71, v108
	v_fma_f32 v112, v70, v108, -v251
	v_fma_f32 v113, v70, v109, v252
	v_add_f32_e32 v30, v64, v110
	v_sub_f32_e32 v32, v64, v110
	v_add_f32_e32 v47, v68, v112
	v_sub_f32_e32 v253, v68, v112
	v_add_f32_e32 v31, v65, v111
	v_sub_f32_e32 v33, v65, v111
	v_add_f32_e32 v250, v69, v113
	v_sub_f32_e32 v254, v69, v113
	v_mul_f32_e32 v251, v250, v107
	v_mul_f32_e32 v252, v250, v106
	v_fma_f32 v110, v47, v106, -v251
	v_fma_f32 v111, v47, v107, v252
	v_mul_f32_e32 v251, v254, v107
	v_mul_f32_e32 v252, v254, v106
	v_fma_f32 v112, v253, v106, -v251
	v_fma_f32 v113, v253, v107, v252
	v_add_f32_e32 v64, v30, v110
	v_add_f32_e32 v65, v31, v111
	v_sub_f32_e32 v66, v32, v113
	v_add_f32_e32 v67, v33, v112
	v_sub_f32_e32 v68, v30, v110
	v_sub_f32_e32 v69, v31, v111
	v_add_f32_e32 v70, v32, v113
	v_sub_f32_e32 v71, v33, v112
	ds_write_b64 v72, v[64:65]
	ds_write_b64 v73, v[66:67]
	ds_write_b64 v74, v[68:69]
	ds_write_b64 v75, v[70:71]
	v_mad_u32_u24 v250, s61, 2, v38
	v_and_b32_e32 v251, 3, v250
	v_sub_u32_e32 v252, v250, v251
	v_lshl_or_b32 v252, v252, 2, v251
	v_cvt_f32_u32_e32 v251, v251
	v_mul_f32_e32 v251, 0x3d800000, v251
	v_cos_f32_e32 v106, v251
	v_sin_f32_e32 v107, v251
	v_bfe_u32 v253, v252, 5, 2
	v_bfe_u32 v254, v252, 6, 1
	v_lshl_or_b32 v253, v253, 2, v253
	v_lshl_or_b32 v253, v254, 4, v253
	v_xor_b32_e32 v253, v253, v252
	v_lshlrev_b32_e32 v253, 3, v253
	v_add_u32_e32 v72, v40, v253
	v_xad_u32 v73, v253, s0, v40
	v_xad_u32 v74, v253, s1, v40
	v_xad_u32 v75, v253, s4, v40
	v_mul_f32_e32 v108, v107, v107
	v_mul_f32_e32 v109, v107, v106
	v_fma_f32 v108, v106, v106, -v108
	v_fma_f32 v109, v106, v107, v109
	ds_read_b64 v[64:65], v72
	ds_read_b64 v[66:67], v73
	ds_read_b64 v[68:69], v74
	ds_read_b64 v[70:71], v75
	s_waitcnt lgkmcnt(8)
	v_mul_f32_e32 v251, v233, v249
	v_mul_f32_e32 v252, v233, v248
	v_fma_f32 v110, v232, v248, -v251
	v_fma_f32 v111, v232, v249, v252
	v_mul_f32_e32 v251, v237, v249
	v_mul_f32_e32 v252, v237, v248
	v_fma_f32 v112, v236, v248, -v251
	v_fma_f32 v113, v236, v249, v252
	v_add_f32_e32 v30, v230, v110
	v_sub_f32_e32 v32, v230, v110
	v_add_f32_e32 v47, v234, v112
	v_sub_f32_e32 v253, v234, v112
	v_add_f32_e32 v31, v231, v111
	v_sub_f32_e32 v33, v231, v111
	v_add_f32_e32 v250, v235, v113
	v_sub_f32_e32 v254, v235, v113
	v_mul_f32_e32 v251, v250, v247
	v_mul_f32_e32 v252, v250, v246
	v_fma_f32 v110, v47, v246, -v251
	v_fma_f32 v111, v47, v247, v252
	v_mul_f32_e32 v251, v254, v247
	v_mul_f32_e32 v252, v254, v246
	v_fma_f32 v112, v253, v246, -v251
	v_fma_f32 v113, v253, v247, v252
	v_add_f32_e32 v230, v30, v110
	v_add_f32_e32 v231, v31, v111
	v_sub_f32_e32 v232, v32, v113
	v_add_f32_e32 v233, v33, v112
	v_sub_f32_e32 v234, v30, v110
	v_sub_f32_e32 v235, v31, v111
	v_add_f32_e32 v236, v32, v113
	v_sub_f32_e32 v237, v33, v112
	ds_write_b64 v238, v[230:231]
	ds_write_b64 v239, v[232:233]
	ds_write_b64 v240, v[234:235]
	ds_write_b64 v241, v[236:237]
	v_mad_u32_u24 v250, s61, 3, v38
	v_and_b32_e32 v251, 3, v250
	v_sub_u32_e32 v252, v250, v251
	v_lshl_or_b32 v252, v252, 2, v251
	v_cvt_f32_u32_e32 v251, v251
	v_mul_f32_e32 v251, 0x3d800000, v251
	v_cos_f32_e32 v246, v251
	v_sin_f32_e32 v247, v251
	v_bfe_u32 v253, v252, 5, 2
	v_bfe_u32 v254, v252, 6, 1
	v_lshl_or_b32 v253, v253, 2, v253
	v_lshl_or_b32 v253, v254, 4, v253
	v_xor_b32_e32 v253, v253, v252
	v_lshlrev_b32_e32 v253, 3, v253
	v_add_u32_e32 v238, v40, v253
	v_xad_u32 v239, v253, s0, v40
	v_xad_u32 v240, v253, s1, v40
	v_xad_u32 v241, v253, s4, v40
	v_mul_f32_e32 v248, v247, v247
	v_mul_f32_e32 v249, v247, v246
	v_fma_f32 v248, v246, v246, -v248
	v_fma_f32 v249, v246, v247, v249
	ds_read_b64 v[230:231], v238
	ds_read_b64 v[232:233], v239
	ds_read_b64 v[234:235], v240
	ds_read_b64 v[236:237], v241
	s_waitcnt lgkmcnt(8)
	v_mul_f32_e32 v251, v67, v109
	v_mul_f32_e32 v252, v67, v108
	v_fma_f32 v110, v66, v108, -v251
	v_fma_f32 v111, v66, v109, v252
	v_mul_f32_e32 v251, v71, v109
	v_mul_f32_e32 v252, v71, v108
	v_fma_f32 v112, v70, v108, -v251
	v_fma_f32 v113, v70, v109, v252
	v_add_f32_e32 v30, v64, v110
	v_sub_f32_e32 v32, v64, v110
	v_add_f32_e32 v47, v68, v112
	v_sub_f32_e32 v253, v68, v112
	v_add_f32_e32 v31, v65, v111
	v_sub_f32_e32 v33, v65, v111
	v_add_f32_e32 v250, v69, v113
	v_sub_f32_e32 v254, v69, v113
	v_mul_f32_e32 v251, v250, v107
	v_mul_f32_e32 v252, v250, v106
	v_fma_f32 v110, v47, v106, -v251
	v_fma_f32 v111, v47, v107, v252
	v_mul_f32_e32 v251, v254, v107
	v_mul_f32_e32 v252, v254, v106
	v_fma_f32 v112, v253, v106, -v251
	v_fma_f32 v113, v253, v107, v252
	v_add_f32_e32 v64, v30, v110
	v_add_f32_e32 v65, v31, v111
	v_sub_f32_e32 v66, v32, v113
	v_add_f32_e32 v67, v33, v112
	v_sub_f32_e32 v68, v30, v110
	v_sub_f32_e32 v69, v31, v111
	v_add_f32_e32 v70, v32, v113
	v_sub_f32_e32 v71, v33, v112
	ds_write_b64 v72, v[64:65]
	ds_write_b64 v73, v[66:67]
	ds_write_b64 v74, v[68:69]
	ds_write_b64 v75, v[70:71]
	v_mad_u32_u24 v250, s61, 4, v38
	v_and_b32_e32 v251, 3, v250
	v_sub_u32_e32 v252, v250, v251
	v_lshl_or_b32 v252, v252, 2, v251
	v_cvt_f32_u32_e32 v251, v251
	v_mul_f32_e32 v251, 0x3d800000, v251
	v_cos_f32_e32 v106, v251
	v_sin_f32_e32 v107, v251
	v_bfe_u32 v253, v252, 5, 2
	v_bfe_u32 v254, v252, 6, 1
	v_lshl_or_b32 v253, v253, 2, v253
	v_lshl_or_b32 v253, v254, 4, v253
	v_xor_b32_e32 v253, v253, v252
	v_lshlrev_b32_e32 v253, 3, v253
	v_add_u32_e32 v72, v40, v253
	v_xad_u32 v73, v253, s0, v40
	v_xad_u32 v74, v253, s1, v40
	v_xad_u32 v75, v253, s4, v40
	v_mul_f32_e32 v108, v107, v107
	v_mul_f32_e32 v109, v107, v106
	v_fma_f32 v108, v106, v106, -v108
	v_fma_f32 v109, v106, v107, v109
	ds_read_b64 v[64:65], v72
	ds_read_b64 v[66:67], v73
	ds_read_b64 v[68:69], v74
	ds_read_b64 v[70:71], v75
	s_waitcnt lgkmcnt(8)
; DI float cos2pi(float x) { return __builtin_amdgcn_cosf(x); }
; DI float sin2pi(float x) { return __builtin_amdgcn_sinf(x); }
; template <bool INV>
; DI void fft_lds(float2* buf_, int L, int logL, int gtid, int NTG) {
;     ...
;     for (int f = 0; f < nf; ++f, S <<= 2) {
;       const float i4 = 0.25f / (float)S;
; #pragma unroll 8
;       for (int t = gtid; t < (L >> 2); t += NTG) {
;         const int k = t & (S - 1), base = ((t - k) << 2) | k;
;         const v2f p0 = buf[base], p1 = buf[base + S], p2 = buf[base + 2 * S], p3 = buf[base + 3 * S];
;         const float fr = (float)k * i4;
;         const v2f w1 = v2f{cos2pi(fr), sin2pi(fr)};
;         const v2f w2 = vcmul(w1, w1);
;         const v2f b1 = vcmul(p1, w2), b3 = vcmul(p3, w2);
;         const v2f q0 = p0 + b1, q1 = p0 - b1, q2 = p2 + b3, q3 = p2 - b3;
;         const v2f c2 = vcmul(q2, w1);
;         const v2f t3 = vcmul(q3, w1); const v2f c3 = v2f{-t3.y, t3.x};
;         buf[base] = q0 + c2;
;         buf[base + 2 * S] = q0 - c2;
;         buf[base + S] = q1 + c3;
;         buf[base + 3 * S] = q1 - c3;
;       }
	v_mul_f32_e32 v251, v233, v249
	v_mul_f32_e32 v252, v233, v248
	v_fma_f32 v110, v232, v248, -v251
	v_fma_f32 v111, v232, v249, v252
	v_mul_f32_e32 v251, v237, v249
	v_mul_f32_e32 v252, v237, v248
	v_fma_f32 v112, v236, v248, -v251
	v_fma_f32 v113, v236, v249, v252
	v_add_f32_e32 v30, v230, v110
	v_sub_f32_e32 v32, v230, v110
	v_add_f32_e32 v47, v234, v112
	v_sub_f32_e32 v253, v234, v112
	v_add_f32_e32 v31, v231, v111
	v_sub_f32_e32 v33, v231, v111
	v_add_f32_e32 v250, v235, v113
	v_sub_f32_e32 v254, v235, v113
	v_mul_f32_e32 v251, v250, v247
	v_mul_f32_e32 v252, v250, v246
	v_fma_f32 v110, v47, v246, -v251
	v_fma_f32 v111, v47, v247, v252
	v_mul_f32_e32 v251, v254, v247
	v_mul_f32_e32 v252, v254, v246
	v_fma_f32 v112, v253, v246, -v251
	v_fma_f32 v113, v253, v247, v252
	v_add_f32_e32 v230, v30, v110
	v_add_f32_e32 v231, v31, v111
	v_sub_f32_e32 v232, v32, v113
	v_add_f32_e32 v233, v33, v112
	v_sub_f32_e32 v234, v30, v110
	v_sub_f32_e32 v235, v31, v111
	v_add_f32_e32 v236, v32, v113
	v_sub_f32_e32 v237, v33, v112
	ds_write_b64 v238, v[230:231]
	ds_write_b64 v239, v[232:233]
	ds_write_b64 v240, v[234:235]
	ds_write_b64 v241, v[236:237]
	v_mad_u32_u24 v250, s61, 5, v38
	v_and_b32_e32 v251, 3, v250
	v_sub_u32_e32 v252, v250, v251
	v_lshl_or_b32 v252, v252, 2, v251
	v_cvt_f32_u32_e32 v251, v251
	v_mul_f32_e32 v251, 0x3d800000, v251
	v_cos_f32_e32 v246, v251
	v_sin_f32_e32 v247, v251
	v_bfe_u32 v253, v252, 5, 2
	v_bfe_u32 v254, v252, 6, 1
	v_lshl_or_b32 v253, v253, 2, v253
	v_lshl_or_b32 v253, v254, 4, v253
	v_xor_b32_e32 v253, v253, v252
	v_lshlrev_b32_e32 v253, 3, v253
	v_add_u32_e32 v238, v40, v253
	v_xad_u32 v239, v253, s0, v40
	v_xad_u32 v240, v253, s1, v40
	v_xad_u32 v241, v253, s4, v40
	v_mul_f32_e32 v248, v247, v247
	v_mul_f32_e32 v249, v247, v246
	v_fma_f32 v248, v246, v246, -v248
	v_fma_f32 v249, v246, v247, v249
	ds_read_b64 v[230:231], v238
	ds_read_b64 v[232:233], v239
	ds_read_b64 v[234:235], v240
	ds_read_b64 v[236:237], v241
	s_waitcnt lgkmcnt(8)
	v_mul_f32_e32 v251, v67, v109
	v_mul_f32_e32 v252, v67, v108
	v_fma_f32 v110, v66, v108, -v251
	v_fma_f32 v111, v66, v109, v252
	v_mul_f32_e32 v251, v71, v109
	v_mul_f32_e32 v252, v71, v108
	v_fma_f32 v112, v70, v108, -v251
	v_fma_f32 v113, v70, v109, v252
	v_add_f32_e32 v30, v64, v110
	v_sub_f32_e32 v32, v64, v110
	v_add_f32_e32 v47, v68, v112
	v_sub_f32_e32 v253, v68, v112
	v_add_f32_e32 v31, v65, v111
	v_sub_f32_e32 v33, v65, v111
	v_add_f32_e32 v250, v69, v113
	v_sub_f32_e32 v254, v69, v113
	v_mul_f32_e32 v251, v250, v107
	v_mul_f32_e32 v252, v250, v106
	v_fma_f32 v110, v47, v106, -v251
	v_fma_f32 v111, v47, v107, v252
	v_mul_f32_e32 v251, v254, v107
	v_mul_f32_e32 v252, v254, v106
	v_fma_f32 v112, v253, v106, -v251
	v_fma_f32 v113, v253, v107, v252
	v_add_f32_e32 v64, v30, v110
	v_add_f32_e32 v65, v31, v111
	v_sub_f32_e32 v66, v32, v113
	v_add_f32_e32 v67, v33, v112
	v_sub_f32_e32 v68, v30, v110
	v_sub_f32_e32 v69, v31, v111
	v_add_f32_e32 v70, v32, v113
	v_sub_f32_e32 v71, v33, v112
	ds_write_b64 v72, v[64:65]
	ds_write_b64 v73, v[66:67]
	ds_write_b64 v74, v[68:69]
	ds_write_b64 v75, v[70:71]
	v_mad_u32_u24 v250, s61, 6, v38
	v_and_b32_e32 v251, 3, v250
	v_sub_u32_e32 v252, v250, v251
	v_lshl_or_b32 v252, v252, 2, v251
	v_cvt_f32_u32_e32 v251, v251
	v_mul_f32_e32 v251, 0x3d800000, v251
	v_cos_f32_e32 v106, v251
	v_sin_f32_e32 v107, v251
	v_bfe_u32 v253, v252, 5, 2
	v_bfe_u32 v254, v252, 6, 1
	v_lshl_or_b32 v253, v253, 2, v253
	v_lshl_or_b32 v253, v254, 4, v253
	v_xor_b32_e32 v253, v253, v252
	v_lshlrev_b32_e32 v253, 3, v253
	v_add_u32_e32 v72, v40, v253
	v_xad_u32 v73, v253, s0, v40
	v_xad_u32 v74, v253, s1, v40
	v_xad_u32 v75, v253, s4, v40
	v_mul_f32_e32 v108, v107, v107
	v_mul_f32_e32 v109, v107, v106
	v_fma_f32 v108, v106, v106, -v108
	v_fma_f32 v109, v106, v107, v109
	ds_read_b64 v[64:65], v72
	ds_read_b64 v[66:67], v73
	ds_read_b64 v[68:69], v74
	ds_read_b64 v[70:71], v75
	s_waitcnt lgkmcnt(8)
	v_mul_f32_e32 v251, v233, v249
	v_mul_f32_e32 v252, v233, v248
	v_fma_f32 v110, v232, v248, -v251
	v_fma_f32 v111, v232, v249, v252
	v_mul_f32_e32 v251, v237, v249
	v_mul_f32_e32 v252, v237, v248
	v_fma_f32 v112, v236, v248, -v251
	v_fma_f32 v113, v236, v249, v252
	v_add_f32_e32 v30, v230, v110
	v_sub_f32_e32 v32, v230, v110
	v_add_f32_e32 v47, v234, v112
	v_sub_f32_e32 v253, v234, v112
	v_add_f32_e32 v31, v231, v111
	v_sub_f32_e32 v33, v231, v111
	v_add_f32_e32 v250, v235, v113
	v_sub_f32_e32 v254, v235, v113
	v_mul_f32_e32 v251, v250, v247
	v_mul_f32_e32 v252, v250, v246
	v_fma_f32 v110, v47, v246, -v251
	v_fma_f32 v111, v47, v247, v252
	v_mul_f32_e32 v251, v254, v247
	v_mul_f32_e32 v252, v254, v246
	v_fma_f32 v112, v253, v246, -v251
	v_fma_f32 v113, v253, v247, v252
	v_add_f32_e32 v230, v30, v110
	v_add_f32_e32 v231, v31, v111
	v_sub_f32_e32 v232, v32, v113
	v_add_f32_e32 v233, v33, v112
	v_sub_f32_e32 v234, v30, v110
	v_sub_f32_e32 v235, v31, v111
	v_add_f32_e32 v236, v32, v113
	v_sub_f32_e32 v237, v33, v112
	ds_write_b64 v238, v[230:231]
	ds_write_b64 v239, v[232:233]
	ds_write_b64 v240, v[234:235]
	ds_write_b64 v241, v[236:237]
	v_mad_u32_u24 v250, s61, 7, v38
	v_and_b32_e32 v251, 3, v250
	v_sub_u32_e32 v252, v250, v251
	v_lshl_or_b32 v252, v252, 2, v251
	v_cvt_f32_u32_e32 v251, v251
	v_mul_f32_e32 v251, 0x3d800000, v251
	v_cos_f32_e32 v246, v251
	v_sin_f32_e32 v247, v251
	v_bfe_u32 v253, v252, 5, 2
	v_bfe_u32 v254, v252, 6, 1
	v_lshl_or_b32 v253, v253, 2, v253
	v_lshl_or_b32 v253, v254, 4, v253
	v_xor_b32_e32 v253, v253, v252
	v_lshlrev_b32_e32 v253, 3, v253
	v_add_u32_e32 v238, v40, v253
	v_xad_u32 v239, v253, s0, v40
	v_xad_u32 v240, v253, s1, v40
	v_xad_u32 v241, v253, s4, v40
	v_mul_f32_e32 v248, v247, v247
	v_mul_f32_e32 v249, v247, v246
	v_fma_f32 v248, v246, v246, -v248
	v_fma_f32 v249, v246, v247, v249
	ds_read_b64 v[230:231], v238
	ds_read_b64 v[232:233], v239
	ds_read_b64 v[234:235], v240
	ds_read_b64 v[236:237], v241
	s_waitcnt lgkmcnt(8)
; DI float cos2pi(float x) { return __builtin_amdgcn_cosf(x); }
; DI float sin2pi(float x) { return __builtin_amdgcn_sinf(x); }
; template <bool INV>
; DI void fft_lds(float2* buf_, int L, int logL, int gtid, int NTG) {
;     ...
;     for (int f = 0; f < nf; ++f, S <<= 2) {
;       const float i4 = 0.25f / (float)S;
; #pragma unroll 8
;       for (int t = gtid; t < (L >> 2); t += NTG) {
;         const int k = t & (S - 1), base = ((t - k) << 2) | k;
;         const v2f p0 = buf[base], p1 = buf[base + S], p2 = buf[base + 2 * S], p3 = buf[base + 3 * S];
;         const float fr = (float)k * i4;
;         const v2f w1 = v2f{cos2pi(fr), sin2pi(fr)};
;         const v2f w2 = vcmul(w1, w1);
;         const v2f b1 = vcmul(p1, w2), b3 = vcmul(p3, w2);
;         const v2f q0 = p0 + b1, q1 = p0 - b1, q2 = p2 + b3, q3 = p2 - b3;
;         const v2f c2 = vcmul(q2, w1);
;         const v2f t3 = vcmul(q3, w1); const v2f c3 = v2f{-t3.y, t3.x};
;         buf[base] = q0 + c2;
;         buf[base + 2 * S] = q0 - c2;
;         buf[base + S] = q1 + c3;
;         buf[base + 3 * S] = q1 - c3;
;       }
	v_mul_f32_e32 v251, v67, v109
	v_mul_f32_e32 v252, v67, v108
	v_fma_f32 v110, v66, v108, -v251
	v_fma_f32 v111, v66, v109, v252
	v_mul_f32_e32 v251, v71, v109
	v_mul_f32_e32 v252, v71, v108
	v_fma_f32 v112, v70, v108, -v251
	v_fma_f32 v113, v70, v109, v252
	v_add_f32_e32 v30, v64, v110
	v_sub_f32_e32 v32, v64, v110
	v_add_f32_e32 v47, v68, v112
	v_sub_f32_e32 v253, v68, v112
	v_add_f32_e32 v31, v65, v111
	v_sub_f32_e32 v33, v65, v111
	v_add_f32_e32 v250, v69, v113
	v_sub_f32_e32 v254, v69, v113
	v_mul_f32_e32 v251, v250, v107
	v_mul_f32_e32 v252, v250, v106
	v_fma_f32 v110, v47, v106, -v251
	v_fma_f32 v111, v47, v107, v252
	v_mul_f32_e32 v251, v254, v107
	v_mul_f32_e32 v252, v254, v106
	v_fma_f32 v112, v253, v106, -v251
	v_fma_f32 v113, v253, v107, v252
	v_add_f32_e32 v64, v30, v110
	v_add_f32_e32 v65, v31, v111
	v_sub_f32_e32 v66, v32, v113
	v_add_f32_e32 v67, v33, v112
	v_sub_f32_e32 v68, v30, v110
	v_sub_f32_e32 v69, v31, v111
	v_add_f32_e32 v70, v32, v113
	v_sub_f32_e32 v71, v33, v112
	ds_write_b64 v72, v[64:65]
	ds_write_b64 v73, v[66:67]
	ds_write_b64 v74, v[68:69]
	ds_write_b64 v75, v[70:71]
	s_waitcnt lgkmcnt(4)
	v_mul_f32_e32 v251, v233, v249
	v_mul_f32_e32 v252, v233, v248
	v_fma_f32 v110, v232, v248, -v251
	v_fma_f32 v111, v232, v249, v252
	v_mul_f32_e32 v251, v237, v249
	v_mul_f32_e32 v252, v237, v248
	v_fma_f32 v112, v236, v248, -v251
	v_fma_f32 v113, v236, v249, v252
	v_add_f32_e32 v30, v230, v110
	v_sub_f32_e32 v32, v230, v110
	v_add_f32_e32 v47, v234, v112
	v_sub_f32_e32 v253, v234, v112
	v_add_f32_e32 v31, v231, v111
	v_sub_f32_e32 v33, v231, v111
	v_add_f32_e32 v250, v235, v113
	v_sub_f32_e32 v254, v235, v113
	v_mul_f32_e32 v251, v250, v247
	v_mul_f32_e32 v252, v250, v246
	v_fma_f32 v110, v47, v246, -v251
	v_fma_f32 v111, v47, v247, v252
	v_mul_f32_e32 v251, v254, v247
	v_mul_f32_e32 v252, v254, v246
	v_fma_f32 v112, v253, v246, -v251
	v_fma_f32 v113, v253, v247, v252
	v_add_f32_e32 v230, v30, v110
	v_add_f32_e32 v231, v31, v111
	v_sub_f32_e32 v232, v32, v113
	v_add_f32_e32 v233, v33, v112
	v_sub_f32_e32 v234, v30, v110
	v_sub_f32_e32 v235, v31, v111
	v_add_f32_e32 v236, v32, v113
	v_sub_f32_e32 v237, v33, v112
	ds_write_b64 v238, v[230:231]
	ds_write_b64 v239, v[232:233]
	ds_write_b64 v240, v[234:235]
	ds_write_b64 v241, v[236:237]
	s_branch .LBB0_722
.Lffs_i16:
	s_movk_i32 s0, 0x80
	s_movk_i32 s1, 0x128
	s_movk_i32 s4, 0x1a8
	v_mov_b32_e32 v250, v38
	v_and_b32_e32 v251, 15, v250
	v_sub_u32_e32 v252, v250, v251
	v_lshl_or_b32 v252, v252, 2, v251
	v_cvt_f32_u32_e32 v251, v251
	v_mul_f32_e32 v251, 0x3c800000, v251
	v_cos_f32_e32 v106, v251
	v_sin_f32_e32 v107, v251
	v_lshl_add_u32 v102, v252, 3, v40
	v_add_u32_e32 v103, 0x80, v102
	v_add_u32_e32 v104, 0x100, v102
	v_add_u32_e32 v105, 0x180, v102
	v_bfe_u32 v253, v252, 5, 2
	v_bfe_u32 v254, v252, 6, 1
	v_lshl_or_b32 v253, v253, 2, v253
	v_lshl_or_b32 v253, v254, 4, v253
	v_xor_b32_e32 v253, v253, v252
	v_lshlrev_b32_e32 v253, 3, v253
	v_add_u32_e32 v72, v40, v253
	v_xad_u32 v73, v253, s0, v40
	v_xad_u32 v74, v253, s1, v40
	v_xad_u32 v75, v253, s4, v40
	v_mul_f32_e32 v108, v107, v107
	v_mul_f32_e32 v109, v107, v106
	v_fma_f32 v108, v106, v106, -v108
	v_fma_f32 v109, v106, v107, v109
	ds_read_b64 v[64:65], v72
	ds_read_b64 v[66:67], v73
	ds_read_b64 v[68:69], v74
	ds_read_b64 v[70:71], v75
	v_mad_u32_u24 v250, s61, 1, v38
	v_and_b32_e32 v251, 15, v250
	v_sub_u32_e32 v252, v250, v251
	v_lshl_or_b32 v252, v252, 2, v251
	v_cvt_f32_u32_e32 v251, v251
	v_mul_f32_e32 v251, 0x3c800000, v251
	v_cos_f32_e32 v246, v251
	v_sin_f32_e32 v247, v251
	v_lshl_add_u32 v242, v252, 3, v40
	v_add_u32_e32 v243, 0x80, v242
	v_add_u32_e32 v244, 0x100, v242
	v_add_u32_e32 v245, 0x180, v242
	v_bfe_u32 v253, v252, 5, 2
	v_bfe_u32 v254, v252, 6, 1
	v_lshl_or_b32 v253, v253, 2, v253
	v_lshl_or_b32 v253, v254, 4, v253
	v_xor_b32_e32 v253, v253, v252
	v_lshlrev_b32_e32 v253, 3, v253
	v_add_u32_e32 v238, v40, v253
	v_xad_u32 v239, v253, s0, v40
	v_xad_u32 v240, v253, s1, v40
	v_xad_u32 v241, v253, s4, v40
	v_mul_f32_e32 v248, v247, v247
	v_mul_f32_e32 v249, v247, v246
	v_fma_f32 v248, v246, v246, -v248
	v_fma_f32 v249, v246, v247, v249
	ds_read_b64 v[230:231], v238
	ds_read_b64 v[232:233], v239
	ds_read_b64 v[234:235], v240
	ds_read_b64 v[236:237], v241
	s_waitcnt lgkmcnt(4)
	v_mul_f32_e32 v251, v67, v109
	v_mul_f32_e32 v252, v67, v108
	v_fma_f32 v110, v66, v108, -v251
	v_fma_f32 v111, v66, v109, v252
	v_mul_f32_e32 v251, v71, v109
	v_mul_f32_e32 v252, v71, v108
	v_fma_f32 v112, v70, v108, -v251
	v_fma_f32 v113, v70, v109, v252
	v_add_f32_e32 v30, v64, v110
	v_sub_f32_e32 v32, v64, v110
	v_add_f32_e32 v47, v68, v112
	v_sub_f32_e32 v253, v68, v112
	v_add_f32_e32 v31, v65, v111
	v_sub_f32_e32 v33, v65, v111
	v_add_f32_e32 v250, v69, v113
	v_sub_f32_e32 v254, v69, v113
	v_mul_f32_e32 v251, v250, v107
	v_mul_f32_e32 v252, v250, v106
	v_fma_f32 v110, v47, v106, -v251
	v_fma_f32 v111, v47, v107, v252
	v_mul_f32_e32 v251, v254, v107
	v_mul_f32_e32 v252, v254, v106
	v_fma_f32 v112, v253, v106, -v251
	v_fma_f32 v113, v253, v107, v252
	v_add_f32_e32 v64, v30, v110
	v_add_f32_e32 v65, v31, v111
	v_sub_f32_e32 v66, v32, v113
	v_add_f32_e32 v67, v33, v112
	v_sub_f32_e32 v68, v30, v110
	v_sub_f32_e32 v69, v31, v111
	v_add_f32_e32 v70, v32, v113
	v_sub_f32_e32 v71, v33, v112
	ds_write_b64 v102, v[64:65]
	ds_write_b64 v103, v[66:67]
	ds_write_b64 v104, v[68:69]
	ds_write_b64 v105, v[70:71]
	v_mad_u32_u24 v250, s61, 2, v38
	v_and_b32_e32 v251, 15, v250
	v_sub_u32_e32 v252, v250, v251
	v_lshl_or_b32 v252, v252, 2, v251
	v_cvt_f32_u32_e32 v251, v251
	v_mul_f32_e32 v251, 0x3c800000, v251
	v_cos_f32_e32 v106, v251
	v_sin_f32_e32 v107, v251
	v_lshl_add_u32 v102, v252, 3, v40
	v_add_u32_e32 v103, 0x80, v102
	v_add_u32_e32 v104, 0x100, v102
	v_add_u32_e32 v105, 0x180, v102
	v_bfe_u32 v253, v252, 5, 2
	v_bfe_u32 v254, v252, 6, 1
	v_lshl_or_b32 v253, v253, 2, v253
	v_lshl_or_b32 v253, v254, 4, v253
	v_xor_b32_e32 v253, v253, v252
	v_lshlrev_b32_e32 v253, 3, v253
	v_add_u32_e32 v72, v40, v253
	v_xad_u32 v73, v253, s0, v40
	v_xad_u32 v74, v253, s1, v40
	v_xad_u32 v75, v253, s4, v40
	v_mul_f32_e32 v108, v107, v107
	v_mul_f32_e32 v109, v107, v106
	v_fma_f32 v108, v106, v106, -v108
	v_fma_f32 v109, v106, v107, v109
	ds_read_b64 v[64:65], v72
	ds_read_b64 v[66:67], v73
	ds_read_b64 v[68:69], v74
	ds_read_b64 v[70:71], v75
	s_waitcnt lgkmcnt(8)
; DI float cos2pi(float x) { return __builtin_amdgcn_cosf(x); }
; DI float sin2pi(float x) { return __builtin_amdgcn_sinf(x); }
; template <bool INV>
; DI void fft_lds(float2* buf_, int L, int logL, int gtid, int NTG) {
;     ...
;     for (int f = 0; f < nf; ++f, S <<= 2) {
;       const float i4 = 0.25f / (float)S;
; #pragma unroll 8
;       for (int t = gtid; t < (L >> 2); t += NTG) {
;         const int k = t & (S - 1), base = ((t - k) << 2) | k;
;         const v2f p0 = buf[base], p1 = buf[base + S], p2 = buf[base + 2 * S], p3 = buf[base + 3 * S];
;         const float fr = (float)k * i4;
;         const v2f w1 = v2f{cos2pi(fr), sin2pi(fr)};
;         const v2f w2 = vcmul(w1, w1);
;         const v2f b1 = vcmul(p1, w2), b3 = vcmul(p3, w2);
;         const v2f q0 = p0 + b1, q1 = p0 - b1, q2 = p2 + b3, q3 = p2 - b3;
;         const v2f c2 = vcmul(q2, w1);
;         const v2f t3 = vcmul(q3, w1); const v2f c3 = v2f{-t3.y, t3.x};
;         buf[base] = q0 + c2;
;         buf[base + 2 * S] = q0 - c2;
;         buf[base + S] = q1 + c3;
;         buf[base + 3 * S] = q1 - c3;
;       }
	v_mul_f32_e32 v251, v233, v249
	v_mul_f32_e32 v252, v233, v248
	v_fma_f32 v110, v232, v248, -v251
	v_fma_f32 v111, v232, v249, v252
	v_mul_f32_e32 v251, v237, v249
	v_mul_f32_e32 v252, v237, v248
	v_fma_f32 v112, v236, v248, -v251
	v_fma_f32 v113, v236, v249, v252
	v_add_f32_e32 v30, v230, v110
	v_sub_f32_e32 v32, v230, v110
	v_add_f32_e32 v47, v234, v112
	v_sub_f32_e32 v253, v234, v112
	v_add_f32_e32 v31, v231, v111
	v_sub_f32_e32 v33, v231, v111
	v_add_f32_e32 v250, v235, v113
	v_sub_f32_e32 v254, v235, v113
	v_mul_f32_e32 v251, v250, v247
	v_mul_f32_e32 v252, v250, v246
	v_fma_f32 v110, v47, v246, -v251
	v_fma_f32 v111, v47, v247, v252
	v_mul_f32_e32 v251, v254, v247
	v_mul_f32_e32 v252, v254, v246
	v_fma_f32 v112, v253, v246, -v251
	v_fma_f32 v113, v253, v247, v252
	v_add_f32_e32 v230, v30, v110
	v_add_f32_e32 v231, v31, v111
	v_sub_f32_e32 v232, v32, v113
	v_add_f32_e32 v233, v33, v112
	v_sub_f32_e32 v234, v30, v110
	v_sub_f32_e32 v235, v31, v111
	v_add_f32_e32 v236, v32, v113
	v_sub_f32_e32 v237, v33, v112
	ds_write_b64 v242, v[230:231]
	ds_write_b64 v243, v[232:233]
	ds_write_b64 v244, v[234:235]
	ds_write_b64 v245, v[236:237]
	v_mad_u32_u24 v250, s61, 3, v38
	v_and_b32_e32 v251, 15, v250
	v_sub_u32_e32 v252, v250, v251
	v_lshl_or_b32 v252, v252, 2, v251
	v_cvt_f32_u32_e32 v251, v251
	v_mul_f32_e32 v251, 0x3c800000, v251
	v_cos_f32_e32 v246, v251
	v_sin_f32_e32 v247, v251
	v_lshl_add_u32 v242, v252, 3, v40
	v_add_u32_e32 v243, 0x80, v242
	v_add_u32_e32 v244, 0x100, v242
	v_add_u32_e32 v245, 0x180, v242
	v_bfe_u32 v253, v252, 5, 2
	v_bfe_u32 v254, v252, 6, 1
	v_lshl_or_b32 v253, v253, 2, v253
	v_lshl_or_b32 v253, v254, 4, v253
	v_xor_b32_e32 v253, v253, v252
	v_lshlrev_b32_e32 v253, 3, v253
	v_add_u32_e32 v238, v40, v253
	v_xad_u32 v239, v253, s0, v40
	v_xad_u32 v240, v253, s1, v40
	v_xad_u32 v241, v253, s4, v40
	v_mul_f32_e32 v248, v247, v247
	v_mul_f32_e32 v249, v247, v246
	v_fma_f32 v248, v246, v246, -v248
	v_fma_f32 v249, v246, v247, v249
	ds_read_b64 v[230:231], v238
	ds_read_b64 v[232:233], v239
	ds_read_b64 v[234:235], v240
	ds_read_b64 v[236:237], v241
	s_waitcnt lgkmcnt(8)
	v_mul_f32_e32 v251, v67, v109
	v_mul_f32_e32 v252, v67, v108
	v_fma_f32 v110, v66, v108, -v251
	v_fma_f32 v111, v66, v109, v252
	v_mul_f32_e32 v251, v71, v109
	v_mul_f32_e32 v252, v71, v108
	v_fma_f32 v112, v70, v108, -v251
	v_fma_f32 v113, v70, v109, v252
	v_add_f32_e32 v30, v64, v110
	v_sub_f32_e32 v32, v64, v110
	v_add_f32_e32 v47, v68, v112
	v_sub_f32_e32 v253, v68, v112
	v_add_f32_e32 v31, v65, v111
	v_sub_f32_e32 v33, v65, v111
	v_add_f32_e32 v250, v69, v113
	v_sub_f32_e32 v254, v69, v113
	v_mul_f32_e32 v251, v250, v107
	v_mul_f32_e32 v252, v250, v106
	v_fma_f32 v110, v47, v106, -v251
	v_fma_f32 v111, v47, v107, v252
	v_mul_f32_e32 v251, v254, v107
	v_mul_f32_e32 v252, v254, v106
	v_fma_f32 v112, v253, v106, -v251
	v_fma_f32 v113, v253, v107, v252
	v_add_f32_e32 v64, v30, v110
	v_add_f32_e32 v65, v31, v111
	v_sub_f32_e32 v66, v32, v113
	v_add_f32_e32 v67, v33, v112
	v_sub_f32_e32 v68, v30, v110
	v_sub_f32_e32 v69, v31, v111
	v_add_f32_e32 v70, v32, v113
	v_sub_f32_e32 v71, v33, v112
	ds_write_b64 v102, v[64:65]
	ds_write_b64 v103, v[66:67]
	ds_write_b64 v104, v[68:69]
	ds_write_b64 v105, v[70:71]
	v_mad_u32_u24 v250, s61, 4, v38
	v_and_b32_e32 v251, 15, v250
	v_sub_u32_e32 v252, v250, v251
	v_lshl_or_b32 v252, v252, 2, v251
	v_cvt_f32_u32_e32 v251, v251
	v_mul_f32_e32 v251, 0x3c800000, v251
	v_cos_f32_e32 v106, v251
	v_sin_f32_e32 v107, v251
	v_lshl_add_u32 v102, v252, 3, v40
	v_add_u32_e32 v103, 0x80, v102
	v_add_u32_e32 v104, 0x100, v102
	v_add_u32_e32 v105, 0x180, v102
	v_bfe_u32 v253, v252, 5, 2
	v_bfe_u32 v254, v252, 6, 1
	v_lshl_or_b32 v253, v253, 2, v253
	v_lshl_or_b32 v253, v254, 4, v253
	v_xor_b32_e32 v253, v253, v252
	v_lshlrev_b32_e32 v253, 3, v253
	v_add_u32_e32 v72, v40, v253
	v_xad_u32 v73, v253, s0, v40
	v_xad_u32 v74, v253, s1, v40
	v_xad_u32 v75, v253, s4, v40
	v_mul_f32_e32 v108, v107, v107
	v_mul_f32_e32 v109, v107, v106
	v_fma_f32 v108, v106, v106, -v108
	v_fma_f32 v109, v106, v107, v109
	ds_read_b64 v[64:65], v72
	ds_read_b64 v[66:67], v73
	ds_read_b64 v[68:69], v74
	ds_read_b64 v[70:71], v75
	s_waitcnt lgkmcnt(8)
	v_mul_f32_e32 v251, v233, v249
	v_mul_f32_e32 v252, v233, v248
	v_fma_f32 v110, v232, v248, -v251
	v_fma_f32 v111, v232, v249, v252
	v_mul_f32_e32 v251, v237, v249
	v_mul_f32_e32 v252, v237, v248
	v_fma_f32 v112, v236, v248, -v251
	v_fma_f32 v113, v236, v249, v252
	v_add_f32_e32 v30, v230, v110
	v_sub_f32_e32 v32, v230, v110
	v_add_f32_e32 v47, v234, v112
	v_sub_f32_e32 v253, v234, v112
	v_add_f32_e32 v31, v231, v111
	v_sub_f32_e32 v33, v231, v111
	v_add_f32_e32 v250, v235, v113
	v_sub_f32_e32 v254, v235, v113
	v_mul_f32_e32 v251, v250, v247
	v_mul_f32_e32 v252, v250, v246
	v_fma_f32 v110, v47, v246, -v251
	v_fma_f32 v111, v47, v247, v252
	v_mul_f32_e32 v251, v254, v247
	v_mul_f32_e32 v252, v254, v246
	v_fma_f32 v112, v253, v246, -v251
	v_fma_f32 v113, v253, v247, v252
	v_add_f32_e32 v230, v30, v110
	v_add_f32_e32 v231, v31, v111
	v_sub_f32_e32 v232, v32, v113
	v_add_f32_e32 v233, v33, v112
	v_sub_f32_e32 v234, v30, v110
	v_sub_f32_e32 v235, v31, v111
	v_add_f32_e32 v236, v32, v113
	v_sub_f32_e32 v237, v33, v112
	ds_write_b64 v242, v[230:231]
	ds_write_b64 v243, v[232:233]
	ds_write_b64 v244, v[234:235]
	ds_write_b64 v245, v[236:237]
	v_mad_u32_u24 v250, s61, 5, v38
	v_and_b32_e32 v251, 15, v250
	v_sub_u32_e32 v252, v250, v251
	v_lshl_or_b32 v252, v252, 2, v251
	v_cvt_f32_u32_e32 v251, v251
	v_mul_f32_e32 v251, 0x3c800000, v251
	v_cos_f32_e32 v246, v251
	v_sin_f32_e32 v247, v251
	v_lshl_add_u32 v242, v252, 3, v40
	v_add_u32_e32 v243, 0x80, v242
	v_add_u32_e32 v244, 0x100, v242
	v_add_u32_e32 v245, 0x180, v242
	v_bfe_u32 v253, v252, 5, 2
	v_bfe_u32 v254, v252, 6, 1
	v_lshl_or_b32 v253, v253, 2, v253
	v_lshl_or_b32 v253, v254, 4, v253
	v_xor_b32_e32 v253, v253, v252
	v_lshlrev_b32_e32 v253, 3, v253
	v_add_u32_e32 v238, v40, v253
	v_xad_u32 v239, v253, s0, v40
	v_xad_u32 v240, v253, s1, v40
	v_xad_u32 v241, v253, s4, v40
	v_mul_f32_e32 v248, v247, v247
	v_mul_f32_e32 v249, v247, v246
	v_fma_f32 v248, v246, v246, -v248
	v_fma_f32 v249, v246, v247, v249
	ds_read_b64 v[230:231], v238
	ds_read_b64 v[232:233], v239
	ds_read_b64 v[234:235], v240
	ds_read_b64 v[236:237], v241
	s_waitcnt lgkmcnt(8)
; DI float cos2pi(float x) { return __builtin_amdgcn_cosf(x); }
; DI float sin2pi(float x) { return __builtin_amdgcn_sinf(x); }
; template <bool INV>
; DI void fft_lds(float2* buf_, int L, int logL, int gtid, int NTG) {
;     ...
;     for (int f = 0; f < nf; ++f, S <<= 2) {
;       const float i4 = 0.25f / (float)S;
; #pragma unroll 8
;       for (int t = gtid; t < (L >> 2); t += NTG) {
;         const int k = t & (S - 1), base = ((t - k) << 2) | k;
;         const v2f p0 = buf[base], p1 = buf[base + S], p2 = buf[base + 2 * S], p3 = buf[base + 3 * S];
;         const float fr = (float)k * i4;
;         const v2f w1 = v2f{cos2pi(fr), sin2pi(fr)};
;         const v2f w2 = vcmul(w1, w1);
;         const v2f b1 = vcmul(p1, w2), b3 = vcmul(p3, w2);
;         const v2f q0 = p0 + b1, q1 = p0 - b1, q2 = p2 + b3, q3 = p2 - b3;
;         const v2f c2 = vcmul(q2, w1);
;         const v2f t3 = vcmul(q3, w1); const v2f c3 = v2f{-t3.y, t3.x};
;         buf[base] = q0 + c2;
;         buf[base + 2 * S] = q0 - c2;
;         buf[base + S] = q1 + c3;
;         buf[base + 3 * S] = q1 - c3;
;       }
;       __syncthreads();
	v_mul_f32_e32 v251, v67, v109
	v_mul_f32_e32 v252, v67, v108
	v_fma_f32 v110, v66, v108, -v251
	v_fma_f32 v111, v66, v109, v252
	v_mul_f32_e32 v251, v71, v109
	v_mul_f32_e32 v252, v71, v108
	v_fma_f32 v112, v70, v108, -v251
	v_fma_f32 v113, v70, v109, v252
	v_add_f32_e32 v30, v64, v110
	v_sub_f32_e32 v32, v64, v110
	v_add_f32_e32 v47, v68, v112
	v_sub_f32_e32 v253, v68, v112
	v_add_f32_e32 v31, v65, v111
	v_sub_f32_e32 v33, v65, v111
	v_add_f32_e32 v250, v69, v113
	v_sub_f32_e32 v254, v69, v113
	v_mul_f32_e32 v251, v250, v107
	v_mul_f32_e32 v252, v250, v106
	v_fma_f32 v110, v47, v106, -v251
	v_fma_f32 v111, v47, v107, v252
	v_mul_f32_e32 v251, v254, v107
	v_mul_f32_e32 v252, v254, v106
	v_fma_f32 v112, v253, v106, -v251
	v_fma_f32 v113, v253, v107, v252
	v_add_f32_e32 v64, v30, v110
	v_add_f32_e32 v65, v31, v111
	v_sub_f32_e32 v66, v32, v113
	v_add_f32_e32 v67, v33, v112
	v_sub_f32_e32 v68, v30, v110
	v_sub_f32_e32 v69, v31, v111
	v_add_f32_e32 v70, v32, v113
	v_sub_f32_e32 v71, v33, v112
	ds_write_b64 v102, v[64:65]
	ds_write_b64 v103, v[66:67]
	ds_write_b64 v104, v[68:69]
	ds_write_b64 v105, v[70:71]
	v_mad_u32_u24 v250, s61, 6, v38
	v_and_b32_e32 v251, 15, v250
	v_sub_u32_e32 v252, v250, v251
	v_lshl_or_b32 v252, v252, 2, v251
	v_cvt_f32_u32_e32 v251, v251
	v_mul_f32_e32 v251, 0x3c800000, v251
	v_cos_f32_e32 v106, v251
	v_sin_f32_e32 v107, v251
	v_lshl_add_u32 v102, v252, 3, v40
	v_add_u32_e32 v103, 0x80, v102
	v_add_u32_e32 v104, 0x100, v102
	v_add_u32_e32 v105, 0x180, v102
	v_bfe_u32 v253, v252, 5, 2
	v_bfe_u32 v254, v252, 6, 1
	v_lshl_or_b32 v253, v253, 2, v253
	v_lshl_or_b32 v253, v254, 4, v253
	v_xor_b32_e32 v253, v253, v252
	v_lshlrev_b32_e32 v253, 3, v253
	v_add_u32_e32 v72, v40, v253
	v_xad_u32 v73, v253, s0, v40
	v_xad_u32 v74, v253, s1, v40
	v_xad_u32 v75, v253, s4, v40
	v_mul_f32_e32 v108, v107, v107
	v_mul_f32_e32 v109, v107, v106
	v_fma_f32 v108, v106, v106, -v108
	v_fma_f32 v109, v106, v107, v109
	ds_read_b64 v[64:65], v72
	ds_read_b64 v[66:67], v73
	ds_read_b64 v[68:69], v74
	ds_read_b64 v[70:71], v75
	s_waitcnt lgkmcnt(8)
	v_mul_f32_e32 v251, v233, v249
	v_mul_f32_e32 v252, v233, v248
	v_fma_f32 v110, v232, v248, -v251
	v_fma_f32 v111, v232, v249, v252
	v_mul_f32_e32 v251, v237, v249
	v_mul_f32_e32 v252, v237, v248
	v_fma_f32 v112, v236, v248, -v251
	v_fma_f32 v113, v236, v249, v252
	v_add_f32_e32 v30, v230, v110
	v_sub_f32_e32 v32, v230, v110
	v_add_f32_e32 v47, v234, v112
	v_sub_f32_e32 v253, v234, v112
	v_add_f32_e32 v31, v231, v111
	v_sub_f32_e32 v33, v231, v111
	v_add_f32_e32 v250, v235, v113
	v_sub_f32_e32 v254, v235, v113
	v_mul_f32_e32 v251, v250, v247
	v_mul_f32_e32 v252, v250, v246
	v_fma_f32 v110, v47, v246, -v251
	v_fma_f32 v111, v47, v247, v252
	v_mul_f32_e32 v251, v254, v247
	v_mul_f32_e32 v252, v254, v246
	v_fma_f32 v112, v253, v246, -v251
	v_fma_f32 v113, v253, v247, v252
	v_add_f32_e32 v230, v30, v110
	v_add_f32_e32 v231, v31, v111
	v_sub_f32_e32 v232, v32, v113
	v_add_f32_e32 v233, v33, v112
	v_sub_f32_e32 v234, v30, v110
	v_sub_f32_e32 v235, v31, v111
	v_add_f32_e32 v236, v32, v113
	v_sub_f32_e32 v237, v33, v112
	ds_write_b64 v242, v[230:231]
	ds_write_b64 v243, v[232:233]
	ds_write_b64 v244, v[234:235]
	ds_write_b64 v245, v[236:237]
	v_mad_u32_u24 v250, s61, 7, v38
	v_and_b32_e32 v251, 15, v250
	v_sub_u32_e32 v252, v250, v251
	v_lshl_or_b32 v252, v252, 2, v251
	v_cvt_f32_u32_e32 v251, v251
	v_mul_f32_e32 v251, 0x3c800000, v251
	v_cos_f32_e32 v246, v251
	v_sin_f32_e32 v247, v251
	v_lshl_add_u32 v242, v252, 3, v40
	v_add_u32_e32 v243, 0x80, v242
	v_add_u32_e32 v244, 0x100, v242
	v_add_u32_e32 v245, 0x180, v242
	v_bfe_u32 v253, v252, 5, 2
	v_bfe_u32 v254, v252, 6, 1
	v_lshl_or_b32 v253, v253, 2, v253
	v_lshl_or_b32 v253, v254, 4, v253
	v_xor_b32_e32 v253, v253, v252
	v_lshlrev_b32_e32 v253, 3, v253
	v_add_u32_e32 v238, v40, v253
	v_xad_u32 v239, v253, s0, v40
	v_xad_u32 v240, v253, s1, v40
	v_xad_u32 v241, v253, s4, v40
	v_mul_f32_e32 v248, v247, v247
	v_mul_f32_e32 v249, v247, v246
	v_fma_f32 v248, v246, v246, -v248
	v_fma_f32 v249, v246, v247, v249
	ds_read_b64 v[230:231], v238
	ds_read_b64 v[232:233], v239
	ds_read_b64 v[234:235], v240
	ds_read_b64 v[236:237], v241
	s_waitcnt lgkmcnt(8)
	v_mul_f32_e32 v251, v67, v109
	v_mul_f32_e32 v252, v67, v108
	v_fma_f32 v110, v66, v108, -v251
	v_fma_f32 v111, v66, v109, v252
	v_mul_f32_e32 v251, v71, v109
	v_mul_f32_e32 v252, v71, v108
	v_fma_f32 v112, v70, v108, -v251
	v_fma_f32 v113, v70, v109, v252
	v_add_f32_e32 v30, v64, v110
	v_sub_f32_e32 v32, v64, v110
	v_add_f32_e32 v47, v68, v112
	v_sub_f32_e32 v253, v68, v112
	v_add_f32_e32 v31, v65, v111
	v_sub_f32_e32 v33, v65, v111
	v_add_f32_e32 v250, v69, v113
	v_sub_f32_e32 v254, v69, v113
	v_mul_f32_e32 v251, v250, v107
	v_mul_f32_e32 v252, v250, v106
	v_fma_f32 v110, v47, v106, -v251
	v_fma_f32 v111, v47, v107, v252
	v_mul_f32_e32 v251, v254, v107
	v_mul_f32_e32 v252, v254, v106
	v_fma_f32 v112, v253, v106, -v251
	v_fma_f32 v113, v253, v107, v252
	v_add_f32_e32 v64, v30, v110
	v_add_f32_e32 v65, v31, v111
	v_sub_f32_e32 v66, v32, v113
	v_add_f32_e32 v67, v33, v112
	v_sub_f32_e32 v68, v30, v110
	v_sub_f32_e32 v69, v31, v111
	v_add_f32_e32 v70, v32, v113
	v_sub_f32_e32 v71, v33, v112
	ds_write_b64 v102, v[64:65]
	ds_write_b64 v103, v[66:67]
	ds_write_b64 v104, v[68:69]
	ds_write_b64 v105, v[70:71]
	s_waitcnt lgkmcnt(4)
	v_mul_f32_e32 v251, v233, v249
	v_mul_f32_e32 v252, v233, v248
	v_fma_f32 v110, v232, v248, -v251
	v_fma_f32 v111, v232, v249, v252
	v_mul_f32_e32 v251, v237, v249
	v_mul_f32_e32 v252, v237, v248
	v_fma_f32 v112, v236, v248, -v251
	v_fma_f32 v113, v236, v249, v252
	v_add_f32_e32 v30, v230, v110
	v_sub_f32_e32 v32, v230, v110
	v_add_f32_e32 v47, v234, v112
	v_sub_f32_e32 v253, v234, v112
	v_add_f32_e32 v31, v231, v111
	v_sub_f32_e32 v33, v231, v111
	v_add_f32_e32 v250, v235, v113
	v_sub_f32_e32 v254, v235, v113
	v_mul_f32_e32 v251, v250, v247
	v_mul_f32_e32 v252, v250, v246
	v_fma_f32 v110, v47, v246, -v251
	v_fma_f32 v111, v47, v247, v252
	v_mul_f32_e32 v251, v254, v247
	v_mul_f32_e32 v252, v254, v246
	v_fma_f32 v112, v253, v246, -v251
	v_fma_f32 v113, v253, v247, v252
	v_add_f32_e32 v230, v30, v110
	v_add_f32_e32 v231, v31, v111
	v_sub_f32_e32 v232, v32, v113
	v_add_f32_e32 v233, v33, v112
	v_sub_f32_e32 v234, v30, v110
	v_sub_f32_e32 v235, v31, v111
	v_add_f32_e32 v236, v32, v113
	v_sub_f32_e32 v237, v33, v112
	ds_write_b64 v242, v[230:231]
	ds_write_b64 v243, v[232:233]
	ds_write_b64 v244, v[234:235]
	ds_write_b64 v245, v[236:237]
	s_branch .LBB0_722
; template <bool INV>
; DI void fft_lds(float2* buf_, int L, int logL, int gtid, int NTG) {
;     ...
;     for (int f = 0; f < nf; ++f, S <<= 2) {
;       const float i4 = 0.25f / (float)S;
; #pragma unroll 8
;       for (int t = gtid; t < (L >> 2); t += NTG) {
;         const int k = t & (S - 1), base = ((t - k) << 2) | k;
;         const v2f p0 = buf[base], p1 = buf[base + S], p2 = buf[base + 2 * S], p3 = buf[base + 3 * S];
.Lffs_i_skip:
	v_cvt_f32_i32_e32 v30, s7
	s_add_i32 s24, s7, -1
	v_lshl_add_u32 v32, s7, 3, v40
	v_div_scale_f32 v31, s[0:1], v30, v30, s60
	v_rcp_f32_e32 v33, v31
	v_div_scale_f32 v47, vcc, s60, v30, s60
	v_fma_f32 v64, -v31, v33, 1.0
	v_fmac_f32_e32 v33, v64, v33
	v_mul_f32_e32 v64, v47, v33
	v_fma_f32 v65, -v31, v64, v47
	v_fmac_f32_e32 v64, v65, v33
	v_fma_f32 v31, -v31, v64, v47
	v_div_fmas_f32 v31, v31, v33, v64
	v_div_fixup_f32 v33, v31, v30, s60
	v_lshl_add_u32 v47, s7, 4, v40
	v_mov_b32_e32 v64, v38
	s_and_saveexec_b64 s[0:1], s[48:49]
	s_cbranch_execz .LBB0_728
	v_mad_u64_u32 v[30:31], s[4:5], s7, 24, v[40:41]
	s_mov_b64 s[4:5], 0
	v_mov_b32_e32 v31, v90
	v_mov_b32_e32 v65, v101
	v_mov_b32_e32 v64, v38
